# per-row-block dependency counters (8-workgroup group sync) replace the grid barrier at 5 of 9 seams per layer; norm rows remapped so each 256-row block is normalised by the workgroups that consume it
# speedup vs baseline: 1.0495x; 1.0483x over previous
.LBB0_263:
	s_mul_i32 s3, s29, s28
	s_ashr_i32 s29, s28, 31
	s_mov_b64 s[4:5], 0xe900100
	s_cmpk_eq_i32 s28, 0x100
	v_writelane_b32 v255, s4, 1
	s_mul_i32 s3, s3, s2
	s_cselect_b64 s[92:93], -1, 0
	v_writelane_b32 v255, s5, 2
	s_add_i32 s2, 0, 0x23f00
	v_writelane_b32 v255, s2, 3
	s_add_i32 s2, 0, 0x23f04
	v_writelane_b32 v255, s2, 4
	s_add_i32 s2, 0, 0x23f10
	s_ashr_i32 s83, s82, 31
	v_writelane_b32 v255, s2, 5
	s_lshl_b64 s[84:85], s[82:83], 11
	s_lshl_b64 s[34:35], s[82:83], 12
	v_writelane_b32 v255, s82, 6
	v_mbcnt_lo_u32_b32 v0, -1, 0
	v_mbcnt_hi_u32_b32 v182, -1, v0
	v_writelane_b32 v255, s83, 7
	v_writelane_b32 v255, s84, 8
	s_mov_b32 s39, 0
	v_and_b32_e32 v0, 64, v182
	v_writelane_b32 v255, s85, 9
	v_writelane_b32 v255, s92, 10
	v_writelane_b32 v255, s39, 45
	v_writelane_b32 v255, s39, 46
	v_writelane_b32 v255, s39, 47
	v_mov_b32_e32 v145, 0
	s_movk_i32 s67, 0x1000
	s_movk_i32 s69, 0xfff
	s_mov_b32 s73, 0xff000000
	s_mov_b64 s[94:95], 0x1000
	v_mov_b32_e32 v146, 0x358637bd
	s_mov_b32 s72, 0x800000
	s_mov_b32 s74, 0xf7800000
	s_movk_i32 s75, 0x1fff
	v_mov_b32_e32 v185, 0x1000
	v_mov_b32_e32 v186, 0x2000
	v_mov_b32_e32 v189, 1
	s_mov_b32 s76, 0x10000
	s_mov_b32 s77, 0x18000
	s_mov_b64 s[48:49], 0x80
	s_mov_b32 s86, 0x8000
	s_movk_i32 s68, 0x1600
	s_mov_b32 s87, 0x40000
	s_mov_b32 s90, 0x48000
	s_mov_b32 s78, 0x50000
	s_mov_b32 s79, 0x58000
	s_mov_b32 s52, 0x3e000000
	s_mov_b32 s66, 0x3c800000
	s_add_i32 s80, 0, 0x43c
	s_add_i32 s81, 0, 60
	v_add_u32_e32 v183, 64, v0
	v_xor_b32_e32 v188, 1, v182
	v_xor_b32_e32 v254, 2, v182
	v_xor_b32_e32 v187, 16, v182
	v_xor_b32_e32 v184, 32, v182
	v_mov_b64_e32 v[148:149], 0x2bf
	v_mov_b64_e32 v[150:151], 0x100
	v_mov_b64_e32 v[152:153], 0xff
	v_mov_b32_e32 v194, 0xcf
	v_mov_b32_e32 v195, 0x3cf
	v_mov_b32_e32 v196, 0xdf
	v_mov_b32_e32 v197, 0x3df
	v_mov_b32_e32 v198, 0xef
	v_mov_b32_e32 v199, 0x3ef
	v_mov_b32_e32 v200, 0xff
	v_mov_b32_e32 v201, 0x3ff
	v_mov_b32_e32 v202, 0xf149f2ca
	s_mov_b32 s70, s39
	v_writelane_b32 v255, s93, 11
	s_branch .LBB0_265

.LBB0_265:
	v_mov_b32_e32 v0, v147
	v_readlane_b32 s2, v255, 0
	s_mov_b32 s71, s39
	v_ashrrev_i32_e32 v1, 6, v0
	v_lshl_add_u32 v96, s2, 3, v1
	s_movk_i32 s2, 0x2000
	v_cmp_gt_i32_e32 vcc, s2, v96
	s_mul_i32 s2, s70, 0xc00
	v_writelane_b32 v255, s2, 12
	s_nop 1
	v_writelane_b32 v255, s3, 13
	s_and_saveexec_b64 s[16:17], vcc
	s_cbranch_execz .LBB0_280
	s_load_dwordx4 s[8:11], s[0:1], 0x90
	s_load_dwordx4 s[12:15], s[0:1], 0x0
	s_load_dwordx4 s[4:7], s[0:1], 0x40
	s_mul_i32 s2, s70, 0x2d000
	s_mul_i32 s24, s70, 0xc00
	s_waitcnt lgkmcnt(0)
	s_add_u32 s22, s10, 0x100000
	s_addc_u32 s23, s11, 0
	s_cmp_lg_u32 s70, 0
	s_cselect_b64 s[18:19], -1, 0
	s_add_u32 s20, s22, s2
	s_mul_hi_u32 s2, s70, 0x2d000
	s_addc_u32 s21, s23, s2
	s_mov_b32 s2, s24
	v_writelane_b32 v255, s2, 12
	v_sub_u32_e64 v1, s70, 1 clamp
	v_cmp_lt_i32_e32 vcc, v188, v183
	v_writelane_b32 v255, s3, 13
	s_movk_i32 s2, 0xc00
	v_mul_lo_u32 v144, v1, s2
	s_mov_b32 s2, 0x2d000
	v_lshlrev_b64 v[2:3], 2, v[144:145]
	v_mul_lo_u32 v144, v1, s2
	v_lshlrev_b32_e32 v1, 2, v0
	v_and_b32_e32 v98, 0xfc, v1
	v_cndmask_b32_e32 v1, v182, v188, vcc
	v_cmp_lt_i32_e32 vcc, v254, v183
	v_lshlrev_b32_e32 v99, 2, v1
	v_lshl_add_u64 v[4:5], s[22:23], 0, v[144:145]
	v_cndmask_b32_e32 v1, v182, v254, vcc
	v_lshlrev_b32_e32 v128, 2, v1
	v_xor_b32_e32 v1, 4, v182
	v_cmp_lt_i32_e32 vcc, v1, v183
	v_lshlrev_b32_e32 v144, 2, v98
	s_mov_b32 s25, s39
	v_cndmask_b32_e32 v1, v182, v1, vcc
	v_lshlrev_b32_e32 v129, 2, v1
	v_xor_b32_e32 v1, 8, v182
	v_lshl_add_u64 v[2:3], s[6:7], 0, v[2:3]
	v_lshl_add_u64 v[4:5], v[4:5], 0, v[144:145]
	s_mov_b64 s[6:7], 0x8000
	v_cmp_lt_i32_e32 vcc, v1, v183
	s_lshl_b64 s[24:25], s[24:25], 2
	v_lshl_add_u64 v[100:101], v[4:5], 0, s[6:7]
	v_lshl_add_u64 v[2:3], v[2:3], 0, v[144:145]
	s_mov_b64 s[6:7], 0x2000
	v_cndmask_b32_e32 v1, v182, v1, vcc
	v_cmp_lt_i32_e32 vcc, v187, v183
	v_ashrrev_i32_e32 v97, 31, v96
	s_add_u32 s4, s4, s24
	v_lshl_add_u64 v[102:103], v[2:3], 0, s[6:7]
	v_lshlrev_b32_e32 v130, 2, v1
	v_cndmask_b32_e32 v1, v182, v187, vcc
	v_cmp_lt_i32_e32 vcc, v184, v183
	v_lshlrev_b64 v[2:3], 11, v[96:97]
	v_and_b32_e32 v4, 63, v0
	s_addc_u32 s5, s5, s25
	v_lshlrev_b32_e32 v131, 2, v1
	v_cndmask_b32_e32 v1, v182, v184, vcc
	v_lshl_or_b32 v2, v4, 3, v2
	v_lshl_add_u64 v[104:105], s[4:5], 0, v[144:145]
	v_lshlrev_b32_e32 v132, 2, v1
	v_lshl_add_u64 v[0:1], s[10:11], 0, v[2:3]
	s_mov_b64 s[4:5], 0x9800600
	v_lshlrev_b64 v[108:109], 12, v[96:97]
	v_lshl_add_u64 v[106:107], v[0:1], 0, s[4:5]
	v_lshl_or_b32 v108, v4, 4, v108
	s_mov_b64 s[10:11], 0
	s_cmp_eq_u32 s70, 0
	s_cbranch_scc1 .Lnorm0_first
	v_readlane_b32 s2, v255, 0
	v_readfirstlane_b32 s7, v147
	s_load_dwordx2 s[4:5], s[0:1], 0x90
	s_load_dwordx2 s[12:13], s[0:1], 0x98
	s_load_dwordx2 s[14:15], s[0:1], 0x40
	s_load_dwordx2 s[40:41], s[0:1], 0x48
	v_and_b32_e32 v0, 63, v147
	v_lshlrev_b32_e32 v1, 3, v0
	v_lshlrev_b32_e32 v0, 4, v0
	s_lshr_b32 s7, s7, 6
	s_and_b32 s27, s2, 6
	s_lshl_b32 s27, s27, 5
	s_and_b32 s37, s2, 0x39
	s_or_b32 s27, s27, s37
	s_lshr_b32 s37, s2, 6
	s_lshl_b32 s37, s37, 1
	s_or_b32 s2, s27, s37
	s_lshl_b32 s2, s2, 3
	s_add_u32 s2, s2, s7
	s_lshl_b32 s24, s2, 2
	s_sub_u32 s27, s24, 0x1000
	s_lshr_b32 s27, s27, 10
	s_add_u32 s27, s27, 1
	s_cmp_lt_u32 s24, 0x1000
	s_cselect_b32 s30, 0, s27
	v_add_u32_e32 v2, 0x8000, v0
	v_mov_b32_e32 v3, v0
	v_add_u32_e32 v4, 0x1000, v0
	s_waitcnt lgkmcnt(0)
	s_lshl_b32 s27, s24, 11
	s_add_u32 s62, s12, s27
	s_addc_u32 s63, s13, 0
	s_add_u32 s58, s62, 0x8800000
	s_addc_u32 s59, s63, 0
	s_add_u32 s60, s58, 0x1000000
	s_addc_u32 s61, s59, 0
	s_add_u32 s62, s62, 0x1000000
	s_addc_u32 s63, s63, 0
	s_lshl_b32 s27, s24, 12
	s_add_u32 s46, s4, s27
	s_addc_u32 s47, s5, 0
	s_mov_b64 s[4:5], s[46:47]
	s_mul_i32 s27, s70, 5
	s_add_u32 s27, s27, s30
	s_mul_i32 s27, s27, 0x9000
	s_add_u32 s27, s27, 0x100000
	s_add_u32 s88, s12, s27
	s_addc_u32 s89, s13, 0
	s_sub_u32 s100, s88, 0x2d000
	s_subb_u32 s101, s89, 0
	s_mul_i32 s27, s70, 0x3000
	s_add_u32 s27, s27, 0xfffff000
	s_add_u32 s40, s40, s27
	s_addc_u32 s41, s41, 0
	s_mul_i32 s27, s70, 0x3000
	s_add_u32 s14, s14, s27
	s_addc_u32 s15, s15, 0
	global_load_dwordx4 v[22:25], v2, s[100:101] offset:0
	global_load_dwordx4 v[38:41], v0, s[40:41] offset:0
	global_load_dwordx4 v[54:57], v3, s[88:89] offset:0
	global_load_dwordx4 v[70:73], v4, s[88:89] offset:0
	global_load_dwordx4 v[86:89], v0, s[14:15] offset:0
	global_load_dwordx4 v[26:29], v2, s[100:101] offset:1024
	global_load_dwordx4 v[42:45], v0, s[40:41] offset:1024
	global_load_dwordx4 v[58:61], v3, s[88:89] offset:1024
	global_load_dwordx4 v[74:77], v4, s[88:89] offset:1024
	global_load_dwordx4 v[90:93], v0, s[14:15] offset:1024
	global_load_dwordx4 v[30:33], v2, s[100:101] offset:2048
	global_load_dwordx4 v[46:49], v0, s[40:41] offset:2048
	global_load_dwordx4 v[62:65], v3, s[88:89] offset:2048
	global_load_dwordx4 v[78:81], v4, s[88:89] offset:2048
	global_load_dwordx4 v[94:97], v0, s[14:15] offset:2048
	global_load_dwordx4 v[34:37], v2, s[100:101] offset:3072
	global_load_dwordx4 v[50:53], v0, s[40:41] offset:3072
	global_load_dwordx4 v[66:69], v3, s[88:89] offset:3072
	global_load_dwordx4 v[82:85], v4, s[88:89] offset:3072
	global_load_dwordx4 v[98:101], v0, s[14:15] offset:3072
	global_load_dwordx4 v[102:105], v0, s[4:5] offset:0
	global_load_dwordx4 v[106:109], v0, s[4:5] offset:1024
	global_load_dwordx4 v[110:113], v0, s[4:5] offset:2048
	global_load_dwordx4 v[114:117], v0, s[4:5] offset:3072
	global_load_dwordx2 v[118:119], v1, s[58:59] offset:0
	global_load_dwordx2 v[122:123], v1, s[58:59] offset:512
	global_load_dwordx2 v[134:135], v1, s[58:59] offset:1024
	global_load_dwordx2 v[138:139], v1, s[58:59] offset:1536
	global_load_dwordx2 v[120:121], v1, s[60:61] offset:0
	global_load_dwordx2 v[124:125], v1, s[60:61] offset:512
	global_load_dwordx2 v[136:137], v1, s[60:61] offset:1024
	global_load_dwordx2 v[140:141], v1, s[60:61] offset:1536
	s_add_u32 s4, s4, 0x1000
	s_addc_u32 s5, s5, 0
	s_add_u32 s58, s58, 0x800
	s_addc_u32 s59, s59, 0
	s_add_u32 s60, s60, 0x800
	s_addc_u32 s61, s61, 0
	global_load_dwordx4 v[154:157], v0, s[4:5] offset:0
	global_load_dwordx4 v[158:161], v0, s[4:5] offset:1024
	global_load_dwordx4 v[162:165], v0, s[4:5] offset:2048
	global_load_dwordx4 v[168:171], v0, s[4:5] offset:3072
	global_load_dwordx2 v[172:173], v1, s[58:59] offset:0
	global_load_dwordx2 v[176:177], v1, s[58:59] offset:512
	global_load_dwordx2 v[204:205], v1, s[58:59] offset:1024
	global_load_dwordx2 v[214:215], v1, s[58:59] offset:1536
	global_load_dwordx2 v[174:175], v1, s[60:61] offset:0
	global_load_dwordx2 v[178:179], v1, s[60:61] offset:512
	global_load_dwordx2 v[206:207], v1, s[60:61] offset:1024
	global_load_dwordx2 v[216:217], v1, s[60:61] offset:1536
	s_add_u32 s4, s4, 0x1000
	s_addc_u32 s5, s5, 0
	s_add_u32 s58, s58, 0x800
	s_addc_u32 s59, s59, 0
	s_add_u32 s60, s60, 0x800
	s_addc_u32 s61, s61, 0
	global_load_dwordx4 v[218:221], v0, s[4:5] offset:0
	global_load_dwordx4 v[222:225], v0, s[4:5] offset:1024
	global_load_dwordx4 v[226:229], v0, s[4:5] offset:2048
	global_load_dwordx4 v[230:233], v0, s[4:5] offset:3072
	global_load_dwordx2 v[234:235], v1, s[58:59] offset:0
	global_load_dwordx2 v[238:239], v1, s[58:59] offset:512
	global_load_dwordx2 v[242:243], v1, s[58:59] offset:1024
	global_load_dwordx2 v[246:247], v1, s[58:59] offset:1536
	global_load_dwordx2 v[236:237], v1, s[60:61] offset:0
	global_load_dwordx2 v[240:241], v1, s[60:61] offset:512
	global_load_dwordx2 v[244:245], v1, s[60:61] offset:1024
	global_load_dwordx2 v[248:249], v1, s[60:61] offset:1536
	s_add_u32 s4, s4, 0x1000
	s_addc_u32 s5, s5, 0
	s_add_u32 s58, s58, 0x800
	s_addc_u32 s59, s59, 0
	s_add_u32 s60, s60, 0x800
	s_addc_u32 s61, s61, 0
	s_waitcnt vmcnt(24)
	v_pk_add_f32 v[70:71], v[70:71], 1.0 op_sel_hi:[1,0]
	v_pk_add_f32 v[72:73], v[72:73], 1.0 op_sel_hi:[1,0]
	v_pk_add_f32 v[74:75], v[74:75], 1.0 op_sel_hi:[1,0]
	v_pk_add_f32 v[76:77], v[76:77], 1.0 op_sel_hi:[1,0]
	v_pk_add_f32 v[78:79], v[78:79], 1.0 op_sel_hi:[1,0]
	v_pk_add_f32 v[80:81], v[80:81], 1.0 op_sel_hi:[1,0]
	v_pk_add_f32 v[82:83], v[82:83], 1.0 op_sel_hi:[1,0]
	v_pk_add_f32 v[84:85], v[84:85], 1.0 op_sel_hi:[1,0]
	v_lshlrev_b32_e32 v14, 16, v118
	v_and_b32_e32 v15, 0xffff0000, v118
	v_lshlrev_b32_e32 v16, 16, v120
	v_and_b32_e32 v17, 0xffff0000, v120
	v_lshlrev_b32_e32 v18, 16, v119
	v_and_b32_e32 v19, 0xffff0000, v119
	v_lshlrev_b32_e32 v20, 16, v121
	v_and_b32_e32 v21, 0xffff0000, v121
	v_pk_add_f32 v[118:119], v[14:15], v[16:17]
	v_pk_add_f32 v[120:121], v[18:19], v[20:21]
	v_lshlrev_b32_e32 v14, 16, v122
	v_and_b32_e32 v15, 0xffff0000, v122
	v_lshlrev_b32_e32 v16, 16, v124
	v_and_b32_e32 v17, 0xffff0000, v124
	v_lshlrev_b32_e32 v18, 16, v123
	v_and_b32_e32 v19, 0xffff0000, v123
	v_lshlrev_b32_e32 v20, 16, v125
	v_and_b32_e32 v21, 0xffff0000, v125
	v_pk_add_f32 v[122:123], v[14:15], v[16:17]
	v_pk_add_f32 v[124:125], v[18:19], v[20:21]
	v_lshlrev_b32_e32 v14, 16, v134
	v_and_b32_e32 v15, 0xffff0000, v134
	v_lshlrev_b32_e32 v16, 16, v136
	v_and_b32_e32 v17, 0xffff0000, v136
	v_lshlrev_b32_e32 v18, 16, v135
	v_and_b32_e32 v19, 0xffff0000, v135
	v_lshlrev_b32_e32 v20, 16, v137
	v_and_b32_e32 v21, 0xffff0000, v137
	v_pk_add_f32 v[134:135], v[14:15], v[16:17]
	v_pk_add_f32 v[136:137], v[18:19], v[20:21]
	v_lshlrev_b32_e32 v14, 16, v138
	v_and_b32_e32 v15, 0xffff0000, v138
	v_lshlrev_b32_e32 v16, 16, v140
	v_and_b32_e32 v17, 0xffff0000, v140
	v_lshlrev_b32_e32 v18, 16, v139
	v_and_b32_e32 v19, 0xffff0000, v139
	v_lshlrev_b32_e32 v20, 16, v141
	v_and_b32_e32 v21, 0xffff0000, v141
	v_pk_add_f32 v[138:139], v[14:15], v[16:17]
	v_pk_add_f32 v[140:141], v[18:19], v[20:21]
	v_pk_mul_f32 v[12:13], v[118:119], v[118:119]
	v_pk_fma_f32 v[12:13], v[120:121], v[120:121], v[12:13]
	v_pk_fma_f32 v[12:13], v[122:123], v[122:123], v[12:13]
	v_pk_fma_f32 v[12:13], v[124:125], v[124:125], v[12:13]
	v_pk_fma_f32 v[12:13], v[134:135], v[134:135], v[12:13]
	v_pk_fma_f32 v[12:13], v[136:137], v[136:137], v[12:13]
	v_pk_fma_f32 v[12:13], v[138:139], v[138:139], v[12:13]
	v_pk_fma_f32 v[12:13], v[140:141], v[140:141], v[12:13]
	v_add_f32_e32 v5, v12, v13
	s_nop 1
	v_add_f32_dpp v5, v5, v5 quad_perm:[1,0,3,2] row_mask:0xf bank_mask:0xf
	s_nop 1
	v_add_f32_dpp v5, v5, v5 quad_perm:[2,3,0,1] row_mask:0xf bank_mask:0xf
	s_nop 1
	v_add_f32_dpp v5, v5, v5 row_half_mirror row_mask:0xf bank_mask:0xf
	s_nop 1
	v_add_f32_dpp v5, v5, v5 row_mirror row_mask:0xf bank_mask:0xf
	s_nop 1
	v_add_f32_dpp v5, v5, v5 row_bcast:15 row_mask:0xa bank_mask:0xf
	s_nop 1
	v_add_f32_dpp v5, v5, v5 row_bcast:31 row_mask:0xc bank_mask:0xf
	s_nop 1
	v_readlane_b32 s32, v5, 63
	s_nop 1
	v_mov_b32_e32 v6, s32
	v_fmamk_f32 v6, v6, 0x3a800000, v146
	v_rsq_f32_e32 v6, v6
	s_nop 0
	v_mul_f32_e32 v8, 0.5, v6
	v_pk_mul_f32 v[14:15], v[118:119], v[8:9] op_sel_hi:[1,0]
	v_pk_mul_f32 v[14:15], v[38:39], v[14:15]
	v_pk_fma_f32 v[102:103], v[22:23], v[14:15], v[102:103]
	v_pk_mul_f32 v[14:15], v[120:121], v[8:9] op_sel_hi:[1,0]
	v_pk_mul_f32 v[14:15], v[40:41], v[14:15]
	v_pk_fma_f32 v[104:105], v[24:25], v[14:15], v[104:105]
	v_pk_mul_f32 v[14:15], v[122:123], v[8:9] op_sel_hi:[1,0]
	v_pk_mul_f32 v[14:15], v[42:43], v[14:15]
	v_pk_fma_f32 v[106:107], v[26:27], v[14:15], v[106:107]
	v_pk_mul_f32 v[14:15], v[124:125], v[8:9] op_sel_hi:[1,0]
	v_pk_mul_f32 v[14:15], v[44:45], v[14:15]
	v_pk_fma_f32 v[108:109], v[28:29], v[14:15], v[108:109]
	v_pk_mul_f32 v[14:15], v[134:135], v[8:9] op_sel_hi:[1,0]
	v_pk_mul_f32 v[14:15], v[46:47], v[14:15]
	v_pk_fma_f32 v[110:111], v[30:31], v[14:15], v[110:111]
	v_pk_mul_f32 v[14:15], v[136:137], v[8:9] op_sel_hi:[1,0]
	v_pk_mul_f32 v[14:15], v[48:49], v[14:15]
	v_pk_fma_f32 v[112:113], v[32:33], v[14:15], v[112:113]
	v_pk_mul_f32 v[14:15], v[138:139], v[8:9] op_sel_hi:[1,0]
	v_pk_mul_f32 v[14:15], v[50:51], v[14:15]
	v_pk_fma_f32 v[114:115], v[34:35], v[14:15], v[114:115]
	v_pk_mul_f32 v[14:15], v[140:141], v[8:9] op_sel_hi:[1,0]
	v_pk_mul_f32 v[14:15], v[52:53], v[14:15]
	v_pk_fma_f32 v[116:117], v[36:37], v[14:15], v[116:117]
	v_pk_mul_f32 v[12:13], v[102:103], v[102:103]
	v_pk_fma_f32 v[12:13], v[104:105], v[104:105], v[12:13]
	v_pk_fma_f32 v[12:13], v[106:107], v[106:107], v[12:13]
	v_pk_fma_f32 v[12:13], v[108:109], v[108:109], v[12:13]
	v_pk_fma_f32 v[12:13], v[110:111], v[110:111], v[12:13]
	v_pk_fma_f32 v[12:13], v[112:113], v[112:113], v[12:13]
	v_pk_fma_f32 v[12:13], v[114:115], v[114:115], v[12:13]
	v_pk_fma_f32 v[12:13], v[116:117], v[116:117], v[12:13]
	v_add_f32_e32 v5, v12, v13
	s_nop 1
	v_add_f32_dpp v5, v5, v5 quad_perm:[1,0,3,2] row_mask:0xf bank_mask:0xf
	s_nop 1
	v_add_f32_dpp v5, v5, v5 quad_perm:[2,3,0,1] row_mask:0xf bank_mask:0xf
	s_nop 1
	v_add_f32_dpp v5, v5, v5 row_half_mirror row_mask:0xf bank_mask:0xf
	s_nop 1
	v_add_f32_dpp v5, v5, v5 row_mirror row_mask:0xf bank_mask:0xf
	s_nop 1
	v_add_f32_dpp v5, v5, v5 row_bcast:15 row_mask:0xa bank_mask:0xf
	s_nop 1
	v_add_f32_dpp v5, v5, v5 row_bcast:31 row_mask:0xc bank_mask:0xf
	s_nop 1
	v_readlane_b32 s32, v5, 63
	s_nop 1
	v_mov_b32_e32 v6, s32
	v_fmamk_f32 v6, v6, 0x3a800000, v146
	v_rsq_f32_e32 v6, v6
	s_nop 0
	v_mov_b32_e32 v10, v6
	v_pk_mul_f32 v[14:15], v[102:103], v[10:11] op_sel_hi:[1,0]
	v_pk_mul_f32 v[14:15], v[86:87], v[14:15]
	v_pk_fma_f32 v[16:17], v[70:71], v[14:15], v[54:55]
	v_pk_mul_f32 v[14:15], v[104:105], v[10:11] op_sel_hi:[1,0]
	v_pk_mul_f32 v[14:15], v[88:89], v[14:15]
	v_pk_fma_f32 v[18:19], v[72:73], v[14:15], v[56:57]
	v_cvt_pk_bf16_f32 v118, v16, v17
	v_cvt_pk_bf16_f32 v119, v18, v19
	v_pk_mul_f32 v[14:15], v[106:107], v[10:11] op_sel_hi:[1,0]
	v_pk_mul_f32 v[14:15], v[90:91], v[14:15]
	v_pk_fma_f32 v[16:17], v[74:75], v[14:15], v[58:59]
	v_pk_mul_f32 v[14:15], v[108:109], v[10:11] op_sel_hi:[1,0]
	v_pk_mul_f32 v[14:15], v[92:93], v[14:15]
	v_pk_fma_f32 v[18:19], v[76:77], v[14:15], v[60:61]
	v_cvt_pk_bf16_f32 v122, v16, v17
	v_cvt_pk_bf16_f32 v123, v18, v19
	v_pk_mul_f32 v[14:15], v[110:111], v[10:11] op_sel_hi:[1,0]
	v_pk_mul_f32 v[14:15], v[94:95], v[14:15]
	v_pk_fma_f32 v[16:17], v[78:79], v[14:15], v[62:63]
	v_pk_mul_f32 v[14:15], v[112:113], v[10:11] op_sel_hi:[1,0]
	v_pk_mul_f32 v[14:15], v[96:97], v[14:15]
	v_pk_fma_f32 v[18:19], v[80:81], v[14:15], v[64:65]
	v_cvt_pk_bf16_f32 v134, v16, v17
	v_cvt_pk_bf16_f32 v135, v18, v19
	v_pk_mul_f32 v[14:15], v[114:115], v[10:11] op_sel_hi:[1,0]
	v_pk_mul_f32 v[14:15], v[98:99], v[14:15]
	v_pk_fma_f32 v[16:17], v[82:83], v[14:15], v[66:67]
	v_pk_mul_f32 v[14:15], v[116:117], v[10:11] op_sel_hi:[1,0]
	v_pk_mul_f32 v[14:15], v[100:101], v[14:15]
	v_pk_fma_f32 v[18:19], v[84:85], v[14:15], v[68:69]
	v_cvt_pk_bf16_f32 v138, v16, v17
	v_cvt_pk_bf16_f32 v139, v18, v19
	global_store_dwordx4 v0, v[102:105], s[46:47] offset:0 sc1
	global_store_dwordx4 v0, v[106:109], s[46:47] offset:1024 sc1
	global_store_dwordx4 v0, v[110:113], s[46:47] offset:2048 sc1
	global_store_dwordx4 v0, v[114:117], s[46:47] offset:3072 sc1
	global_store_dwordx2 v1, v[118:119], s[62:63] offset:0 sc1
	global_store_dwordx2 v1, v[122:123], s[62:63] offset:512 sc1
	global_store_dwordx2 v1, v[134:135], s[62:63] offset:1024 sc1
	global_store_dwordx2 v1, v[138:139], s[62:63] offset:1536 sc1
	s_add_u32 s46, s46, 0x1000
	s_addc_u32 s47, s47, 0
	s_add_u32 s62, s62, 0x800
	s_addc_u32 s63, s63, 0
	s_nop 1
	global_load_dwordx4 v[102:105], v0, s[4:5] offset:0
	global_load_dwordx4 v[106:109], v0, s[4:5] offset:1024
	global_load_dwordx4 v[110:113], v0, s[4:5] offset:2048
	global_load_dwordx4 v[114:117], v0, s[4:5] offset:3072
	global_load_dwordx2 v[118:119], v1, s[58:59] offset:0
	global_load_dwordx2 v[122:123], v1, s[58:59] offset:512
	global_load_dwordx2 v[134:135], v1, s[58:59] offset:1024
	global_load_dwordx2 v[138:139], v1, s[58:59] offset:1536
	global_load_dwordx2 v[120:121], v1, s[60:61] offset:0
	global_load_dwordx2 v[124:125], v1, s[60:61] offset:512
	global_load_dwordx2 v[136:137], v1, s[60:61] offset:1024
	global_load_dwordx2 v[140:141], v1, s[60:61] offset:1536
	s_add_u32 s4, s4, 0x1000
	s_addc_u32 s5, s5, 0
	s_add_u32 s58, s58, 0x800
	s_addc_u32 s59, s59, 0
	s_add_u32 s60, s60, 0x800
	s_addc_u32 s61, s61, 0
	s_waitcnt vmcnt(32)
	v_lshlrev_b32_e32 v14, 16, v172
	v_and_b32_e32 v15, 0xffff0000, v172
	v_lshlrev_b32_e32 v16, 16, v174
	v_and_b32_e32 v17, 0xffff0000, v174
	v_lshlrev_b32_e32 v18, 16, v173
	v_and_b32_e32 v19, 0xffff0000, v173
	v_lshlrev_b32_e32 v20, 16, v175
	v_and_b32_e32 v21, 0xffff0000, v175
	v_pk_add_f32 v[172:173], v[14:15], v[16:17]
	v_pk_add_f32 v[174:175], v[18:19], v[20:21]
	v_lshlrev_b32_e32 v14, 16, v176
	v_and_b32_e32 v15, 0xffff0000, v176
	v_lshlrev_b32_e32 v16, 16, v178
	v_and_b32_e32 v17, 0xffff0000, v178
	v_lshlrev_b32_e32 v18, 16, v177
	v_and_b32_e32 v19, 0xffff0000, v177
	v_lshlrev_b32_e32 v20, 16, v179
	v_and_b32_e32 v21, 0xffff0000, v179
	v_pk_add_f32 v[176:177], v[14:15], v[16:17]
	v_pk_add_f32 v[178:179], v[18:19], v[20:21]
	v_lshlrev_b32_e32 v14, 16, v204
	v_and_b32_e32 v15, 0xffff0000, v204
	v_lshlrev_b32_e32 v16, 16, v206
	v_and_b32_e32 v17, 0xffff0000, v206
	v_lshlrev_b32_e32 v18, 16, v205
	v_and_b32_e32 v19, 0xffff0000, v205
	v_lshlrev_b32_e32 v20, 16, v207
	v_and_b32_e32 v21, 0xffff0000, v207
	v_pk_add_f32 v[204:205], v[14:15], v[16:17]
	v_pk_add_f32 v[206:207], v[18:19], v[20:21]
	v_lshlrev_b32_e32 v14, 16, v214
	v_and_b32_e32 v15, 0xffff0000, v214
	v_lshlrev_b32_e32 v16, 16, v216
	v_and_b32_e32 v17, 0xffff0000, v216
	v_lshlrev_b32_e32 v18, 16, v215
	v_and_b32_e32 v19, 0xffff0000, v215
	v_lshlrev_b32_e32 v20, 16, v217
	v_and_b32_e32 v21, 0xffff0000, v217
	v_pk_add_f32 v[214:215], v[14:15], v[16:17]
	v_pk_add_f32 v[216:217], v[18:19], v[20:21]
	v_pk_mul_f32 v[12:13], v[172:173], v[172:173]
	v_pk_fma_f32 v[12:13], v[174:175], v[174:175], v[12:13]
	v_pk_fma_f32 v[12:13], v[176:177], v[176:177], v[12:13]
	v_pk_fma_f32 v[12:13], v[178:179], v[178:179], v[12:13]
	v_pk_fma_f32 v[12:13], v[204:205], v[204:205], v[12:13]
	v_pk_fma_f32 v[12:13], v[206:207], v[206:207], v[12:13]
	v_pk_fma_f32 v[12:13], v[214:215], v[214:215], v[12:13]
	v_pk_fma_f32 v[12:13], v[216:217], v[216:217], v[12:13]
	v_add_f32_e32 v5, v12, v13
	s_nop 1
	v_add_f32_dpp v5, v5, v5 quad_perm:[1,0,3,2] row_mask:0xf bank_mask:0xf
	s_nop 1
	v_add_f32_dpp v5, v5, v5 quad_perm:[2,3,0,1] row_mask:0xf bank_mask:0xf
	s_nop 1
	v_add_f32_dpp v5, v5, v5 row_half_mirror row_mask:0xf bank_mask:0xf
	s_nop 1
	v_add_f32_dpp v5, v5, v5 row_mirror row_mask:0xf bank_mask:0xf
	s_nop 1
	v_add_f32_dpp v5, v5, v5 row_bcast:15 row_mask:0xa bank_mask:0xf
	s_nop 1
	v_add_f32_dpp v5, v5, v5 row_bcast:31 row_mask:0xc bank_mask:0xf
	s_nop 1
	v_readlane_b32 s32, v5, 63
	s_nop 1
	v_mov_b32_e32 v6, s32
	v_fmamk_f32 v6, v6, 0x3a800000, v146
	v_rsq_f32_e32 v6, v6
	s_nop 0
	v_mul_f32_e32 v8, 0.5, v6
	v_pk_mul_f32 v[14:15], v[172:173], v[8:9] op_sel_hi:[1,0]
	v_pk_mul_f32 v[14:15], v[38:39], v[14:15]
	v_pk_fma_f32 v[154:155], v[22:23], v[14:15], v[154:155]
	v_pk_mul_f32 v[14:15], v[174:175], v[8:9] op_sel_hi:[1,0]
	v_pk_mul_f32 v[14:15], v[40:41], v[14:15]
	v_pk_fma_f32 v[156:157], v[24:25], v[14:15], v[156:157]
	v_pk_mul_f32 v[14:15], v[176:177], v[8:9] op_sel_hi:[1,0]
	v_pk_mul_f32 v[14:15], v[42:43], v[14:15]
	v_pk_fma_f32 v[158:159], v[26:27], v[14:15], v[158:159]
	v_pk_mul_f32 v[14:15], v[178:179], v[8:9] op_sel_hi:[1,0]
	v_pk_mul_f32 v[14:15], v[44:45], v[14:15]
	v_pk_fma_f32 v[160:161], v[28:29], v[14:15], v[160:161]
	v_pk_mul_f32 v[14:15], v[204:205], v[8:9] op_sel_hi:[1,0]
	v_pk_mul_f32 v[14:15], v[46:47], v[14:15]
	v_pk_fma_f32 v[162:163], v[30:31], v[14:15], v[162:163]
	v_pk_mul_f32 v[14:15], v[206:207], v[8:9] op_sel_hi:[1,0]
	v_pk_mul_f32 v[14:15], v[48:49], v[14:15]
	v_pk_fma_f32 v[164:165], v[32:33], v[14:15], v[164:165]
	v_pk_mul_f32 v[14:15], v[214:215], v[8:9] op_sel_hi:[1,0]
	v_pk_mul_f32 v[14:15], v[50:51], v[14:15]
	v_pk_fma_f32 v[168:169], v[34:35], v[14:15], v[168:169]
	v_pk_mul_f32 v[14:15], v[216:217], v[8:9] op_sel_hi:[1,0]
	v_pk_mul_f32 v[14:15], v[52:53], v[14:15]
	v_pk_fma_f32 v[170:171], v[36:37], v[14:15], v[170:171]
	v_pk_mul_f32 v[12:13], v[154:155], v[154:155]
	v_pk_fma_f32 v[12:13], v[156:157], v[156:157], v[12:13]
	v_pk_fma_f32 v[12:13], v[158:159], v[158:159], v[12:13]
	v_pk_fma_f32 v[12:13], v[160:161], v[160:161], v[12:13]
	v_pk_fma_f32 v[12:13], v[162:163], v[162:163], v[12:13]
	v_pk_fma_f32 v[12:13], v[164:165], v[164:165], v[12:13]
	v_pk_fma_f32 v[12:13], v[168:169], v[168:169], v[12:13]
	v_pk_fma_f32 v[12:13], v[170:171], v[170:171], v[12:13]
	v_add_f32_e32 v5, v12, v13
	s_nop 1
	v_add_f32_dpp v5, v5, v5 quad_perm:[1,0,3,2] row_mask:0xf bank_mask:0xf
	s_nop 1
	v_add_f32_dpp v5, v5, v5 quad_perm:[2,3,0,1] row_mask:0xf bank_mask:0xf
	s_nop 1
	v_add_f32_dpp v5, v5, v5 row_half_mirror row_mask:0xf bank_mask:0xf
	s_nop 1
	v_add_f32_dpp v5, v5, v5 row_mirror row_mask:0xf bank_mask:0xf
	s_nop 1
	v_add_f32_dpp v5, v5, v5 row_bcast:15 row_mask:0xa bank_mask:0xf
	s_nop 1
	v_add_f32_dpp v5, v5, v5 row_bcast:31 row_mask:0xc bank_mask:0xf
	s_nop 1
	v_readlane_b32 s32, v5, 63
	s_nop 1
	v_mov_b32_e32 v6, s32
	v_fmamk_f32 v6, v6, 0x3a800000, v146
	v_rsq_f32_e32 v6, v6
	s_nop 0
	v_mov_b32_e32 v10, v6
	v_pk_mul_f32 v[14:15], v[154:155], v[10:11] op_sel_hi:[1,0]
	v_pk_mul_f32 v[14:15], v[86:87], v[14:15]
	v_pk_fma_f32 v[16:17], v[70:71], v[14:15], v[54:55]
	v_pk_mul_f32 v[14:15], v[156:157], v[10:11] op_sel_hi:[1,0]
	v_pk_mul_f32 v[14:15], v[88:89], v[14:15]
	v_pk_fma_f32 v[18:19], v[72:73], v[14:15], v[56:57]
	v_cvt_pk_bf16_f32 v172, v16, v17
	v_cvt_pk_bf16_f32 v173, v18, v19
	v_pk_mul_f32 v[14:15], v[158:159], v[10:11] op_sel_hi:[1,0]
	v_pk_mul_f32 v[14:15], v[90:91], v[14:15]
	v_pk_fma_f32 v[16:17], v[74:75], v[14:15], v[58:59]
	v_pk_mul_f32 v[14:15], v[160:161], v[10:11] op_sel_hi:[1,0]
	v_pk_mul_f32 v[14:15], v[92:93], v[14:15]
	v_pk_fma_f32 v[18:19], v[76:77], v[14:15], v[60:61]
	v_cvt_pk_bf16_f32 v176, v16, v17
	v_cvt_pk_bf16_f32 v177, v18, v19
	v_pk_mul_f32 v[14:15], v[162:163], v[10:11] op_sel_hi:[1,0]
	v_pk_mul_f32 v[14:15], v[94:95], v[14:15]
	v_pk_fma_f32 v[16:17], v[78:79], v[14:15], v[62:63]
	v_pk_mul_f32 v[14:15], v[164:165], v[10:11] op_sel_hi:[1,0]
	v_pk_mul_f32 v[14:15], v[96:97], v[14:15]
	v_pk_fma_f32 v[18:19], v[80:81], v[14:15], v[64:65]
	v_cvt_pk_bf16_f32 v204, v16, v17
	v_cvt_pk_bf16_f32 v205, v18, v19
	v_pk_mul_f32 v[14:15], v[168:169], v[10:11] op_sel_hi:[1,0]
	v_pk_mul_f32 v[14:15], v[98:99], v[14:15]
	v_pk_fma_f32 v[16:17], v[82:83], v[14:15], v[66:67]
	v_pk_mul_f32 v[14:15], v[170:171], v[10:11] op_sel_hi:[1,0]
	v_pk_mul_f32 v[14:15], v[100:101], v[14:15]
	v_pk_fma_f32 v[18:19], v[84:85], v[14:15], v[68:69]
	v_cvt_pk_bf16_f32 v214, v16, v17
	v_cvt_pk_bf16_f32 v215, v18, v19
	global_store_dwordx4 v0, v[154:157], s[46:47] offset:0 sc1
	global_store_dwordx4 v0, v[158:161], s[46:47] offset:1024 sc1
	global_store_dwordx4 v0, v[162:165], s[46:47] offset:2048 sc1
	global_store_dwordx4 v0, v[168:171], s[46:47] offset:3072 sc1
	global_store_dwordx2 v1, v[172:173], s[62:63] offset:0 sc1
	global_store_dwordx2 v1, v[176:177], s[62:63] offset:512 sc1
	global_store_dwordx2 v1, v[204:205], s[62:63] offset:1024 sc1
	global_store_dwordx2 v1, v[214:215], s[62:63] offset:1536 sc1
	s_add_u32 s46, s46, 0x1000
	s_addc_u32 s47, s47, 0
	s_add_u32 s62, s62, 0x800
	s_addc_u32 s63, s63, 0
	s_waitcnt vmcnt(28)
	v_lshlrev_b32_e32 v14, 16, v234
	v_and_b32_e32 v15, 0xffff0000, v234
	v_lshlrev_b32_e32 v16, 16, v236
	v_and_b32_e32 v17, 0xffff0000, v236
	v_lshlrev_b32_e32 v18, 16, v235
	v_and_b32_e32 v19, 0xffff0000, v235
	v_lshlrev_b32_e32 v20, 16, v237
	v_and_b32_e32 v21, 0xffff0000, v237
	v_pk_add_f32 v[234:235], v[14:15], v[16:17]
	v_pk_add_f32 v[236:237], v[18:19], v[20:21]
	v_lshlrev_b32_e32 v14, 16, v238
	v_and_b32_e32 v15, 0xffff0000, v238
	v_lshlrev_b32_e32 v16, 16, v240
	v_and_b32_e32 v17, 0xffff0000, v240
	v_lshlrev_b32_e32 v18, 16, v239
	v_and_b32_e32 v19, 0xffff0000, v239
	v_lshlrev_b32_e32 v20, 16, v241
	v_and_b32_e32 v21, 0xffff0000, v241
	v_pk_add_f32 v[238:239], v[14:15], v[16:17]
	v_pk_add_f32 v[240:241], v[18:19], v[20:21]
	v_lshlrev_b32_e32 v14, 16, v242
	v_and_b32_e32 v15, 0xffff0000, v242
	v_lshlrev_b32_e32 v16, 16, v244
	v_and_b32_e32 v17, 0xffff0000, v244
	v_lshlrev_b32_e32 v18, 16, v243
	v_and_b32_e32 v19, 0xffff0000, v243
	v_lshlrev_b32_e32 v20, 16, v245
	v_and_b32_e32 v21, 0xffff0000, v245
	v_pk_add_f32 v[242:243], v[14:15], v[16:17]
	v_pk_add_f32 v[244:245], v[18:19], v[20:21]
	v_lshlrev_b32_e32 v14, 16, v246
	v_and_b32_e32 v15, 0xffff0000, v246
	v_lshlrev_b32_e32 v16, 16, v248
	v_and_b32_e32 v17, 0xffff0000, v248
	v_lshlrev_b32_e32 v18, 16, v247
	v_and_b32_e32 v19, 0xffff0000, v247
	v_lshlrev_b32_e32 v20, 16, v249
	v_and_b32_e32 v21, 0xffff0000, v249
	v_pk_add_f32 v[246:247], v[14:15], v[16:17]
	v_pk_add_f32 v[248:249], v[18:19], v[20:21]
	v_pk_mul_f32 v[12:13], v[234:235], v[234:235]
	v_pk_fma_f32 v[12:13], v[236:237], v[236:237], v[12:13]
	v_pk_fma_f32 v[12:13], v[238:239], v[238:239], v[12:13]
	v_pk_fma_f32 v[12:13], v[240:241], v[240:241], v[12:13]
	v_pk_fma_f32 v[12:13], v[242:243], v[242:243], v[12:13]
	v_pk_fma_f32 v[12:13], v[244:245], v[244:245], v[12:13]
	v_pk_fma_f32 v[12:13], v[246:247], v[246:247], v[12:13]
	v_pk_fma_f32 v[12:13], v[248:249], v[248:249], v[12:13]
	v_add_f32_e32 v5, v12, v13
	s_nop 1
	v_add_f32_dpp v5, v5, v5 quad_perm:[1,0,3,2] row_mask:0xf bank_mask:0xf
	s_nop 1
	v_add_f32_dpp v5, v5, v5 quad_perm:[2,3,0,1] row_mask:0xf bank_mask:0xf
	s_nop 1
	v_add_f32_dpp v5, v5, v5 row_half_mirror row_mask:0xf bank_mask:0xf
	s_nop 1
	v_add_f32_dpp v5, v5, v5 row_mirror row_mask:0xf bank_mask:0xf
	s_nop 1
	v_add_f32_dpp v5, v5, v5 row_bcast:15 row_mask:0xa bank_mask:0xf
	s_nop 1
	v_add_f32_dpp v5, v5, v5 row_bcast:31 row_mask:0xc bank_mask:0xf
	s_nop 1
	v_readlane_b32 s32, v5, 63
	s_nop 1
	v_mov_b32_e32 v6, s32
	v_fmamk_f32 v6, v6, 0x3a800000, v146
	v_rsq_f32_e32 v6, v6
	s_nop 0
	v_mul_f32_e32 v8, 0.5, v6
	v_pk_mul_f32 v[14:15], v[234:235], v[8:9] op_sel_hi:[1,0]
	v_pk_mul_f32 v[14:15], v[38:39], v[14:15]
	v_pk_fma_f32 v[218:219], v[22:23], v[14:15], v[218:219]
	v_pk_mul_f32 v[14:15], v[236:237], v[8:9] op_sel_hi:[1,0]
	v_pk_mul_f32 v[14:15], v[40:41], v[14:15]
	v_pk_fma_f32 v[220:221], v[24:25], v[14:15], v[220:221]
	v_pk_mul_f32 v[14:15], v[238:239], v[8:9] op_sel_hi:[1,0]
	v_pk_mul_f32 v[14:15], v[42:43], v[14:15]
	v_pk_fma_f32 v[222:223], v[26:27], v[14:15], v[222:223]
	v_pk_mul_f32 v[14:15], v[240:241], v[8:9] op_sel_hi:[1,0]
	v_pk_mul_f32 v[14:15], v[44:45], v[14:15]
	v_pk_fma_f32 v[224:225], v[28:29], v[14:15], v[224:225]
	v_pk_mul_f32 v[14:15], v[242:243], v[8:9] op_sel_hi:[1,0]
	v_pk_mul_f32 v[14:15], v[46:47], v[14:15]
	v_pk_fma_f32 v[226:227], v[30:31], v[14:15], v[226:227]
	v_pk_mul_f32 v[14:15], v[244:245], v[8:9] op_sel_hi:[1,0]
	v_pk_mul_f32 v[14:15], v[48:49], v[14:15]
	v_pk_fma_f32 v[228:229], v[32:33], v[14:15], v[228:229]
	v_pk_mul_f32 v[14:15], v[246:247], v[8:9] op_sel_hi:[1,0]
	v_pk_mul_f32 v[14:15], v[50:51], v[14:15]
	v_pk_fma_f32 v[230:231], v[34:35], v[14:15], v[230:231]
	v_pk_mul_f32 v[14:15], v[248:249], v[8:9] op_sel_hi:[1,0]
	v_pk_mul_f32 v[14:15], v[52:53], v[14:15]
	v_pk_fma_f32 v[232:233], v[36:37], v[14:15], v[232:233]
	v_pk_mul_f32 v[12:13], v[218:219], v[218:219]
	v_pk_fma_f32 v[12:13], v[220:221], v[220:221], v[12:13]
	v_pk_fma_f32 v[12:13], v[222:223], v[222:223], v[12:13]
	v_pk_fma_f32 v[12:13], v[224:225], v[224:225], v[12:13]
	v_pk_fma_f32 v[12:13], v[226:227], v[226:227], v[12:13]
	v_pk_fma_f32 v[12:13], v[228:229], v[228:229], v[12:13]
	v_pk_fma_f32 v[12:13], v[230:231], v[230:231], v[12:13]
	v_pk_fma_f32 v[12:13], v[232:233], v[232:233], v[12:13]
	v_add_f32_e32 v5, v12, v13
	s_nop 1
	v_add_f32_dpp v5, v5, v5 quad_perm:[1,0,3,2] row_mask:0xf bank_mask:0xf
	s_nop 1
	v_add_f32_dpp v5, v5, v5 quad_perm:[2,3,0,1] row_mask:0xf bank_mask:0xf
	s_nop 1
	v_add_f32_dpp v5, v5, v5 row_half_mirror row_mask:0xf bank_mask:0xf
	s_nop 1
	v_add_f32_dpp v5, v5, v5 row_mirror row_mask:0xf bank_mask:0xf
	s_nop 1
	v_add_f32_dpp v5, v5, v5 row_bcast:15 row_mask:0xa bank_mask:0xf
	s_nop 1
	v_add_f32_dpp v5, v5, v5 row_bcast:31 row_mask:0xc bank_mask:0xf
	s_nop 1
	v_readlane_b32 s32, v5, 63
	s_nop 1
	v_mov_b32_e32 v6, s32
	v_fmamk_f32 v6, v6, 0x3a800000, v146
	v_rsq_f32_e32 v6, v6
	s_nop 0
	v_mov_b32_e32 v10, v6
	v_pk_mul_f32 v[14:15], v[218:219], v[10:11] op_sel_hi:[1,0]
	v_pk_mul_f32 v[14:15], v[86:87], v[14:15]
	v_pk_fma_f32 v[16:17], v[70:71], v[14:15], v[54:55]
	v_pk_mul_f32 v[14:15], v[220:221], v[10:11] op_sel_hi:[1,0]
	v_pk_mul_f32 v[14:15], v[88:89], v[14:15]
	v_pk_fma_f32 v[18:19], v[72:73], v[14:15], v[56:57]
	v_cvt_pk_bf16_f32 v234, v16, v17
	v_cvt_pk_bf16_f32 v235, v18, v19
	v_pk_mul_f32 v[14:15], v[222:223], v[10:11] op_sel_hi:[1,0]
	v_pk_mul_f32 v[14:15], v[90:91], v[14:15]
	v_pk_fma_f32 v[16:17], v[74:75], v[14:15], v[58:59]
	v_pk_mul_f32 v[14:15], v[224:225], v[10:11] op_sel_hi:[1,0]
	v_pk_mul_f32 v[14:15], v[92:93], v[14:15]
	v_pk_fma_f32 v[18:19], v[76:77], v[14:15], v[60:61]
	v_cvt_pk_bf16_f32 v238, v16, v17
	v_cvt_pk_bf16_f32 v239, v18, v19
	v_pk_mul_f32 v[14:15], v[226:227], v[10:11] op_sel_hi:[1,0]
	v_pk_mul_f32 v[14:15], v[94:95], v[14:15]
	v_pk_fma_f32 v[16:17], v[78:79], v[14:15], v[62:63]
	v_pk_mul_f32 v[14:15], v[228:229], v[10:11] op_sel_hi:[1,0]
	v_pk_mul_f32 v[14:15], v[96:97], v[14:15]
	v_pk_fma_f32 v[18:19], v[80:81], v[14:15], v[64:65]
	v_cvt_pk_bf16_f32 v242, v16, v17
	v_cvt_pk_bf16_f32 v243, v18, v19
	v_pk_mul_f32 v[14:15], v[230:231], v[10:11] op_sel_hi:[1,0]
	v_pk_mul_f32 v[14:15], v[98:99], v[14:15]
	v_pk_fma_f32 v[16:17], v[82:83], v[14:15], v[66:67]
	v_pk_mul_f32 v[14:15], v[232:233], v[10:11] op_sel_hi:[1,0]
	v_pk_mul_f32 v[14:15], v[100:101], v[14:15]
	v_pk_fma_f32 v[18:19], v[84:85], v[14:15], v[68:69]
	v_cvt_pk_bf16_f32 v246, v16, v17
	v_cvt_pk_bf16_f32 v247, v18, v19
	global_store_dwordx4 v0, v[218:221], s[46:47] offset:0 sc1
	global_store_dwordx4 v0, v[222:225], s[46:47] offset:1024 sc1
	global_store_dwordx4 v0, v[226:229], s[46:47] offset:2048 sc1
	global_store_dwordx4 v0, v[230:233], s[46:47] offset:3072 sc1
	global_store_dwordx2 v1, v[234:235], s[62:63] offset:0 sc1
	global_store_dwordx2 v1, v[238:239], s[62:63] offset:512 sc1
	global_store_dwordx2 v1, v[242:243], s[62:63] offset:1024 sc1
	global_store_dwordx2 v1, v[246:247], s[62:63] offset:1536 sc1
	s_add_u32 s46, s46, 0x1000
	s_addc_u32 s47, s47, 0
	s_add_u32 s62, s62, 0x800
	s_addc_u32 s63, s63, 0
	s_waitcnt vmcnt(16)
	v_lshlrev_b32_e32 v14, 16, v118
	v_and_b32_e32 v15, 0xffff0000, v118
	v_lshlrev_b32_e32 v16, 16, v120
	v_and_b32_e32 v17, 0xffff0000, v120
	v_lshlrev_b32_e32 v18, 16, v119
	v_and_b32_e32 v19, 0xffff0000, v119
	v_lshlrev_b32_e32 v20, 16, v121
	v_and_b32_e32 v21, 0xffff0000, v121
	v_pk_add_f32 v[118:119], v[14:15], v[16:17]
	v_pk_add_f32 v[120:121], v[18:19], v[20:21]
	v_lshlrev_b32_e32 v14, 16, v122
	v_and_b32_e32 v15, 0xffff0000, v122
	v_lshlrev_b32_e32 v16, 16, v124
	v_and_b32_e32 v17, 0xffff0000, v124
	v_lshlrev_b32_e32 v18, 16, v123
	v_and_b32_e32 v19, 0xffff0000, v123
	v_lshlrev_b32_e32 v20, 16, v125
	v_and_b32_e32 v21, 0xffff0000, v125
	v_pk_add_f32 v[122:123], v[14:15], v[16:17]
	v_pk_add_f32 v[124:125], v[18:19], v[20:21]
	v_lshlrev_b32_e32 v14, 16, v134
	v_and_b32_e32 v15, 0xffff0000, v134
	v_lshlrev_b32_e32 v16, 16, v136
	v_and_b32_e32 v17, 0xffff0000, v136
	v_lshlrev_b32_e32 v18, 16, v135
	v_and_b32_e32 v19, 0xffff0000, v135
	v_lshlrev_b32_e32 v20, 16, v137
	v_and_b32_e32 v21, 0xffff0000, v137
	v_pk_add_f32 v[134:135], v[14:15], v[16:17]
	v_pk_add_f32 v[136:137], v[18:19], v[20:21]
	v_lshlrev_b32_e32 v14, 16, v138
	v_and_b32_e32 v15, 0xffff0000, v138
	v_lshlrev_b32_e32 v16, 16, v140
	v_and_b32_e32 v17, 0xffff0000, v140
	v_lshlrev_b32_e32 v18, 16, v139
	v_and_b32_e32 v19, 0xffff0000, v139
	v_lshlrev_b32_e32 v20, 16, v141
	v_and_b32_e32 v21, 0xffff0000, v141
	v_pk_add_f32 v[138:139], v[14:15], v[16:17]
	v_pk_add_f32 v[140:141], v[18:19], v[20:21]
	v_pk_mul_f32 v[12:13], v[118:119], v[118:119]
	v_pk_fma_f32 v[12:13], v[120:121], v[120:121], v[12:13]
	v_pk_fma_f32 v[12:13], v[122:123], v[122:123], v[12:13]
	v_pk_fma_f32 v[12:13], v[124:125], v[124:125], v[12:13]
	v_pk_fma_f32 v[12:13], v[134:135], v[134:135], v[12:13]
	v_pk_fma_f32 v[12:13], v[136:137], v[136:137], v[12:13]
	v_pk_fma_f32 v[12:13], v[138:139], v[138:139], v[12:13]
	v_pk_fma_f32 v[12:13], v[140:141], v[140:141], v[12:13]
	v_add_f32_e32 v5, v12, v13
	s_nop 1
	v_add_f32_dpp v5, v5, v5 quad_perm:[1,0,3,2] row_mask:0xf bank_mask:0xf
	s_nop 1
	v_add_f32_dpp v5, v5, v5 quad_perm:[2,3,0,1] row_mask:0xf bank_mask:0xf
	s_nop 1
	v_add_f32_dpp v5, v5, v5 row_half_mirror row_mask:0xf bank_mask:0xf
	s_nop 1
	v_add_f32_dpp v5, v5, v5 row_mirror row_mask:0xf bank_mask:0xf
	s_nop 1
	v_add_f32_dpp v5, v5, v5 row_bcast:15 row_mask:0xa bank_mask:0xf
	s_nop 1
	v_add_f32_dpp v5, v5, v5 row_bcast:31 row_mask:0xc bank_mask:0xf
	s_nop 1
	v_readlane_b32 s32, v5, 63
	s_nop 1
	v_mov_b32_e32 v6, s32
	v_fmamk_f32 v6, v6, 0x3a800000, v146
	v_rsq_f32_e32 v6, v6
	s_nop 0
	v_mul_f32_e32 v8, 0.5, v6
	v_pk_mul_f32 v[14:15], v[118:119], v[8:9] op_sel_hi:[1,0]
	v_pk_mul_f32 v[14:15], v[38:39], v[14:15]
	v_pk_fma_f32 v[102:103], v[22:23], v[14:15], v[102:103]
	v_pk_mul_f32 v[14:15], v[120:121], v[8:9] op_sel_hi:[1,0]
	v_pk_mul_f32 v[14:15], v[40:41], v[14:15]
	v_pk_fma_f32 v[104:105], v[24:25], v[14:15], v[104:105]
	v_pk_mul_f32 v[14:15], v[122:123], v[8:9] op_sel_hi:[1,0]
	v_pk_mul_f32 v[14:15], v[42:43], v[14:15]
	v_pk_fma_f32 v[106:107], v[26:27], v[14:15], v[106:107]
	v_pk_mul_f32 v[14:15], v[124:125], v[8:9] op_sel_hi:[1,0]
	v_pk_mul_f32 v[14:15], v[44:45], v[14:15]
	v_pk_fma_f32 v[108:109], v[28:29], v[14:15], v[108:109]
	v_pk_mul_f32 v[14:15], v[134:135], v[8:9] op_sel_hi:[1,0]
	v_pk_mul_f32 v[14:15], v[46:47], v[14:15]
	v_pk_fma_f32 v[110:111], v[30:31], v[14:15], v[110:111]
	v_pk_mul_f32 v[14:15], v[136:137], v[8:9] op_sel_hi:[1,0]
	v_pk_mul_f32 v[14:15], v[48:49], v[14:15]
	v_pk_fma_f32 v[112:113], v[32:33], v[14:15], v[112:113]
	v_pk_mul_f32 v[14:15], v[138:139], v[8:9] op_sel_hi:[1,0]
	v_pk_mul_f32 v[14:15], v[50:51], v[14:15]
	v_pk_fma_f32 v[114:115], v[34:35], v[14:15], v[114:115]
	v_pk_mul_f32 v[14:15], v[140:141], v[8:9] op_sel_hi:[1,0]
	v_pk_mul_f32 v[14:15], v[52:53], v[14:15]
	v_pk_fma_f32 v[116:117], v[36:37], v[14:15], v[116:117]
	v_pk_mul_f32 v[12:13], v[102:103], v[102:103]
	v_pk_fma_f32 v[12:13], v[104:105], v[104:105], v[12:13]
	v_pk_fma_f32 v[12:13], v[106:107], v[106:107], v[12:13]
	v_pk_fma_f32 v[12:13], v[108:109], v[108:109], v[12:13]
	v_pk_fma_f32 v[12:13], v[110:111], v[110:111], v[12:13]
	v_pk_fma_f32 v[12:13], v[112:113], v[112:113], v[12:13]
	v_pk_fma_f32 v[12:13], v[114:115], v[114:115], v[12:13]
	v_pk_fma_f32 v[12:13], v[116:117], v[116:117], v[12:13]
	v_add_f32_e32 v5, v12, v13
	s_nop 1
	v_add_f32_dpp v5, v5, v5 quad_perm:[1,0,3,2] row_mask:0xf bank_mask:0xf
	s_nop 1
	v_add_f32_dpp v5, v5, v5 quad_perm:[2,3,0,1] row_mask:0xf bank_mask:0xf
	s_nop 1
	v_add_f32_dpp v5, v5, v5 row_half_mirror row_mask:0xf bank_mask:0xf
	s_nop 1
	v_add_f32_dpp v5, v5, v5 row_mirror row_mask:0xf bank_mask:0xf
	s_nop 1
	v_add_f32_dpp v5, v5, v5 row_bcast:15 row_mask:0xa bank_mask:0xf
	s_nop 1
	v_add_f32_dpp v5, v5, v5 row_bcast:31 row_mask:0xc bank_mask:0xf
	s_nop 1
	v_readlane_b32 s32, v5, 63
	s_nop 1
	v_mov_b32_e32 v6, s32
	v_fmamk_f32 v6, v6, 0x3a800000, v146
	v_rsq_f32_e32 v6, v6
	s_nop 0
	v_mov_b32_e32 v10, v6
	v_pk_mul_f32 v[14:15], v[102:103], v[10:11] op_sel_hi:[1,0]
	v_pk_mul_f32 v[14:15], v[86:87], v[14:15]
	v_pk_fma_f32 v[16:17], v[70:71], v[14:15], v[54:55]
	v_pk_mul_f32 v[14:15], v[104:105], v[10:11] op_sel_hi:[1,0]
	v_pk_mul_f32 v[14:15], v[88:89], v[14:15]
	v_pk_fma_f32 v[18:19], v[72:73], v[14:15], v[56:57]
	v_cvt_pk_bf16_f32 v118, v16, v17
	v_cvt_pk_bf16_f32 v119, v18, v19
	v_pk_mul_f32 v[14:15], v[106:107], v[10:11] op_sel_hi:[1,0]
	v_pk_mul_f32 v[14:15], v[90:91], v[14:15]
	v_pk_fma_f32 v[16:17], v[74:75], v[14:15], v[58:59]
	v_pk_mul_f32 v[14:15], v[108:109], v[10:11] op_sel_hi:[1,0]
	v_pk_mul_f32 v[14:15], v[92:93], v[14:15]
	v_pk_fma_f32 v[18:19], v[76:77], v[14:15], v[60:61]
	v_cvt_pk_bf16_f32 v122, v16, v17
	v_cvt_pk_bf16_f32 v123, v18, v19
	v_pk_mul_f32 v[14:15], v[110:111], v[10:11] op_sel_hi:[1,0]
	v_pk_mul_f32 v[14:15], v[94:95], v[14:15]
	v_pk_fma_f32 v[16:17], v[78:79], v[14:15], v[62:63]
	v_pk_mul_f32 v[14:15], v[112:113], v[10:11] op_sel_hi:[1,0]
	v_pk_mul_f32 v[14:15], v[96:97], v[14:15]
	v_pk_fma_f32 v[18:19], v[80:81], v[14:15], v[64:65]
	v_cvt_pk_bf16_f32 v134, v16, v17
	v_cvt_pk_bf16_f32 v135, v18, v19
	v_pk_mul_f32 v[14:15], v[114:115], v[10:11] op_sel_hi:[1,0]
	v_pk_mul_f32 v[14:15], v[98:99], v[14:15]
	v_pk_fma_f32 v[16:17], v[82:83], v[14:15], v[66:67]
	v_pk_mul_f32 v[14:15], v[116:117], v[10:11] op_sel_hi:[1,0]
	v_pk_mul_f32 v[14:15], v[100:101], v[14:15]
	v_pk_fma_f32 v[18:19], v[84:85], v[14:15], v[68:69]
	v_cvt_pk_bf16_f32 v138, v16, v17
	v_cvt_pk_bf16_f32 v139, v18, v19
	global_store_dwordx4 v0, v[102:105], s[46:47] offset:0 sc1
	global_store_dwordx4 v0, v[106:109], s[46:47] offset:1024 sc1
	global_store_dwordx4 v0, v[110:113], s[46:47] offset:2048 sc1
	global_store_dwordx4 v0, v[114:117], s[46:47] offset:3072 sc1
	global_store_dwordx2 v1, v[118:119], s[62:63] offset:0 sc1
	global_store_dwordx2 v1, v[122:123], s[62:63] offset:512 sc1
	global_store_dwordx2 v1, v[134:135], s[62:63] offset:1024 sc1
	global_store_dwordx2 v1, v[138:139], s[62:63] offset:1536 sc1
	s_add_u32 s46, s46, 0x1000
	s_addc_u32 s47, s47, 0
	s_add_u32 s62, s62, 0x800
	s_addc_u32 s63, s63, 0
	s_branch .Lnorm0_done
.Lnorm0_first:
	v_readlane_b32 s2, v255, 0
	v_readfirstlane_b32 s7, v147
	s_load_dwordx2 s[4:5], s[0:1], 0x90
	s_load_dwordx2 s[12:13], s[0:1], 0x98
	s_load_dwordx2 s[14:15], s[0:1], 0x40
	s_load_dwordx2 s[58:59], s[0:1], 0x0
	s_load_dwordx2 s[60:61], s[0:1], 0x8
	v_and_b32_e32 v0, 63, v147
	v_lshlrev_b32_e32 v1, 3, v0
	v_lshlrev_b32_e32 v0, 4, v0
	s_lshr_b32 s7, s7, 6
	s_and_b32 s27, s2, 6
	s_lshl_b32 s27, s27, 5
	s_and_b32 s37, s2, 0x39
	s_or_b32 s27, s27, s37
	s_lshr_b32 s37, s2, 6
	s_lshl_b32 s37, s37, 1
	s_or_b32 s2, s27, s37
	s_lshl_b32 s2, s2, 3
	s_add_u32 s2, s2, s7
	s_lshl_b32 s24, s2, 2
	s_sub_u32 s27, s24, 0x1000
	s_lshr_b32 s27, s27, 10
	s_add_u32 s27, s27, 1
	s_cmp_lt_u32 s24, 0x1000
	s_cselect_b32 s30, 0, s27
	v_mov_b32_e32 v3, v0
	v_add_u32_e32 v4, 0x1000, v0
	s_waitcnt lgkmcnt(0)
	s_lshl_b32 s27, s24, 11
	s_add_u32 s62, s12, s27
	s_addc_u32 s63, s13, 0
	s_add_u32 s62, s62, 0x1000000
	s_addc_u32 s63, s63, 0
	s_lshl_b32 s27, s24, 12
	s_add_u32 s46, s4, s27
	s_addc_u32 s47, s5, 0
	s_sub_u32 s37, s27, 0x1000000
	s_cmp_lt_u32 s24, 0x1000
	s_cselect_b32 s4, s58, s60
	s_cselect_b32 s5, s59, s61
	s_cselect_b32 s27, s27, s37
	s_add_u32 s4, s4, s27
	s_addc_u32 s5, s5, 0
	s_mul_i32 s27, s70, 5
	s_add_u32 s27, s27, s30
	s_mul_i32 s27, s27, 0x9000
	s_add_u32 s27, s27, 0x100000
	s_add_u32 s88, s12, s27
	s_addc_u32 s89, s13, 0
	s_mul_i32 s27, s70, 0x3000
	s_add_u32 s14, s14, s27
	s_addc_u32 s15, s15, 0
	global_load_dwordx4 v[22:25], v3, s[88:89] offset:0
	global_load_dwordx4 v[38:41], v4, s[88:89] offset:0
	global_load_dwordx4 v[54:57], v0, s[14:15] offset:0
	global_load_dwordx4 v[26:29], v3, s[88:89] offset:1024
	global_load_dwordx4 v[42:45], v4, s[88:89] offset:1024
	global_load_dwordx4 v[58:61], v0, s[14:15] offset:1024
	global_load_dwordx4 v[30:33], v3, s[88:89] offset:2048
	global_load_dwordx4 v[46:49], v4, s[88:89] offset:2048
	global_load_dwordx4 v[62:65], v0, s[14:15] offset:2048
	global_load_dwordx4 v[34:37], v3, s[88:89] offset:3072
	global_load_dwordx4 v[50:53], v4, s[88:89] offset:3072
	global_load_dwordx4 v[66:69], v0, s[14:15] offset:3072
	global_load_dwordx4 v[70:73], v0, s[4:5] offset:0 nt
	global_load_dwordx4 v[74:77], v0, s[4:5] offset:1024 nt
	global_load_dwordx4 v[78:81], v0, s[4:5] offset:2048 nt
	global_load_dwordx4 v[82:85], v0, s[4:5] offset:3072 nt
	s_add_u32 s4, s4, 0x1000
	s_addc_u32 s5, s5, 0
	global_load_dwordx4 v[86:89], v0, s[4:5] offset:0 nt
	global_load_dwordx4 v[90:93], v0, s[4:5] offset:1024 nt
	global_load_dwordx4 v[94:97], v0, s[4:5] offset:2048 nt
	global_load_dwordx4 v[98:101], v0, s[4:5] offset:3072 nt
	s_add_u32 s4, s4, 0x1000
	s_addc_u32 s5, s5, 0
	global_load_dwordx4 v[102:105], v0, s[4:5] offset:0 nt
	global_load_dwordx4 v[106:109], v0, s[4:5] offset:1024 nt
	global_load_dwordx4 v[110:113], v0, s[4:5] offset:2048 nt
	global_load_dwordx4 v[114:117], v0, s[4:5] offset:3072 nt
	s_add_u32 s4, s4, 0x1000
	s_addc_u32 s5, s5, 0
	s_waitcnt vmcnt(8)
	v_pk_add_f32 v[38:39], v[38:39], 1.0 op_sel_hi:[1,0]
	v_pk_add_f32 v[40:41], v[40:41], 1.0 op_sel_hi:[1,0]
	v_pk_add_f32 v[42:43], v[42:43], 1.0 op_sel_hi:[1,0]
	v_pk_add_f32 v[44:45], v[44:45], 1.0 op_sel_hi:[1,0]
	v_pk_add_f32 v[46:47], v[46:47], 1.0 op_sel_hi:[1,0]
	v_pk_add_f32 v[48:49], v[48:49], 1.0 op_sel_hi:[1,0]
	v_pk_add_f32 v[50:51], v[50:51], 1.0 op_sel_hi:[1,0]
	v_pk_add_f32 v[52:53], v[52:53], 1.0 op_sel_hi:[1,0]
	v_pk_mul_f32 v[12:13], v[70:71], v[70:71]
	v_pk_fma_f32 v[12:13], v[72:73], v[72:73], v[12:13]
	v_pk_fma_f32 v[12:13], v[74:75], v[74:75], v[12:13]
	v_pk_fma_f32 v[12:13], v[76:77], v[76:77], v[12:13]
	v_pk_fma_f32 v[12:13], v[78:79], v[78:79], v[12:13]
	v_pk_fma_f32 v[12:13], v[80:81], v[80:81], v[12:13]
	v_pk_fma_f32 v[12:13], v[82:83], v[82:83], v[12:13]
	v_pk_fma_f32 v[12:13], v[84:85], v[84:85], v[12:13]
	v_add_f32_e32 v5, v12, v13
	s_nop 1
	v_add_f32_dpp v5, v5, v5 quad_perm:[1,0,3,2] row_mask:0xf bank_mask:0xf
	s_nop 1
	v_add_f32_dpp v5, v5, v5 quad_perm:[2,3,0,1] row_mask:0xf bank_mask:0xf
	s_nop 1
	v_add_f32_dpp v5, v5, v5 row_half_mirror row_mask:0xf bank_mask:0xf
	s_nop 1
	v_add_f32_dpp v5, v5, v5 row_mirror row_mask:0xf bank_mask:0xf
	s_nop 1
	v_add_f32_dpp v5, v5, v5 row_bcast:15 row_mask:0xa bank_mask:0xf
	s_nop 1
	v_add_f32_dpp v5, v5, v5 row_bcast:31 row_mask:0xc bank_mask:0xf
	s_nop 1
	v_readlane_b32 s32, v5, 63
	s_nop 1
	v_mov_b32_e32 v6, s32
	v_fmamk_f32 v6, v6, 0x3a800000, v146
	v_rsq_f32_e32 v6, v6
	s_nop 0
	v_mov_b32_e32 v10, v6
	v_pk_mul_f32 v[14:15], v[70:71], v[10:11] op_sel_hi:[1,0]
	v_pk_mul_f32 v[14:15], v[54:55], v[14:15]
	v_pk_fma_f32 v[16:17], v[38:39], v[14:15], v[22:23]
	v_pk_mul_f32 v[14:15], v[72:73], v[10:11] op_sel_hi:[1,0]
	v_pk_mul_f32 v[14:15], v[56:57], v[14:15]
	v_pk_fma_f32 v[18:19], v[40:41], v[14:15], v[24:25]
	v_cvt_pk_bf16_f32 v118, v16, v17
	v_cvt_pk_bf16_f32 v119, v18, v19
	v_pk_mul_f32 v[14:15], v[74:75], v[10:11] op_sel_hi:[1,0]
	v_pk_mul_f32 v[14:15], v[58:59], v[14:15]
	v_pk_fma_f32 v[16:17], v[42:43], v[14:15], v[26:27]
	v_pk_mul_f32 v[14:15], v[76:77], v[10:11] op_sel_hi:[1,0]
	v_pk_mul_f32 v[14:15], v[60:61], v[14:15]
	v_pk_fma_f32 v[18:19], v[44:45], v[14:15], v[28:29]
	v_cvt_pk_bf16_f32 v120, v16, v17
	v_cvt_pk_bf16_f32 v121, v18, v19
	v_pk_mul_f32 v[14:15], v[78:79], v[10:11] op_sel_hi:[1,0]
	v_pk_mul_f32 v[14:15], v[62:63], v[14:15]
	v_pk_fma_f32 v[16:17], v[46:47], v[14:15], v[30:31]
	v_pk_mul_f32 v[14:15], v[80:81], v[10:11] op_sel_hi:[1,0]
	v_pk_mul_f32 v[14:15], v[64:65], v[14:15]
	v_pk_fma_f32 v[18:19], v[48:49], v[14:15], v[32:33]
	v_cvt_pk_bf16_f32 v122, v16, v17
	v_cvt_pk_bf16_f32 v123, v18, v19
	v_pk_mul_f32 v[14:15], v[82:83], v[10:11] op_sel_hi:[1,0]
	v_pk_mul_f32 v[14:15], v[66:67], v[14:15]
	v_pk_fma_f32 v[16:17], v[50:51], v[14:15], v[34:35]
	v_pk_mul_f32 v[14:15], v[84:85], v[10:11] op_sel_hi:[1,0]
	v_pk_mul_f32 v[14:15], v[68:69], v[14:15]
	v_pk_fma_f32 v[18:19], v[52:53], v[14:15], v[36:37]
	v_cvt_pk_bf16_f32 v124, v16, v17
	v_cvt_pk_bf16_f32 v125, v18, v19
	global_store_dwordx4 v0, v[70:73], s[46:47] offset:0 sc1
	global_store_dwordx4 v0, v[74:77], s[46:47] offset:1024 sc1
	global_store_dwordx4 v0, v[78:81], s[46:47] offset:2048 sc1
	global_store_dwordx4 v0, v[82:85], s[46:47] offset:3072 sc1
	global_store_dwordx2 v1, v[118:119], s[62:63] offset:0 sc1
	global_store_dwordx2 v1, v[120:121], s[62:63] offset:512 sc1
	global_store_dwordx2 v1, v[122:123], s[62:63] offset:1024 sc1
	global_store_dwordx2 v1, v[124:125], s[62:63] offset:1536 sc1
	s_add_u32 s46, s46, 0x1000
	s_addc_u32 s47, s47, 0
	s_add_u32 s62, s62, 0x800
	s_addc_u32 s63, s63, 0
	s_nop 1
	global_load_dwordx4 v[70:73], v0, s[4:5] offset:0 nt
	global_load_dwordx4 v[74:77], v0, s[4:5] offset:1024 nt
	global_load_dwordx4 v[78:81], v0, s[4:5] offset:2048 nt
	global_load_dwordx4 v[82:85], v0, s[4:5] offset:3072 nt
	s_add_u32 s4, s4, 0x1000
	s_addc_u32 s5, s5, 0
	s_waitcnt vmcnt(16)
	v_pk_mul_f32 v[12:13], v[86:87], v[86:87]
	v_pk_fma_f32 v[12:13], v[88:89], v[88:89], v[12:13]
	v_pk_fma_f32 v[12:13], v[90:91], v[90:91], v[12:13]
	v_pk_fma_f32 v[12:13], v[92:93], v[92:93], v[12:13]
	v_pk_fma_f32 v[12:13], v[94:95], v[94:95], v[12:13]
	v_pk_fma_f32 v[12:13], v[96:97], v[96:97], v[12:13]
	v_pk_fma_f32 v[12:13], v[98:99], v[98:99], v[12:13]
	v_pk_fma_f32 v[12:13], v[100:101], v[100:101], v[12:13]
	v_add_f32_e32 v5, v12, v13
	s_nop 1
	v_add_f32_dpp v5, v5, v5 quad_perm:[1,0,3,2] row_mask:0xf bank_mask:0xf
	s_nop 1
	v_add_f32_dpp v5, v5, v5 quad_perm:[2,3,0,1] row_mask:0xf bank_mask:0xf
	s_nop 1
	v_add_f32_dpp v5, v5, v5 row_half_mirror row_mask:0xf bank_mask:0xf
	s_nop 1
	v_add_f32_dpp v5, v5, v5 row_mirror row_mask:0xf bank_mask:0xf
	s_nop 1
	v_add_f32_dpp v5, v5, v5 row_bcast:15 row_mask:0xa bank_mask:0xf
	s_nop 1
	v_add_f32_dpp v5, v5, v5 row_bcast:31 row_mask:0xc bank_mask:0xf
	s_nop 1
	v_readlane_b32 s32, v5, 63
	s_nop 1
	v_mov_b32_e32 v6, s32
	v_fmamk_f32 v6, v6, 0x3a800000, v146
	v_rsq_f32_e32 v6, v6
	s_nop 0
	v_mov_b32_e32 v10, v6
	v_pk_mul_f32 v[14:15], v[86:87], v[10:11] op_sel_hi:[1,0]
	v_pk_mul_f32 v[14:15], v[54:55], v[14:15]
	v_pk_fma_f32 v[16:17], v[38:39], v[14:15], v[22:23]
	v_pk_mul_f32 v[14:15], v[88:89], v[10:11] op_sel_hi:[1,0]
	v_pk_mul_f32 v[14:15], v[56:57], v[14:15]
	v_pk_fma_f32 v[18:19], v[40:41], v[14:15], v[24:25]
	v_cvt_pk_bf16_f32 v118, v16, v17
	v_cvt_pk_bf16_f32 v119, v18, v19
	v_pk_mul_f32 v[14:15], v[90:91], v[10:11] op_sel_hi:[1,0]
	v_pk_mul_f32 v[14:15], v[58:59], v[14:15]
	v_pk_fma_f32 v[16:17], v[42:43], v[14:15], v[26:27]
	v_pk_mul_f32 v[14:15], v[92:93], v[10:11] op_sel_hi:[1,0]
	v_pk_mul_f32 v[14:15], v[60:61], v[14:15]
	v_pk_fma_f32 v[18:19], v[44:45], v[14:15], v[28:29]
	v_cvt_pk_bf16_f32 v120, v16, v17
	v_cvt_pk_bf16_f32 v121, v18, v19
	v_pk_mul_f32 v[14:15], v[94:95], v[10:11] op_sel_hi:[1,0]
	v_pk_mul_f32 v[14:15], v[62:63], v[14:15]
	v_pk_fma_f32 v[16:17], v[46:47], v[14:15], v[30:31]
	v_pk_mul_f32 v[14:15], v[96:97], v[10:11] op_sel_hi:[1,0]
	v_pk_mul_f32 v[14:15], v[64:65], v[14:15]
	v_pk_fma_f32 v[18:19], v[48:49], v[14:15], v[32:33]
	v_cvt_pk_bf16_f32 v122, v16, v17
	v_cvt_pk_bf16_f32 v123, v18, v19
	v_pk_mul_f32 v[14:15], v[98:99], v[10:11] op_sel_hi:[1,0]
	v_pk_mul_f32 v[14:15], v[66:67], v[14:15]
	v_pk_fma_f32 v[16:17], v[50:51], v[14:15], v[34:35]
	v_pk_mul_f32 v[14:15], v[100:101], v[10:11] op_sel_hi:[1,0]
	v_pk_mul_f32 v[14:15], v[68:69], v[14:15]
	v_pk_fma_f32 v[18:19], v[52:53], v[14:15], v[36:37]
	v_cvt_pk_bf16_f32 v124, v16, v17
	v_cvt_pk_bf16_f32 v125, v18, v19
	global_store_dwordx4 v0, v[86:89], s[46:47] offset:0 sc1
	global_store_dwordx4 v0, v[90:93], s[46:47] offset:1024 sc1
	global_store_dwordx4 v0, v[94:97], s[46:47] offset:2048 sc1
	global_store_dwordx4 v0, v[98:101], s[46:47] offset:3072 sc1
	global_store_dwordx2 v1, v[118:119], s[62:63] offset:0 sc1
	global_store_dwordx2 v1, v[120:121], s[62:63] offset:512 sc1
	global_store_dwordx2 v1, v[122:123], s[62:63] offset:1024 sc1
	global_store_dwordx2 v1, v[124:125], s[62:63] offset:1536 sc1
	s_add_u32 s46, s46, 0x1000
	s_addc_u32 s47, s47, 0
	s_add_u32 s62, s62, 0x800
	s_addc_u32 s63, s63, 0
	s_waitcnt vmcnt(20)
	v_pk_mul_f32 v[12:13], v[102:103], v[102:103]
	v_pk_fma_f32 v[12:13], v[104:105], v[104:105], v[12:13]
	v_pk_fma_f32 v[12:13], v[106:107], v[106:107], v[12:13]
	v_pk_fma_f32 v[12:13], v[108:109], v[108:109], v[12:13]
	v_pk_fma_f32 v[12:13], v[110:111], v[110:111], v[12:13]
	v_pk_fma_f32 v[12:13], v[112:113], v[112:113], v[12:13]
	v_pk_fma_f32 v[12:13], v[114:115], v[114:115], v[12:13]
	v_pk_fma_f32 v[12:13], v[116:117], v[116:117], v[12:13]
	v_add_f32_e32 v5, v12, v13
	s_nop 1
	v_add_f32_dpp v5, v5, v5 quad_perm:[1,0,3,2] row_mask:0xf bank_mask:0xf
	s_nop 1
	v_add_f32_dpp v5, v5, v5 quad_perm:[2,3,0,1] row_mask:0xf bank_mask:0xf
	s_nop 1
	v_add_f32_dpp v5, v5, v5 row_half_mirror row_mask:0xf bank_mask:0xf
	s_nop 1
	v_add_f32_dpp v5, v5, v5 row_mirror row_mask:0xf bank_mask:0xf
	s_nop 1
	v_add_f32_dpp v5, v5, v5 row_bcast:15 row_mask:0xa bank_mask:0xf
	s_nop 1
	v_add_f32_dpp v5, v5, v5 row_bcast:31 row_mask:0xc bank_mask:0xf
	s_nop 1
	v_readlane_b32 s32, v5, 63
	s_nop 1
	v_mov_b32_e32 v6, s32
	v_fmamk_f32 v6, v6, 0x3a800000, v146
	v_rsq_f32_e32 v6, v6
	s_nop 0
	v_mov_b32_e32 v10, v6
	v_pk_mul_f32 v[14:15], v[102:103], v[10:11] op_sel_hi:[1,0]
	v_pk_mul_f32 v[14:15], v[54:55], v[14:15]
	v_pk_fma_f32 v[16:17], v[38:39], v[14:15], v[22:23]
	v_pk_mul_f32 v[14:15], v[104:105], v[10:11] op_sel_hi:[1,0]
	v_pk_mul_f32 v[14:15], v[56:57], v[14:15]
	v_pk_fma_f32 v[18:19], v[40:41], v[14:15], v[24:25]
	v_cvt_pk_bf16_f32 v118, v16, v17
	v_cvt_pk_bf16_f32 v119, v18, v19
	v_pk_mul_f32 v[14:15], v[106:107], v[10:11] op_sel_hi:[1,0]
	v_pk_mul_f32 v[14:15], v[58:59], v[14:15]
	v_pk_fma_f32 v[16:17], v[42:43], v[14:15], v[26:27]
	v_pk_mul_f32 v[14:15], v[108:109], v[10:11] op_sel_hi:[1,0]
	v_pk_mul_f32 v[14:15], v[60:61], v[14:15]
	v_pk_fma_f32 v[18:19], v[44:45], v[14:15], v[28:29]
	v_cvt_pk_bf16_f32 v120, v16, v17
	v_cvt_pk_bf16_f32 v121, v18, v19
	v_pk_mul_f32 v[14:15], v[110:111], v[10:11] op_sel_hi:[1,0]
	v_pk_mul_f32 v[14:15], v[62:63], v[14:15]
	v_pk_fma_f32 v[16:17], v[46:47], v[14:15], v[30:31]
	v_pk_mul_f32 v[14:15], v[112:113], v[10:11] op_sel_hi:[1,0]
	v_pk_mul_f32 v[14:15], v[64:65], v[14:15]
	v_pk_fma_f32 v[18:19], v[48:49], v[14:15], v[32:33]
	v_cvt_pk_bf16_f32 v122, v16, v17
	v_cvt_pk_bf16_f32 v123, v18, v19
	v_pk_mul_f32 v[14:15], v[114:115], v[10:11] op_sel_hi:[1,0]
	v_pk_mul_f32 v[14:15], v[66:67], v[14:15]
	v_pk_fma_f32 v[16:17], v[50:51], v[14:15], v[34:35]
	v_pk_mul_f32 v[14:15], v[116:117], v[10:11] op_sel_hi:[1,0]
	v_pk_mul_f32 v[14:15], v[68:69], v[14:15]
	v_pk_fma_f32 v[18:19], v[52:53], v[14:15], v[36:37]
	v_cvt_pk_bf16_f32 v124, v16, v17
	v_cvt_pk_bf16_f32 v125, v18, v19
	global_store_dwordx4 v0, v[102:105], s[46:47] offset:0 sc1
	global_store_dwordx4 v0, v[106:109], s[46:47] offset:1024 sc1
	global_store_dwordx4 v0, v[110:113], s[46:47] offset:2048 sc1
	global_store_dwordx4 v0, v[114:117], s[46:47] offset:3072 sc1
	global_store_dwordx2 v1, v[118:119], s[62:63] offset:0 sc1
	global_store_dwordx2 v1, v[120:121], s[62:63] offset:512 sc1
	global_store_dwordx2 v1, v[122:123], s[62:63] offset:1024 sc1
	global_store_dwordx2 v1, v[124:125], s[62:63] offset:1536 sc1
	s_add_u32 s46, s46, 0x1000
	s_addc_u32 s47, s47, 0
	s_add_u32 s62, s62, 0x800
	s_addc_u32 s63, s63, 0
	s_waitcnt vmcnt(16)
	v_pk_mul_f32 v[12:13], v[70:71], v[70:71]
	v_pk_fma_f32 v[12:13], v[72:73], v[72:73], v[12:13]
	v_pk_fma_f32 v[12:13], v[74:75], v[74:75], v[12:13]
	v_pk_fma_f32 v[12:13], v[76:77], v[76:77], v[12:13]
	v_pk_fma_f32 v[12:13], v[78:79], v[78:79], v[12:13]
	v_pk_fma_f32 v[12:13], v[80:81], v[80:81], v[12:13]
	v_pk_fma_f32 v[12:13], v[82:83], v[82:83], v[12:13]
	v_pk_fma_f32 v[12:13], v[84:85], v[84:85], v[12:13]
	v_add_f32_e32 v5, v12, v13
	s_nop 1
	v_add_f32_dpp v5, v5, v5 quad_perm:[1,0,3,2] row_mask:0xf bank_mask:0xf
	s_nop 1
	v_add_f32_dpp v5, v5, v5 quad_perm:[2,3,0,1] row_mask:0xf bank_mask:0xf
	s_nop 1
	v_add_f32_dpp v5, v5, v5 row_half_mirror row_mask:0xf bank_mask:0xf
	s_nop 1
	v_add_f32_dpp v5, v5, v5 row_mirror row_mask:0xf bank_mask:0xf
	s_nop 1
	v_add_f32_dpp v5, v5, v5 row_bcast:15 row_mask:0xa bank_mask:0xf
	s_nop 1
	v_add_f32_dpp v5, v5, v5 row_bcast:31 row_mask:0xc bank_mask:0xf
	s_nop 1
	v_readlane_b32 s32, v5, 63
	s_nop 1
	v_mov_b32_e32 v6, s32
	v_fmamk_f32 v6, v6, 0x3a800000, v146
	v_rsq_f32_e32 v6, v6
	s_nop 0
	v_mov_b32_e32 v10, v6
	v_pk_mul_f32 v[14:15], v[70:71], v[10:11] op_sel_hi:[1,0]
	v_pk_mul_f32 v[14:15], v[54:55], v[14:15]
	v_pk_fma_f32 v[16:17], v[38:39], v[14:15], v[22:23]
	v_pk_mul_f32 v[14:15], v[72:73], v[10:11] op_sel_hi:[1,0]
	v_pk_mul_f32 v[14:15], v[56:57], v[14:15]
	v_pk_fma_f32 v[18:19], v[40:41], v[14:15], v[24:25]
	v_cvt_pk_bf16_f32 v118, v16, v17
	v_cvt_pk_bf16_f32 v119, v18, v19
	v_pk_mul_f32 v[14:15], v[74:75], v[10:11] op_sel_hi:[1,0]
	v_pk_mul_f32 v[14:15], v[58:59], v[14:15]
	v_pk_fma_f32 v[16:17], v[42:43], v[14:15], v[26:27]
	v_pk_mul_f32 v[14:15], v[76:77], v[10:11] op_sel_hi:[1,0]
	v_pk_mul_f32 v[14:15], v[60:61], v[14:15]
	v_pk_fma_f32 v[18:19], v[44:45], v[14:15], v[28:29]
	v_cvt_pk_bf16_f32 v120, v16, v17
	v_cvt_pk_bf16_f32 v121, v18, v19
	v_pk_mul_f32 v[14:15], v[78:79], v[10:11] op_sel_hi:[1,0]
	v_pk_mul_f32 v[14:15], v[62:63], v[14:15]
	v_pk_fma_f32 v[16:17], v[46:47], v[14:15], v[30:31]
	v_pk_mul_f32 v[14:15], v[80:81], v[10:11] op_sel_hi:[1,0]
	v_pk_mul_f32 v[14:15], v[64:65], v[14:15]
	v_pk_fma_f32 v[18:19], v[48:49], v[14:15], v[32:33]
	v_cvt_pk_bf16_f32 v122, v16, v17
	v_cvt_pk_bf16_f32 v123, v18, v19
	v_pk_mul_f32 v[14:15], v[82:83], v[10:11] op_sel_hi:[1,0]
	v_pk_mul_f32 v[14:15], v[66:67], v[14:15]
	v_pk_fma_f32 v[16:17], v[50:51], v[14:15], v[34:35]
	v_pk_mul_f32 v[14:15], v[84:85], v[10:11] op_sel_hi:[1,0]
	v_pk_mul_f32 v[14:15], v[68:69], v[14:15]
	v_pk_fma_f32 v[18:19], v[52:53], v[14:15], v[36:37]
	v_cvt_pk_bf16_f32 v124, v16, v17
	v_cvt_pk_bf16_f32 v125, v18, v19
	global_store_dwordx4 v0, v[70:73], s[46:47] offset:0 sc1
	global_store_dwordx4 v0, v[74:77], s[46:47] offset:1024 sc1
	global_store_dwordx4 v0, v[78:81], s[46:47] offset:2048 sc1
	global_store_dwordx4 v0, v[82:85], s[46:47] offset:3072 sc1
	global_store_dwordx2 v1, v[118:119], s[62:63] offset:0 sc1
	global_store_dwordx2 v1, v[120:121], s[62:63] offset:512 sc1
	global_store_dwordx2 v1, v[122:123], s[62:63] offset:1024 sc1
	global_store_dwordx2 v1, v[124:125], s[62:63] offset:1536 sc1
	s_add_u32 s46, s46, 0x1000
	s_addc_u32 s47, s47, 0
	s_add_u32 s62, s62, 0x800
	s_addc_u32 s63, s63, 0

.Lxb_noinv_2:
	v_cmp_eq_u32_e32 vcc, 0, v0
	s_and_saveexec_b64 s[0:1], vcc
	s_xor_b64 s[0:1], exec, s[0:1]
	s_cbranch_execz .LBB0_438
	s_load_dwordx2 s[12:13], s[8:9], 0x98
	v_readlane_b32 s14, v255, 0
	v_readlane_b32 s15, v255, 45
	s_nop 0
	s_lshr_b32 s24, s14, 3
	s_and_b32 s24, s24, 7
	s_and_b32 s27, s14, 6
	s_lshl_b32 s27, s27, 2
	s_or_b32 s27, s27, s24
	s_and_b32 s30, s14, 3
	s_lshl_b32 s30, s30, 3
	s_or_b32 s30, s30, s24
	s_lshl_b32 s27, s27, 1
	s_and_b32 s24, s14, 1
	s_or_b32 s27, s27, s24
	s_lshl_b32 s27, s27, 7
	s_add_u32 s27, s27, 0x8000
	s_lshl_b32 s30, s30, 1
	s_bfe_u32 s24, s14, 0x10002
	s_or_b32 s30, s30, s24
	s_lshl_b32 s30, s30, 7
	s_add_u32 s30, s30, 0x8000
	s_add_u32 s15, s15, 4
	v_writelane_b32 v255, s15, 45
	v_mov_b32_e32 v0, s27
	s_waitcnt lgkmcnt(0)
	global_atomic_add v0, v189, s[12:13]
	v_mov_b32_e32 v7, s30
	s_mov_b32 s32, 0
.Lgs_poll_b2:
	global_load_dword v6, v7, s[12:13] sc1
	s_waitcnt vmcnt(0)
	v_readfirstlane_b32 s34, v6
	s_nop 0
	s_cmp_ge_u32 s34, s15
	s_cbranch_scc1 .Lgs_done_b2
	s_sleep 1
	s_add_u32 s32, s32, 1
	s_cmp_lt_u32 s32, 0x2000
	s_cbranch_scc1 .Lgs_poll_b2
.Lgs_done_b2:
.LBB0_438:
	s_or_b64 exec, exec, s[0:1]
	v_readlane_b32 s0, v255, 19
	v_readlane_b32 s1, v255, 20
	s_xor_b64 s[10:11], s[0:1], -1
	s_waitcnt lgkmcnt(0)
	s_barrier
	s_mov_b64 s[0:1], s[8:9]
	v_readlane_b32 s26, v255, 0
	v_mov_b32_e32 v8, v147
	s_cmpk_lt_i32 s26, 0x100
	v_readfirstlane_b32 s12, v8
	s_cbranch_scc0 .LBB0_466
	s_ashr_i32 s27, s26, 31
	s_lshr_b32 s4, s27, 29
	s_add_i32 s13, s26, s4
	s_and_b32 s4, s13, -8
	s_sub_i32 s9, s26, s4
	s_cmp_gt_i32 s9, -1
	s_mov_b64 s[6:7], -1
	s_cbranch_scc0 .LBB0_441
	s_lshl_b32 s8, s9, 5
	s_mov_b64 s[6:7], 0

.Lxb_noinv_3:
	v_cmp_eq_u32_e32 vcc, 0, v0
	s_and_saveexec_b64 s[4:5], vcc
	s_xor_b64 s[4:5], exec, s[4:5]
	s_cbranch_execz .LBB0_519
	s_load_dwordx2 s[12:13], s[0:1], 0x98
	v_readlane_b32 s14, v255, 0
	v_readlane_b32 s15, v255, 46
	s_nop 0
	s_lshr_b32 s24, s14, 3
	s_and_b32 s24, s24, 7
	s_and_b32 s27, s14, 6
	s_lshl_b32 s27, s27, 2
	s_or_b32 s27, s27, s24
	s_and_b32 s30, s14, 3
	s_lshl_b32 s30, s30, 3
	s_or_b32 s30, s30, s24
	s_lshl_b32 s27, s27, 7
	s_add_u32 s27, s27, 0xa000
	s_lshl_b32 s30, s30, 7
	s_add_u32 s30, s30, 0xa000
	s_add_u32 s15, s15, 8
	v_writelane_b32 v255, s15, 46
	v_mov_b32_e32 v0, s30
	s_waitcnt lgkmcnt(0)
	global_atomic_add v0, v189, s[12:13]
	v_mov_b32_e32 v7, s27
	s_mov_b32 s32, 0

.Lgs_done_b3:
.LBB0_519:
	s_or_b64 exec, exec, s[4:5]
	s_mov_b64 s[4:5], -1
	v_writelane_b32 v255, s4, 19
	s_and_b64 vcc, exec, s[10:11]
	s_waitcnt lgkmcnt(0)
	v_writelane_b32 v255, s5, 20
	s_mov_b64 s[4:5], -1
	s_barrier
	s_cbranch_vccz .LBB0_335
	s_mov_b64 s[16:17], s[0:1]
	v_mov_b32_e32 v0, v147
	v_readlane_b32 s2, v255, 0
	s_nop 0
	v_ashrrev_i32_e32 v1, 6, v0
	v_lshl_add_u32 v16, s2, 3, v1
	s_movk_i32 s2, 0x2000
	v_cmp_gt_i32_e32 vcc, s2, v16
	s_and_saveexec_b64 s[8:9], vcc
	s_cbranch_execz .LBB0_523
	s_load_dwordx4 s[4:7], s[16:17], 0x90
	s_load_dwordx4 s[12:15], s[16:17], 0x40
	v_lshlrev_b32_e32 v1, 2, v0
	v_cmp_lt_i32_e32 vcc, v188, v183
	v_and_b32_e32 v2, 0xfc, v1
	s_mul_i32 s2, s70, 0x2d000
	v_cndmask_b32_e32 v1, v182, v188, vcc
	v_cmp_lt_i32_e32 vcc, v254, v183
	s_waitcnt lgkmcnt(0)
	s_add_u32 s18, s6, s2
	s_mul_hi_u32 s2, s70, 0x2d000
	v_lshlrev_b32_e32 v28, 2, v1
	v_cndmask_b32_e32 v1, v182, v254, vcc
	s_addc_u32 s19, s7, s2
	v_readlane_b32 s20, v255, 12
	v_lshlrev_b32_e32 v29, 2, v1
	v_xor_b32_e32 v1, 4, v182
	s_add_u32 s10, s18, 0x103000
	v_readlane_b32 s21, v255, 13
	v_cmp_lt_i32_e32 vcc, v1, v183
	s_addc_u32 s11, s19, 0
	s_lshl_b64 s[20:21], s[20:21], 2
	v_cndmask_b32_e32 v1, v182, v1, vcc
	s_add_u32 s12, s12, s20
	v_lshlrev_b32_e32 v144, 2, v2
	v_lshlrev_b32_e32 v30, 2, v1
	v_xor_b32_e32 v1, 8, v182
	s_addc_u32 s13, s13, s21
	v_lshl_add_u64 v[4:5], s[18:19], 0, v[144:145]
	s_mov_b64 s[18:19], 0x102000
	v_cmp_lt_i32_e32 vcc, v1, v183
	v_lshl_add_u64 v[18:19], v[4:5], 0, s[18:19]
	v_lshl_add_u64 v[4:5], s[12:13], 0, v[144:145]
	v_cndmask_b32_e32 v1, v182, v1, vcc
	v_cmp_lt_i32_e32 vcc, v187, v183
	v_ashrrev_i32_e32 v17, 31, v16
	v_lshl_add_u64 v[22:23], v[4:5], 0, s[94:95]
	v_lshlrev_b32_e32 v31, 2, v1
	v_cndmask_b32_e32 v1, v182, v187, vcc
	v_cmp_lt_i32_e32 vcc, v184, v183
	v_lshlrev_b64 v[4:5], 11, v[16:17]
	v_and_b32_e32 v3, 63, v0
	v_lshlrev_b32_e32 v32, 2, v1
	v_cndmask_b32_e32 v1, v182, v184, vcc
	v_lshl_or_b32 v4, v3, 3, v4
	v_lshlrev_b32_e32 v33, 2, v1
	v_lshl_add_u64 v[0:1], s[6:7], 0, v[4:5]
	s_mov_b64 s[6:7], 0x9800600
	s_add_u32 s14, s14, s20
	v_lshl_add_u64 v[24:25], v[0:1], 0, s[6:7]
	v_lshlrev_b64 v[0:1], 12, v[16:17]
	s_addc_u32 s15, s15, s21
	v_lshl_or_b32 v0, v3, 4, v0
	v_lshl_add_u64 v[20:21], s[14:15], 0, v[144:145]
	v_lshl_add_u64 v[26:27], s[4:5], 0, v[0:1]
	s_mov_b64 s[4:5], 0
	v_lshlrev_b32_e32 v144, 2, v2
	v_readlane_b32 s2, v255, 0
	v_readfirstlane_b32 s7, v147
	s_load_dwordx2 s[4:5], s[16:17], 0x90
	s_load_dwordx2 s[12:13], s[16:17], 0x98
	s_load_dwordx2 s[14:15], s[16:17], 0x40
	s_load_dwordx2 s[40:41], s[16:17], 0x48
	v_and_b32_e32 v0, 63, v147
	v_lshlrev_b32_e32 v1, 3, v0
	v_lshlrev_b32_e32 v0, 4, v0
	s_lshr_b32 s7, s7, 6
	s_and_b32 s27, s2, 6
	s_lshl_b32 s27, s27, 5
	s_and_b32 s37, s2, 0x39
	s_or_b32 s27, s27, s37
	s_lshr_b32 s37, s2, 6
	s_lshl_b32 s37, s37, 1
	s_or_b32 s2, s27, s37
	s_lshl_b32 s2, s2, 3
	s_add_u32 s2, s2, s7
	s_lshl_b32 s24, s2, 2
	s_sub_u32 s27, s24, 0x1000
	s_lshr_b32 s27, s27, 10
	s_add_u32 s27, s27, 1
	s_cmp_lt_u32 s24, 0x1000
	s_cselect_b32 s30, 0, s27
	v_add_u32_e32 v2, 0x2000, v0
	v_add_u32_e32 v3, 0x3000, v0
	v_add_u32_e32 v4, 0x4000, v0
	s_waitcnt lgkmcnt(0)
	s_lshl_b32 s27, s24, 11
	s_add_u32 s62, s12, s27
	s_addc_u32 s63, s13, 0
	s_add_u32 s58, s62, 0x8800000
	s_addc_u32 s59, s63, 0
	s_add_u32 s60, s58, 0x1000000
	s_addc_u32 s61, s59, 0
	s_add_u32 s62, s62, 0x1000000
	s_addc_u32 s63, s63, 0
	s_lshl_b32 s27, s24, 12
	s_add_u32 s46, s4, s27
	s_addc_u32 s47, s5, 0
	s_mov_b64 s[4:5], s[46:47]
	s_mul_i32 s27, s70, 5
	s_add_u32 s27, s27, s30
	s_mul_i32 s27, s27, 0x9000
	s_add_u32 s27, s27, 0x100000
	s_add_u32 s88, s12, s27
	s_addc_u32 s89, s13, 0
	s_mov_b64 s[100:101], s[88:89]
	s_mul_i32 s27, s70, 0x3000
	s_add_u32 s40, s40, s27
	s_addc_u32 s41, s41, 0
	s_mul_i32 s27, s70, 0x3000
	s_add_u32 s27, s27, 0x1000
	s_add_u32 s14, s14, s27
	s_addc_u32 s15, s15, 0
	global_load_dwordx4 v[22:25], v2, s[100:101] offset:0
	global_load_dwordx4 v[38:41], v0, s[40:41] offset:0
	global_load_dwordx4 v[54:57], v3, s[88:89] offset:0
	global_load_dwordx4 v[70:73], v4, s[88:89] offset:0
	global_load_dwordx4 v[86:89], v0, s[14:15] offset:0
	global_load_dwordx4 v[26:29], v2, s[100:101] offset:1024
	global_load_dwordx4 v[42:45], v0, s[40:41] offset:1024
	global_load_dwordx4 v[58:61], v3, s[88:89] offset:1024
	global_load_dwordx4 v[74:77], v4, s[88:89] offset:1024
	global_load_dwordx4 v[90:93], v0, s[14:15] offset:1024
	global_load_dwordx4 v[30:33], v2, s[100:101] offset:2048
	global_load_dwordx4 v[46:49], v0, s[40:41] offset:2048
	global_load_dwordx4 v[62:65], v3, s[88:89] offset:2048
	global_load_dwordx4 v[78:81], v4, s[88:89] offset:2048
	global_load_dwordx4 v[94:97], v0, s[14:15] offset:2048
	global_load_dwordx4 v[34:37], v2, s[100:101] offset:3072
	global_load_dwordx4 v[50:53], v0, s[40:41] offset:3072
	global_load_dwordx4 v[66:69], v3, s[88:89] offset:3072
	global_load_dwordx4 v[82:85], v4, s[88:89] offset:3072
	global_load_dwordx4 v[98:101], v0, s[14:15] offset:3072
	global_load_dwordx4 v[102:105], v0, s[4:5] offset:0
	global_load_dwordx4 v[106:109], v0, s[4:5] offset:1024
	global_load_dwordx4 v[110:113], v0, s[4:5] offset:2048
	global_load_dwordx4 v[114:117], v0, s[4:5] offset:3072
	global_load_dwordx2 v[118:119], v1, s[58:59] offset:0
	global_load_dwordx2 v[122:123], v1, s[58:59] offset:512
	global_load_dwordx2 v[134:135], v1, s[58:59] offset:1024
	global_load_dwordx2 v[138:139], v1, s[58:59] offset:1536
	global_load_dwordx2 v[120:121], v1, s[60:61] offset:0
	global_load_dwordx2 v[124:125], v1, s[60:61] offset:512
	global_load_dwordx2 v[136:137], v1, s[60:61] offset:1024
	global_load_dwordx2 v[140:141], v1, s[60:61] offset:1536
	s_add_u32 s4, s4, 0x1000
	s_addc_u32 s5, s5, 0
	s_add_u32 s58, s58, 0x800
	s_addc_u32 s59, s59, 0
	s_add_u32 s60, s60, 0x800
	s_addc_u32 s61, s61, 0
	global_load_dwordx4 v[154:157], v0, s[4:5] offset:0
	global_load_dwordx4 v[158:161], v0, s[4:5] offset:1024
	global_load_dwordx4 v[162:165], v0, s[4:5] offset:2048
	global_load_dwordx4 v[168:171], v0, s[4:5] offset:3072
	global_load_dwordx2 v[172:173], v1, s[58:59] offset:0
	global_load_dwordx2 v[176:177], v1, s[58:59] offset:512
	global_load_dwordx2 v[204:205], v1, s[58:59] offset:1024
	global_load_dwordx2 v[214:215], v1, s[58:59] offset:1536
	global_load_dwordx2 v[174:175], v1, s[60:61] offset:0
	global_load_dwordx2 v[178:179], v1, s[60:61] offset:512
	global_load_dwordx2 v[206:207], v1, s[60:61] offset:1024
	global_load_dwordx2 v[216:217], v1, s[60:61] offset:1536
	s_add_u32 s4, s4, 0x1000
	s_addc_u32 s5, s5, 0
	s_add_u32 s58, s58, 0x800
	s_addc_u32 s59, s59, 0
	s_add_u32 s60, s60, 0x800
	s_addc_u32 s61, s61, 0
	global_load_dwordx4 v[218:221], v0, s[4:5] offset:0
	global_load_dwordx4 v[222:225], v0, s[4:5] offset:1024
	global_load_dwordx4 v[226:229], v0, s[4:5] offset:2048
	global_load_dwordx4 v[230:233], v0, s[4:5] offset:3072
	global_load_dwordx2 v[234:235], v1, s[58:59] offset:0
	global_load_dwordx2 v[238:239], v1, s[58:59] offset:512
	global_load_dwordx2 v[242:243], v1, s[58:59] offset:1024
	global_load_dwordx2 v[246:247], v1, s[58:59] offset:1536
	global_load_dwordx2 v[236:237], v1, s[60:61] offset:0
	global_load_dwordx2 v[240:241], v1, s[60:61] offset:512
	global_load_dwordx2 v[244:245], v1, s[60:61] offset:1024
	global_load_dwordx2 v[248:249], v1, s[60:61] offset:1536
	s_add_u32 s4, s4, 0x1000
	s_addc_u32 s5, s5, 0
	s_add_u32 s58, s58, 0x800
	s_addc_u32 s59, s59, 0
	s_add_u32 s60, s60, 0x800
	s_addc_u32 s61, s61, 0
	s_waitcnt vmcnt(24)
	v_pk_add_f32 v[70:71], v[70:71], 1.0 op_sel_hi:[1,0]
	v_pk_add_f32 v[72:73], v[72:73], 1.0 op_sel_hi:[1,0]
	v_pk_add_f32 v[74:75], v[74:75], 1.0 op_sel_hi:[1,0]
	v_pk_add_f32 v[76:77], v[76:77], 1.0 op_sel_hi:[1,0]
	v_pk_add_f32 v[78:79], v[78:79], 1.0 op_sel_hi:[1,0]
	v_pk_add_f32 v[80:81], v[80:81], 1.0 op_sel_hi:[1,0]
	v_pk_add_f32 v[82:83], v[82:83], 1.0 op_sel_hi:[1,0]
	v_pk_add_f32 v[84:85], v[84:85], 1.0 op_sel_hi:[1,0]
	v_lshlrev_b32_e32 v14, 16, v118
	v_and_b32_e32 v15, 0xffff0000, v118
	v_lshlrev_b32_e32 v16, 16, v120
	v_and_b32_e32 v17, 0xffff0000, v120
	v_lshlrev_b32_e32 v18, 16, v119
	v_and_b32_e32 v19, 0xffff0000, v119
	v_lshlrev_b32_e32 v20, 16, v121
	v_and_b32_e32 v21, 0xffff0000, v121
	v_pk_add_f32 v[118:119], v[14:15], v[16:17]
	v_pk_add_f32 v[120:121], v[18:19], v[20:21]
	v_lshlrev_b32_e32 v14, 16, v122
	v_and_b32_e32 v15, 0xffff0000, v122
	v_lshlrev_b32_e32 v16, 16, v124
	v_and_b32_e32 v17, 0xffff0000, v124
	v_lshlrev_b32_e32 v18, 16, v123
	v_and_b32_e32 v19, 0xffff0000, v123
	v_lshlrev_b32_e32 v20, 16, v125
	v_and_b32_e32 v21, 0xffff0000, v125
	v_pk_add_f32 v[122:123], v[14:15], v[16:17]
	v_pk_add_f32 v[124:125], v[18:19], v[20:21]
	v_lshlrev_b32_e32 v14, 16, v134
	v_and_b32_e32 v15, 0xffff0000, v134
	v_lshlrev_b32_e32 v16, 16, v136
	v_and_b32_e32 v17, 0xffff0000, v136
	v_lshlrev_b32_e32 v18, 16, v135
	v_and_b32_e32 v19, 0xffff0000, v135
	v_lshlrev_b32_e32 v20, 16, v137
	v_and_b32_e32 v21, 0xffff0000, v137
	v_pk_add_f32 v[134:135], v[14:15], v[16:17]
	v_pk_add_f32 v[136:137], v[18:19], v[20:21]
	v_lshlrev_b32_e32 v14, 16, v138
	v_and_b32_e32 v15, 0xffff0000, v138
	v_lshlrev_b32_e32 v16, 16, v140
	v_and_b32_e32 v17, 0xffff0000, v140
	v_lshlrev_b32_e32 v18, 16, v139
	v_and_b32_e32 v19, 0xffff0000, v139
	v_lshlrev_b32_e32 v20, 16, v141
	v_and_b32_e32 v21, 0xffff0000, v141
	v_pk_add_f32 v[138:139], v[14:15], v[16:17]
	v_pk_add_f32 v[140:141], v[18:19], v[20:21]
	v_pk_mul_f32 v[12:13], v[118:119], v[118:119]
	v_pk_fma_f32 v[12:13], v[120:121], v[120:121], v[12:13]
	v_pk_fma_f32 v[12:13], v[122:123], v[122:123], v[12:13]
	v_pk_fma_f32 v[12:13], v[124:125], v[124:125], v[12:13]
	v_pk_fma_f32 v[12:13], v[134:135], v[134:135], v[12:13]
	v_pk_fma_f32 v[12:13], v[136:137], v[136:137], v[12:13]
	v_pk_fma_f32 v[12:13], v[138:139], v[138:139], v[12:13]
	v_pk_fma_f32 v[12:13], v[140:141], v[140:141], v[12:13]
	v_add_f32_e32 v5, v12, v13
	s_nop 1
	v_add_f32_dpp v5, v5, v5 quad_perm:[1,0,3,2] row_mask:0xf bank_mask:0xf
	s_nop 1
	v_add_f32_dpp v5, v5, v5 quad_perm:[2,3,0,1] row_mask:0xf bank_mask:0xf
	s_nop 1
	v_add_f32_dpp v5, v5, v5 row_half_mirror row_mask:0xf bank_mask:0xf
	s_nop 1
	v_add_f32_dpp v5, v5, v5 row_mirror row_mask:0xf bank_mask:0xf
	s_nop 1
	v_add_f32_dpp v5, v5, v5 row_bcast:15 row_mask:0xa bank_mask:0xf
	s_nop 1
	v_add_f32_dpp v5, v5, v5 row_bcast:31 row_mask:0xc bank_mask:0xf
	s_nop 1
	v_readlane_b32 s32, v5, 63
	s_nop 1
	v_mov_b32_e32 v6, s32
	v_fmamk_f32 v6, v6, 0x3a800000, v146
	v_rsq_f32_e32 v6, v6
	s_nop 0
	v_mul_f32_e32 v8, 0.5, v6
	v_pk_mul_f32 v[14:15], v[118:119], v[8:9] op_sel_hi:[1,0]
	v_pk_mul_f32 v[14:15], v[38:39], v[14:15]
	v_pk_fma_f32 v[102:103], v[22:23], v[14:15], v[102:103]
	v_pk_mul_f32 v[14:15], v[120:121], v[8:9] op_sel_hi:[1,0]
	v_pk_mul_f32 v[14:15], v[40:41], v[14:15]
	v_pk_fma_f32 v[104:105], v[24:25], v[14:15], v[104:105]
	v_pk_mul_f32 v[14:15], v[122:123], v[8:9] op_sel_hi:[1,0]
	v_pk_mul_f32 v[14:15], v[42:43], v[14:15]
	v_pk_fma_f32 v[106:107], v[26:27], v[14:15], v[106:107]
	v_pk_mul_f32 v[14:15], v[124:125], v[8:9] op_sel_hi:[1,0]
	v_pk_mul_f32 v[14:15], v[44:45], v[14:15]
	v_pk_fma_f32 v[108:109], v[28:29], v[14:15], v[108:109]
	v_pk_mul_f32 v[14:15], v[134:135], v[8:9] op_sel_hi:[1,0]
	v_pk_mul_f32 v[14:15], v[46:47], v[14:15]
	v_pk_fma_f32 v[110:111], v[30:31], v[14:15], v[110:111]
	v_pk_mul_f32 v[14:15], v[136:137], v[8:9] op_sel_hi:[1,0]
	v_pk_mul_f32 v[14:15], v[48:49], v[14:15]
	v_pk_fma_f32 v[112:113], v[32:33], v[14:15], v[112:113]
	v_pk_mul_f32 v[14:15], v[138:139], v[8:9] op_sel_hi:[1,0]
	v_pk_mul_f32 v[14:15], v[50:51], v[14:15]
	v_pk_fma_f32 v[114:115], v[34:35], v[14:15], v[114:115]
	v_pk_mul_f32 v[14:15], v[140:141], v[8:9] op_sel_hi:[1,0]
	v_pk_mul_f32 v[14:15], v[52:53], v[14:15]
	v_pk_fma_f32 v[116:117], v[36:37], v[14:15], v[116:117]
	v_pk_mul_f32 v[12:13], v[102:103], v[102:103]
	v_pk_fma_f32 v[12:13], v[104:105], v[104:105], v[12:13]
	v_pk_fma_f32 v[12:13], v[106:107], v[106:107], v[12:13]
	v_pk_fma_f32 v[12:13], v[108:109], v[108:109], v[12:13]
	v_pk_fma_f32 v[12:13], v[110:111], v[110:111], v[12:13]
	v_pk_fma_f32 v[12:13], v[112:113], v[112:113], v[12:13]
	v_pk_fma_f32 v[12:13], v[114:115], v[114:115], v[12:13]
	v_pk_fma_f32 v[12:13], v[116:117], v[116:117], v[12:13]
	v_add_f32_e32 v5, v12, v13
	s_nop 1
	v_add_f32_dpp v5, v5, v5 quad_perm:[1,0,3,2] row_mask:0xf bank_mask:0xf
	s_nop 1
	v_add_f32_dpp v5, v5, v5 quad_perm:[2,3,0,1] row_mask:0xf bank_mask:0xf
	s_nop 1
	v_add_f32_dpp v5, v5, v5 row_half_mirror row_mask:0xf bank_mask:0xf
	s_nop 1
	v_add_f32_dpp v5, v5, v5 row_mirror row_mask:0xf bank_mask:0xf
	s_nop 1
	v_add_f32_dpp v5, v5, v5 row_bcast:15 row_mask:0xa bank_mask:0xf
	s_nop 1
	v_add_f32_dpp v5, v5, v5 row_bcast:31 row_mask:0xc bank_mask:0xf
	s_nop 1
	v_readlane_b32 s32, v5, 63
	s_nop 1
	v_mov_b32_e32 v6, s32
	v_fmamk_f32 v6, v6, 0x3a800000, v146
	v_rsq_f32_e32 v6, v6
	s_nop 0
	v_mov_b32_e32 v10, v6
	v_pk_mul_f32 v[14:15], v[102:103], v[10:11] op_sel_hi:[1,0]
	v_pk_mul_f32 v[14:15], v[86:87], v[14:15]
	v_pk_fma_f32 v[16:17], v[70:71], v[14:15], v[54:55]
	v_pk_mul_f32 v[14:15], v[104:105], v[10:11] op_sel_hi:[1,0]
	v_pk_mul_f32 v[14:15], v[88:89], v[14:15]
	v_pk_fma_f32 v[18:19], v[72:73], v[14:15], v[56:57]
	v_cvt_pk_bf16_f32 v118, v16, v17
	v_cvt_pk_bf16_f32 v119, v18, v19
	v_pk_mul_f32 v[14:15], v[106:107], v[10:11] op_sel_hi:[1,0]
	v_pk_mul_f32 v[14:15], v[90:91], v[14:15]
	v_pk_fma_f32 v[16:17], v[74:75], v[14:15], v[58:59]
	v_pk_mul_f32 v[14:15], v[108:109], v[10:11] op_sel_hi:[1,0]
	v_pk_mul_f32 v[14:15], v[92:93], v[14:15]
	v_pk_fma_f32 v[18:19], v[76:77], v[14:15], v[60:61]
	v_cvt_pk_bf16_f32 v122, v16, v17
	v_cvt_pk_bf16_f32 v123, v18, v19
	v_pk_mul_f32 v[14:15], v[110:111], v[10:11] op_sel_hi:[1,0]
	v_pk_mul_f32 v[14:15], v[94:95], v[14:15]
	v_pk_fma_f32 v[16:17], v[78:79], v[14:15], v[62:63]
	v_pk_mul_f32 v[14:15], v[112:113], v[10:11] op_sel_hi:[1,0]
	v_pk_mul_f32 v[14:15], v[96:97], v[14:15]
	v_pk_fma_f32 v[18:19], v[80:81], v[14:15], v[64:65]
	v_cvt_pk_bf16_f32 v134, v16, v17
	v_cvt_pk_bf16_f32 v135, v18, v19
	v_pk_mul_f32 v[14:15], v[114:115], v[10:11] op_sel_hi:[1,0]
	v_pk_mul_f32 v[14:15], v[98:99], v[14:15]
	v_pk_fma_f32 v[16:17], v[82:83], v[14:15], v[66:67]
	v_pk_mul_f32 v[14:15], v[116:117], v[10:11] op_sel_hi:[1,0]
	v_pk_mul_f32 v[14:15], v[100:101], v[14:15]
	v_pk_fma_f32 v[18:19], v[84:85], v[14:15], v[68:69]
	v_cvt_pk_bf16_f32 v138, v16, v17
	v_cvt_pk_bf16_f32 v139, v18, v19
	global_store_dwordx4 v0, v[102:105], s[46:47] offset:0 sc1
	global_store_dwordx4 v0, v[106:109], s[46:47] offset:1024 sc1
	global_store_dwordx4 v0, v[110:113], s[46:47] offset:2048 sc1
	global_store_dwordx4 v0, v[114:117], s[46:47] offset:3072 sc1
	global_store_dwordx2 v1, v[118:119], s[62:63] offset:0 sc1
	global_store_dwordx2 v1, v[122:123], s[62:63] offset:512 sc1
	global_store_dwordx2 v1, v[134:135], s[62:63] offset:1024 sc1
	global_store_dwordx2 v1, v[138:139], s[62:63] offset:1536 sc1
	s_add_u32 s46, s46, 0x1000
	s_addc_u32 s47, s47, 0
	s_add_u32 s62, s62, 0x800
	s_addc_u32 s63, s63, 0
	s_nop 1
	global_load_dwordx4 v[102:105], v0, s[4:5] offset:0
	global_load_dwordx4 v[106:109], v0, s[4:5] offset:1024
	global_load_dwordx4 v[110:113], v0, s[4:5] offset:2048
	global_load_dwordx4 v[114:117], v0, s[4:5] offset:3072
	global_load_dwordx2 v[118:119], v1, s[58:59] offset:0
	global_load_dwordx2 v[122:123], v1, s[58:59] offset:512
	global_load_dwordx2 v[134:135], v1, s[58:59] offset:1024
	global_load_dwordx2 v[138:139], v1, s[58:59] offset:1536
	global_load_dwordx2 v[120:121], v1, s[60:61] offset:0
	global_load_dwordx2 v[124:125], v1, s[60:61] offset:512
	global_load_dwordx2 v[136:137], v1, s[60:61] offset:1024
	global_load_dwordx2 v[140:141], v1, s[60:61] offset:1536
	s_add_u32 s4, s4, 0x1000
	s_addc_u32 s5, s5, 0
	s_add_u32 s58, s58, 0x800
	s_addc_u32 s59, s59, 0
	s_add_u32 s60, s60, 0x800
	s_addc_u32 s61, s61, 0
	s_waitcnt vmcnt(32)
	v_lshlrev_b32_e32 v14, 16, v172
	v_and_b32_e32 v15, 0xffff0000, v172
	v_lshlrev_b32_e32 v16, 16, v174
	v_and_b32_e32 v17, 0xffff0000, v174
	v_lshlrev_b32_e32 v18, 16, v173
	v_and_b32_e32 v19, 0xffff0000, v173
	v_lshlrev_b32_e32 v20, 16, v175
	v_and_b32_e32 v21, 0xffff0000, v175
	v_pk_add_f32 v[172:173], v[14:15], v[16:17]
	v_pk_add_f32 v[174:175], v[18:19], v[20:21]
	v_lshlrev_b32_e32 v14, 16, v176
	v_and_b32_e32 v15, 0xffff0000, v176
	v_lshlrev_b32_e32 v16, 16, v178
	v_and_b32_e32 v17, 0xffff0000, v178
	v_lshlrev_b32_e32 v18, 16, v177
	v_and_b32_e32 v19, 0xffff0000, v177
	v_lshlrev_b32_e32 v20, 16, v179
	v_and_b32_e32 v21, 0xffff0000, v179
	v_pk_add_f32 v[176:177], v[14:15], v[16:17]
	v_pk_add_f32 v[178:179], v[18:19], v[20:21]
	v_lshlrev_b32_e32 v14, 16, v204
	v_and_b32_e32 v15, 0xffff0000, v204
	v_lshlrev_b32_e32 v16, 16, v206
	v_and_b32_e32 v17, 0xffff0000, v206
	v_lshlrev_b32_e32 v18, 16, v205
	v_and_b32_e32 v19, 0xffff0000, v205
	v_lshlrev_b32_e32 v20, 16, v207
	v_and_b32_e32 v21, 0xffff0000, v207
	v_pk_add_f32 v[204:205], v[14:15], v[16:17]
	v_pk_add_f32 v[206:207], v[18:19], v[20:21]
	v_lshlrev_b32_e32 v14, 16, v214
	v_and_b32_e32 v15, 0xffff0000, v214
	v_lshlrev_b32_e32 v16, 16, v216
	v_and_b32_e32 v17, 0xffff0000, v216
	v_lshlrev_b32_e32 v18, 16, v215
	v_and_b32_e32 v19, 0xffff0000, v215
	v_lshlrev_b32_e32 v20, 16, v217
	v_and_b32_e32 v21, 0xffff0000, v217
	v_pk_add_f32 v[214:215], v[14:15], v[16:17]
	v_pk_add_f32 v[216:217], v[18:19], v[20:21]
	v_pk_mul_f32 v[12:13], v[172:173], v[172:173]
	v_pk_fma_f32 v[12:13], v[174:175], v[174:175], v[12:13]
	v_pk_fma_f32 v[12:13], v[176:177], v[176:177], v[12:13]
	v_pk_fma_f32 v[12:13], v[178:179], v[178:179], v[12:13]
	v_pk_fma_f32 v[12:13], v[204:205], v[204:205], v[12:13]
	v_pk_fma_f32 v[12:13], v[206:207], v[206:207], v[12:13]
	v_pk_fma_f32 v[12:13], v[214:215], v[214:215], v[12:13]
	v_pk_fma_f32 v[12:13], v[216:217], v[216:217], v[12:13]
	v_add_f32_e32 v5, v12, v13
	s_nop 1
	v_add_f32_dpp v5, v5, v5 quad_perm:[1,0,3,2] row_mask:0xf bank_mask:0xf
	s_nop 1
	v_add_f32_dpp v5, v5, v5 quad_perm:[2,3,0,1] row_mask:0xf bank_mask:0xf
	s_nop 1
	v_add_f32_dpp v5, v5, v5 row_half_mirror row_mask:0xf bank_mask:0xf
	s_nop 1
	v_add_f32_dpp v5, v5, v5 row_mirror row_mask:0xf bank_mask:0xf
	s_nop 1
	v_add_f32_dpp v5, v5, v5 row_bcast:15 row_mask:0xa bank_mask:0xf
	s_nop 1
	v_add_f32_dpp v5, v5, v5 row_bcast:31 row_mask:0xc bank_mask:0xf
	s_nop 1
	v_readlane_b32 s32, v5, 63
	s_nop 1
	v_mov_b32_e32 v6, s32
	v_fmamk_f32 v6, v6, 0x3a800000, v146
	v_rsq_f32_e32 v6, v6
	s_nop 0
	v_mul_f32_e32 v8, 0.5, v6
	v_pk_mul_f32 v[14:15], v[172:173], v[8:9] op_sel_hi:[1,0]
	v_pk_mul_f32 v[14:15], v[38:39], v[14:15]
	v_pk_fma_f32 v[154:155], v[22:23], v[14:15], v[154:155]
	v_pk_mul_f32 v[14:15], v[174:175], v[8:9] op_sel_hi:[1,0]
	v_pk_mul_f32 v[14:15], v[40:41], v[14:15]
	v_pk_fma_f32 v[156:157], v[24:25], v[14:15], v[156:157]
	v_pk_mul_f32 v[14:15], v[176:177], v[8:9] op_sel_hi:[1,0]
	v_pk_mul_f32 v[14:15], v[42:43], v[14:15]
	v_pk_fma_f32 v[158:159], v[26:27], v[14:15], v[158:159]
	v_pk_mul_f32 v[14:15], v[178:179], v[8:9] op_sel_hi:[1,0]
	v_pk_mul_f32 v[14:15], v[44:45], v[14:15]
	v_pk_fma_f32 v[160:161], v[28:29], v[14:15], v[160:161]
	v_pk_mul_f32 v[14:15], v[204:205], v[8:9] op_sel_hi:[1,0]
	v_pk_mul_f32 v[14:15], v[46:47], v[14:15]
	v_pk_fma_f32 v[162:163], v[30:31], v[14:15], v[162:163]
	v_pk_mul_f32 v[14:15], v[206:207], v[8:9] op_sel_hi:[1,0]
	v_pk_mul_f32 v[14:15], v[48:49], v[14:15]
	v_pk_fma_f32 v[164:165], v[32:33], v[14:15], v[164:165]
	v_pk_mul_f32 v[14:15], v[214:215], v[8:9] op_sel_hi:[1,0]
	v_pk_mul_f32 v[14:15], v[50:51], v[14:15]
	v_pk_fma_f32 v[168:169], v[34:35], v[14:15], v[168:169]
	v_pk_mul_f32 v[14:15], v[216:217], v[8:9] op_sel_hi:[1,0]
	v_pk_mul_f32 v[14:15], v[52:53], v[14:15]
	v_pk_fma_f32 v[170:171], v[36:37], v[14:15], v[170:171]
	v_pk_mul_f32 v[12:13], v[154:155], v[154:155]
	v_pk_fma_f32 v[12:13], v[156:157], v[156:157], v[12:13]
	v_pk_fma_f32 v[12:13], v[158:159], v[158:159], v[12:13]
	v_pk_fma_f32 v[12:13], v[160:161], v[160:161], v[12:13]
	v_pk_fma_f32 v[12:13], v[162:163], v[162:163], v[12:13]
	v_pk_fma_f32 v[12:13], v[164:165], v[164:165], v[12:13]
	v_pk_fma_f32 v[12:13], v[168:169], v[168:169], v[12:13]
	v_pk_fma_f32 v[12:13], v[170:171], v[170:171], v[12:13]
	v_add_f32_e32 v5, v12, v13
	s_nop 1
	v_add_f32_dpp v5, v5, v5 quad_perm:[1,0,3,2] row_mask:0xf bank_mask:0xf
	s_nop 1
	v_add_f32_dpp v5, v5, v5 quad_perm:[2,3,0,1] row_mask:0xf bank_mask:0xf
	s_nop 1
	v_add_f32_dpp v5, v5, v5 row_half_mirror row_mask:0xf bank_mask:0xf
	s_nop 1
	v_add_f32_dpp v5, v5, v5 row_mirror row_mask:0xf bank_mask:0xf
	s_nop 1
	v_add_f32_dpp v5, v5, v5 row_bcast:15 row_mask:0xa bank_mask:0xf
	s_nop 1
	v_add_f32_dpp v5, v5, v5 row_bcast:31 row_mask:0xc bank_mask:0xf
	s_nop 1
	v_readlane_b32 s32, v5, 63
	s_nop 1
	v_mov_b32_e32 v6, s32
	v_fmamk_f32 v6, v6, 0x3a800000, v146
	v_rsq_f32_e32 v6, v6
	s_nop 0
	v_mov_b32_e32 v10, v6
	v_pk_mul_f32 v[14:15], v[154:155], v[10:11] op_sel_hi:[1,0]
	v_pk_mul_f32 v[14:15], v[86:87], v[14:15]
	v_pk_fma_f32 v[16:17], v[70:71], v[14:15], v[54:55]
	v_pk_mul_f32 v[14:15], v[156:157], v[10:11] op_sel_hi:[1,0]
	v_pk_mul_f32 v[14:15], v[88:89], v[14:15]
	v_pk_fma_f32 v[18:19], v[72:73], v[14:15], v[56:57]
	v_cvt_pk_bf16_f32 v172, v16, v17
	v_cvt_pk_bf16_f32 v173, v18, v19
	v_pk_mul_f32 v[14:15], v[158:159], v[10:11] op_sel_hi:[1,0]
	v_pk_mul_f32 v[14:15], v[90:91], v[14:15]
	v_pk_fma_f32 v[16:17], v[74:75], v[14:15], v[58:59]
	v_pk_mul_f32 v[14:15], v[160:161], v[10:11] op_sel_hi:[1,0]
	v_pk_mul_f32 v[14:15], v[92:93], v[14:15]
	v_pk_fma_f32 v[18:19], v[76:77], v[14:15], v[60:61]
	v_cvt_pk_bf16_f32 v176, v16, v17
	v_cvt_pk_bf16_f32 v177, v18, v19
	v_pk_mul_f32 v[14:15], v[162:163], v[10:11] op_sel_hi:[1,0]
	v_pk_mul_f32 v[14:15], v[94:95], v[14:15]
	v_pk_fma_f32 v[16:17], v[78:79], v[14:15], v[62:63]
	v_pk_mul_f32 v[14:15], v[164:165], v[10:11] op_sel_hi:[1,0]
	v_pk_mul_f32 v[14:15], v[96:97], v[14:15]
	v_pk_fma_f32 v[18:19], v[80:81], v[14:15], v[64:65]
	v_cvt_pk_bf16_f32 v204, v16, v17
	v_cvt_pk_bf16_f32 v205, v18, v19
	v_pk_mul_f32 v[14:15], v[168:169], v[10:11] op_sel_hi:[1,0]
	v_pk_mul_f32 v[14:15], v[98:99], v[14:15]
	v_pk_fma_f32 v[16:17], v[82:83], v[14:15], v[66:67]
	v_pk_mul_f32 v[14:15], v[170:171], v[10:11] op_sel_hi:[1,0]
	v_pk_mul_f32 v[14:15], v[100:101], v[14:15]
	v_pk_fma_f32 v[18:19], v[84:85], v[14:15], v[68:69]
	v_cvt_pk_bf16_f32 v214, v16, v17
	v_cvt_pk_bf16_f32 v215, v18, v19
	global_store_dwordx4 v0, v[154:157], s[46:47] offset:0 sc1
	global_store_dwordx4 v0, v[158:161], s[46:47] offset:1024 sc1
	global_store_dwordx4 v0, v[162:165], s[46:47] offset:2048 sc1
	global_store_dwordx4 v0, v[168:171], s[46:47] offset:3072 sc1
	global_store_dwordx2 v1, v[172:173], s[62:63] offset:0 sc1
	global_store_dwordx2 v1, v[176:177], s[62:63] offset:512 sc1
	global_store_dwordx2 v1, v[204:205], s[62:63] offset:1024 sc1
	global_store_dwordx2 v1, v[214:215], s[62:63] offset:1536 sc1
	s_add_u32 s46, s46, 0x1000
	s_addc_u32 s47, s47, 0
	s_add_u32 s62, s62, 0x800
	s_addc_u32 s63, s63, 0
	s_waitcnt vmcnt(28)
	v_lshlrev_b32_e32 v14, 16, v234
	v_and_b32_e32 v15, 0xffff0000, v234
	v_lshlrev_b32_e32 v16, 16, v236
	v_and_b32_e32 v17, 0xffff0000, v236
	v_lshlrev_b32_e32 v18, 16, v235
	v_and_b32_e32 v19, 0xffff0000, v235
	v_lshlrev_b32_e32 v20, 16, v237
	v_and_b32_e32 v21, 0xffff0000, v237
	v_pk_add_f32 v[234:235], v[14:15], v[16:17]
	v_pk_add_f32 v[236:237], v[18:19], v[20:21]
	v_lshlrev_b32_e32 v14, 16, v238
	v_and_b32_e32 v15, 0xffff0000, v238
	v_lshlrev_b32_e32 v16, 16, v240
	v_and_b32_e32 v17, 0xffff0000, v240
	v_lshlrev_b32_e32 v18, 16, v239
	v_and_b32_e32 v19, 0xffff0000, v239
	v_lshlrev_b32_e32 v20, 16, v241
	v_and_b32_e32 v21, 0xffff0000, v241
	v_pk_add_f32 v[238:239], v[14:15], v[16:17]
	v_pk_add_f32 v[240:241], v[18:19], v[20:21]
	v_lshlrev_b32_e32 v14, 16, v242
	v_and_b32_e32 v15, 0xffff0000, v242
	v_lshlrev_b32_e32 v16, 16, v244
	v_and_b32_e32 v17, 0xffff0000, v244
	v_lshlrev_b32_e32 v18, 16, v243
	v_and_b32_e32 v19, 0xffff0000, v243
	v_lshlrev_b32_e32 v20, 16, v245
	v_and_b32_e32 v21, 0xffff0000, v245
	v_pk_add_f32 v[242:243], v[14:15], v[16:17]
	v_pk_add_f32 v[244:245], v[18:19], v[20:21]
	v_lshlrev_b32_e32 v14, 16, v246
	v_and_b32_e32 v15, 0xffff0000, v246
	v_lshlrev_b32_e32 v16, 16, v248
	v_and_b32_e32 v17, 0xffff0000, v248
	v_lshlrev_b32_e32 v18, 16, v247
	v_and_b32_e32 v19, 0xffff0000, v247
	v_lshlrev_b32_e32 v20, 16, v249
	v_and_b32_e32 v21, 0xffff0000, v249
	v_pk_add_f32 v[246:247], v[14:15], v[16:17]
	v_pk_add_f32 v[248:249], v[18:19], v[20:21]
	v_pk_mul_f32 v[12:13], v[234:235], v[234:235]
	v_pk_fma_f32 v[12:13], v[236:237], v[236:237], v[12:13]
	v_pk_fma_f32 v[12:13], v[238:239], v[238:239], v[12:13]
	v_pk_fma_f32 v[12:13], v[240:241], v[240:241], v[12:13]
	v_pk_fma_f32 v[12:13], v[242:243], v[242:243], v[12:13]
	v_pk_fma_f32 v[12:13], v[244:245], v[244:245], v[12:13]
	v_pk_fma_f32 v[12:13], v[246:247], v[246:247], v[12:13]
	v_pk_fma_f32 v[12:13], v[248:249], v[248:249], v[12:13]
	v_add_f32_e32 v5, v12, v13
	s_nop 1
	v_add_f32_dpp v5, v5, v5 quad_perm:[1,0,3,2] row_mask:0xf bank_mask:0xf
	s_nop 1
	v_add_f32_dpp v5, v5, v5 quad_perm:[2,3,0,1] row_mask:0xf bank_mask:0xf
	s_nop 1
	v_add_f32_dpp v5, v5, v5 row_half_mirror row_mask:0xf bank_mask:0xf
	s_nop 1
	v_add_f32_dpp v5, v5, v5 row_mirror row_mask:0xf bank_mask:0xf
	s_nop 1
	v_add_f32_dpp v5, v5, v5 row_bcast:15 row_mask:0xa bank_mask:0xf
	s_nop 1
	v_add_f32_dpp v5, v5, v5 row_bcast:31 row_mask:0xc bank_mask:0xf
	s_nop 1
	v_readlane_b32 s32, v5, 63
	s_nop 1
	v_mov_b32_e32 v6, s32
	v_fmamk_f32 v6, v6, 0x3a800000, v146
	v_rsq_f32_e32 v6, v6
	s_nop 0
	v_mul_f32_e32 v8, 0.5, v6
	v_pk_mul_f32 v[14:15], v[234:235], v[8:9] op_sel_hi:[1,0]
	v_pk_mul_f32 v[14:15], v[38:39], v[14:15]
	v_pk_fma_f32 v[218:219], v[22:23], v[14:15], v[218:219]
	v_pk_mul_f32 v[14:15], v[236:237], v[8:9] op_sel_hi:[1,0]
	v_pk_mul_f32 v[14:15], v[40:41], v[14:15]
	v_pk_fma_f32 v[220:221], v[24:25], v[14:15], v[220:221]
	v_pk_mul_f32 v[14:15], v[238:239], v[8:9] op_sel_hi:[1,0]
	v_pk_mul_f32 v[14:15], v[42:43], v[14:15]
	v_pk_fma_f32 v[222:223], v[26:27], v[14:15], v[222:223]
	v_pk_mul_f32 v[14:15], v[240:241], v[8:9] op_sel_hi:[1,0]
	v_pk_mul_f32 v[14:15], v[44:45], v[14:15]
	v_pk_fma_f32 v[224:225], v[28:29], v[14:15], v[224:225]
	v_pk_mul_f32 v[14:15], v[242:243], v[8:9] op_sel_hi:[1,0]
	v_pk_mul_f32 v[14:15], v[46:47], v[14:15]
	v_pk_fma_f32 v[226:227], v[30:31], v[14:15], v[226:227]
	v_pk_mul_f32 v[14:15], v[244:245], v[8:9] op_sel_hi:[1,0]
	v_pk_mul_f32 v[14:15], v[48:49], v[14:15]
	v_pk_fma_f32 v[228:229], v[32:33], v[14:15], v[228:229]
	v_pk_mul_f32 v[14:15], v[246:247], v[8:9] op_sel_hi:[1,0]
	v_pk_mul_f32 v[14:15], v[50:51], v[14:15]
	v_pk_fma_f32 v[230:231], v[34:35], v[14:15], v[230:231]
	v_pk_mul_f32 v[14:15], v[248:249], v[8:9] op_sel_hi:[1,0]
	v_pk_mul_f32 v[14:15], v[52:53], v[14:15]
	v_pk_fma_f32 v[232:233], v[36:37], v[14:15], v[232:233]
	v_pk_mul_f32 v[12:13], v[218:219], v[218:219]
	v_pk_fma_f32 v[12:13], v[220:221], v[220:221], v[12:13]
	v_pk_fma_f32 v[12:13], v[222:223], v[222:223], v[12:13]
	v_pk_fma_f32 v[12:13], v[224:225], v[224:225], v[12:13]
	v_pk_fma_f32 v[12:13], v[226:227], v[226:227], v[12:13]
	v_pk_fma_f32 v[12:13], v[228:229], v[228:229], v[12:13]
	v_pk_fma_f32 v[12:13], v[230:231], v[230:231], v[12:13]
	v_pk_fma_f32 v[12:13], v[232:233], v[232:233], v[12:13]
	v_add_f32_e32 v5, v12, v13
	s_nop 1
	v_add_f32_dpp v5, v5, v5 quad_perm:[1,0,3,2] row_mask:0xf bank_mask:0xf
	s_nop 1
	v_add_f32_dpp v5, v5, v5 quad_perm:[2,3,0,1] row_mask:0xf bank_mask:0xf
	s_nop 1
	v_add_f32_dpp v5, v5, v5 row_half_mirror row_mask:0xf bank_mask:0xf
	s_nop 1
	v_add_f32_dpp v5, v5, v5 row_mirror row_mask:0xf bank_mask:0xf
	s_nop 1
	v_add_f32_dpp v5, v5, v5 row_bcast:15 row_mask:0xa bank_mask:0xf
	s_nop 1
	v_add_f32_dpp v5, v5, v5 row_bcast:31 row_mask:0xc bank_mask:0xf
	s_nop 1
	v_readlane_b32 s32, v5, 63
	s_nop 1
	v_mov_b32_e32 v6, s32
	v_fmamk_f32 v6, v6, 0x3a800000, v146
	v_rsq_f32_e32 v6, v6
	s_nop 0
	v_mov_b32_e32 v10, v6
	v_pk_mul_f32 v[14:15], v[218:219], v[10:11] op_sel_hi:[1,0]
	v_pk_mul_f32 v[14:15], v[86:87], v[14:15]
	v_pk_fma_f32 v[16:17], v[70:71], v[14:15], v[54:55]
	v_pk_mul_f32 v[14:15], v[220:221], v[10:11] op_sel_hi:[1,0]
	v_pk_mul_f32 v[14:15], v[88:89], v[14:15]
	v_pk_fma_f32 v[18:19], v[72:73], v[14:15], v[56:57]
	v_cvt_pk_bf16_f32 v234, v16, v17
	v_cvt_pk_bf16_f32 v235, v18, v19
	v_pk_mul_f32 v[14:15], v[222:223], v[10:11] op_sel_hi:[1,0]
	v_pk_mul_f32 v[14:15], v[90:91], v[14:15]
	v_pk_fma_f32 v[16:17], v[74:75], v[14:15], v[58:59]
	v_pk_mul_f32 v[14:15], v[224:225], v[10:11] op_sel_hi:[1,0]
	v_pk_mul_f32 v[14:15], v[92:93], v[14:15]
	v_pk_fma_f32 v[18:19], v[76:77], v[14:15], v[60:61]
	v_cvt_pk_bf16_f32 v238, v16, v17
	v_cvt_pk_bf16_f32 v239, v18, v19
	v_pk_mul_f32 v[14:15], v[226:227], v[10:11] op_sel_hi:[1,0]
	v_pk_mul_f32 v[14:15], v[94:95], v[14:15]
	v_pk_fma_f32 v[16:17], v[78:79], v[14:15], v[62:63]
	v_pk_mul_f32 v[14:15], v[228:229], v[10:11] op_sel_hi:[1,0]
	v_pk_mul_f32 v[14:15], v[96:97], v[14:15]
	v_pk_fma_f32 v[18:19], v[80:81], v[14:15], v[64:65]
	v_cvt_pk_bf16_f32 v242, v16, v17
	v_cvt_pk_bf16_f32 v243, v18, v19
	v_pk_mul_f32 v[14:15], v[230:231], v[10:11] op_sel_hi:[1,0]
	v_pk_mul_f32 v[14:15], v[98:99], v[14:15]
	v_pk_fma_f32 v[16:17], v[82:83], v[14:15], v[66:67]
	v_pk_mul_f32 v[14:15], v[232:233], v[10:11] op_sel_hi:[1,0]
	v_pk_mul_f32 v[14:15], v[100:101], v[14:15]
	v_pk_fma_f32 v[18:19], v[84:85], v[14:15], v[68:69]
	v_cvt_pk_bf16_f32 v246, v16, v17
	v_cvt_pk_bf16_f32 v247, v18, v19
	global_store_dwordx4 v0, v[218:221], s[46:47] offset:0 sc1
	global_store_dwordx4 v0, v[222:225], s[46:47] offset:1024 sc1
	global_store_dwordx4 v0, v[226:229], s[46:47] offset:2048 sc1
	global_store_dwordx4 v0, v[230:233], s[46:47] offset:3072 sc1
	global_store_dwordx2 v1, v[234:235], s[62:63] offset:0 sc1
	global_store_dwordx2 v1, v[238:239], s[62:63] offset:512 sc1
	global_store_dwordx2 v1, v[242:243], s[62:63] offset:1024 sc1
	global_store_dwordx2 v1, v[246:247], s[62:63] offset:1536 sc1
	s_add_u32 s46, s46, 0x1000
	s_addc_u32 s47, s47, 0
	s_add_u32 s62, s62, 0x800
	s_addc_u32 s63, s63, 0
	s_waitcnt vmcnt(16)
	v_lshlrev_b32_e32 v14, 16, v118
	v_and_b32_e32 v15, 0xffff0000, v118
	v_lshlrev_b32_e32 v16, 16, v120
	v_and_b32_e32 v17, 0xffff0000, v120
	v_lshlrev_b32_e32 v18, 16, v119
	v_and_b32_e32 v19, 0xffff0000, v119
	v_lshlrev_b32_e32 v20, 16, v121
	v_and_b32_e32 v21, 0xffff0000, v121
	v_pk_add_f32 v[118:119], v[14:15], v[16:17]
	v_pk_add_f32 v[120:121], v[18:19], v[20:21]
	v_lshlrev_b32_e32 v14, 16, v122
	v_and_b32_e32 v15, 0xffff0000, v122
	v_lshlrev_b32_e32 v16, 16, v124
	v_and_b32_e32 v17, 0xffff0000, v124
	v_lshlrev_b32_e32 v18, 16, v123
	v_and_b32_e32 v19, 0xffff0000, v123
	v_lshlrev_b32_e32 v20, 16, v125
	v_and_b32_e32 v21, 0xffff0000, v125
	v_pk_add_f32 v[122:123], v[14:15], v[16:17]
	v_pk_add_f32 v[124:125], v[18:19], v[20:21]
	v_lshlrev_b32_e32 v14, 16, v134
	v_and_b32_e32 v15, 0xffff0000, v134
	v_lshlrev_b32_e32 v16, 16, v136
	v_and_b32_e32 v17, 0xffff0000, v136
	v_lshlrev_b32_e32 v18, 16, v135
	v_and_b32_e32 v19, 0xffff0000, v135
	v_lshlrev_b32_e32 v20, 16, v137
	v_and_b32_e32 v21, 0xffff0000, v137
	v_pk_add_f32 v[134:135], v[14:15], v[16:17]
	v_pk_add_f32 v[136:137], v[18:19], v[20:21]
	v_lshlrev_b32_e32 v14, 16, v138
	v_and_b32_e32 v15, 0xffff0000, v138
	v_lshlrev_b32_e32 v16, 16, v140
	v_and_b32_e32 v17, 0xffff0000, v140
	v_lshlrev_b32_e32 v18, 16, v139
	v_and_b32_e32 v19, 0xffff0000, v139
	v_lshlrev_b32_e32 v20, 16, v141
	v_and_b32_e32 v21, 0xffff0000, v141
	v_pk_add_f32 v[138:139], v[14:15], v[16:17]
	v_pk_add_f32 v[140:141], v[18:19], v[20:21]
	v_pk_mul_f32 v[12:13], v[118:119], v[118:119]
	v_pk_fma_f32 v[12:13], v[120:121], v[120:121], v[12:13]
	v_pk_fma_f32 v[12:13], v[122:123], v[122:123], v[12:13]
	v_pk_fma_f32 v[12:13], v[124:125], v[124:125], v[12:13]
	v_pk_fma_f32 v[12:13], v[134:135], v[134:135], v[12:13]
	v_pk_fma_f32 v[12:13], v[136:137], v[136:137], v[12:13]
	v_pk_fma_f32 v[12:13], v[138:139], v[138:139], v[12:13]
	v_pk_fma_f32 v[12:13], v[140:141], v[140:141], v[12:13]
	v_add_f32_e32 v5, v12, v13
	s_nop 1
	v_add_f32_dpp v5, v5, v5 quad_perm:[1,0,3,2] row_mask:0xf bank_mask:0xf
	s_nop 1
	v_add_f32_dpp v5, v5, v5 quad_perm:[2,3,0,1] row_mask:0xf bank_mask:0xf
	s_nop 1
	v_add_f32_dpp v5, v5, v5 row_half_mirror row_mask:0xf bank_mask:0xf
	s_nop 1
	v_add_f32_dpp v5, v5, v5 row_mirror row_mask:0xf bank_mask:0xf
	s_nop 1
	v_add_f32_dpp v5, v5, v5 row_bcast:15 row_mask:0xa bank_mask:0xf
	s_nop 1
	v_add_f32_dpp v5, v5, v5 row_bcast:31 row_mask:0xc bank_mask:0xf
	s_nop 1
	v_readlane_b32 s32, v5, 63
	s_nop 1
	v_mov_b32_e32 v6, s32
	v_fmamk_f32 v6, v6, 0x3a800000, v146
	v_rsq_f32_e32 v6, v6
	s_nop 0
	v_mul_f32_e32 v8, 0.5, v6
	v_pk_mul_f32 v[14:15], v[118:119], v[8:9] op_sel_hi:[1,0]
	v_pk_mul_f32 v[14:15], v[38:39], v[14:15]
	v_pk_fma_f32 v[102:103], v[22:23], v[14:15], v[102:103]
	v_pk_mul_f32 v[14:15], v[120:121], v[8:9] op_sel_hi:[1,0]
	v_pk_mul_f32 v[14:15], v[40:41], v[14:15]
	v_pk_fma_f32 v[104:105], v[24:25], v[14:15], v[104:105]
	v_pk_mul_f32 v[14:15], v[122:123], v[8:9] op_sel_hi:[1,0]
	v_pk_mul_f32 v[14:15], v[42:43], v[14:15]
	v_pk_fma_f32 v[106:107], v[26:27], v[14:15], v[106:107]
	v_pk_mul_f32 v[14:15], v[124:125], v[8:9] op_sel_hi:[1,0]
	v_pk_mul_f32 v[14:15], v[44:45], v[14:15]
	v_pk_fma_f32 v[108:109], v[28:29], v[14:15], v[108:109]
	v_pk_mul_f32 v[14:15], v[134:135], v[8:9] op_sel_hi:[1,0]
	v_pk_mul_f32 v[14:15], v[46:47], v[14:15]
	v_pk_fma_f32 v[110:111], v[30:31], v[14:15], v[110:111]
	v_pk_mul_f32 v[14:15], v[136:137], v[8:9] op_sel_hi:[1,0]
	v_pk_mul_f32 v[14:15], v[48:49], v[14:15]
	v_pk_fma_f32 v[112:113], v[32:33], v[14:15], v[112:113]
	v_pk_mul_f32 v[14:15], v[138:139], v[8:9] op_sel_hi:[1,0]
	v_pk_mul_f32 v[14:15], v[50:51], v[14:15]
	v_pk_fma_f32 v[114:115], v[34:35], v[14:15], v[114:115]
	v_pk_mul_f32 v[14:15], v[140:141], v[8:9] op_sel_hi:[1,0]
	v_pk_mul_f32 v[14:15], v[52:53], v[14:15]
	v_pk_fma_f32 v[116:117], v[36:37], v[14:15], v[116:117]
	v_pk_mul_f32 v[12:13], v[102:103], v[102:103]
	v_pk_fma_f32 v[12:13], v[104:105], v[104:105], v[12:13]
	v_pk_fma_f32 v[12:13], v[106:107], v[106:107], v[12:13]
	v_pk_fma_f32 v[12:13], v[108:109], v[108:109], v[12:13]
	v_pk_fma_f32 v[12:13], v[110:111], v[110:111], v[12:13]
	v_pk_fma_f32 v[12:13], v[112:113], v[112:113], v[12:13]
	v_pk_fma_f32 v[12:13], v[114:115], v[114:115], v[12:13]
	v_pk_fma_f32 v[12:13], v[116:117], v[116:117], v[12:13]
	v_add_f32_e32 v5, v12, v13
	s_nop 1
	v_add_f32_dpp v5, v5, v5 quad_perm:[1,0,3,2] row_mask:0xf bank_mask:0xf
	s_nop 1
	v_add_f32_dpp v5, v5, v5 quad_perm:[2,3,0,1] row_mask:0xf bank_mask:0xf
	s_nop 1
	v_add_f32_dpp v5, v5, v5 row_half_mirror row_mask:0xf bank_mask:0xf
	s_nop 1
	v_add_f32_dpp v5, v5, v5 row_mirror row_mask:0xf bank_mask:0xf
	s_nop 1
	v_add_f32_dpp v5, v5, v5 row_bcast:15 row_mask:0xa bank_mask:0xf
	s_nop 1
	v_add_f32_dpp v5, v5, v5 row_bcast:31 row_mask:0xc bank_mask:0xf
	s_nop 1
	v_readlane_b32 s32, v5, 63
	s_nop 1
	v_mov_b32_e32 v6, s32
	v_fmamk_f32 v6, v6, 0x3a800000, v146
	v_rsq_f32_e32 v6, v6
	s_nop 0
	v_mov_b32_e32 v10, v6
	v_pk_mul_f32 v[14:15], v[102:103], v[10:11] op_sel_hi:[1,0]
	v_pk_mul_f32 v[14:15], v[86:87], v[14:15]
	v_pk_fma_f32 v[16:17], v[70:71], v[14:15], v[54:55]
	v_pk_mul_f32 v[14:15], v[104:105], v[10:11] op_sel_hi:[1,0]
	v_pk_mul_f32 v[14:15], v[88:89], v[14:15]
	v_pk_fma_f32 v[18:19], v[72:73], v[14:15], v[56:57]
	v_cvt_pk_bf16_f32 v118, v16, v17
	v_cvt_pk_bf16_f32 v119, v18, v19
	v_pk_mul_f32 v[14:15], v[106:107], v[10:11] op_sel_hi:[1,0]
	v_pk_mul_f32 v[14:15], v[90:91], v[14:15]
	v_pk_fma_f32 v[16:17], v[74:75], v[14:15], v[58:59]
	v_pk_mul_f32 v[14:15], v[108:109], v[10:11] op_sel_hi:[1,0]
	v_pk_mul_f32 v[14:15], v[92:93], v[14:15]
	v_pk_fma_f32 v[18:19], v[76:77], v[14:15], v[60:61]
	v_cvt_pk_bf16_f32 v122, v16, v17
	v_cvt_pk_bf16_f32 v123, v18, v19
	v_pk_mul_f32 v[14:15], v[110:111], v[10:11] op_sel_hi:[1,0]
	v_pk_mul_f32 v[14:15], v[94:95], v[14:15]
	v_pk_fma_f32 v[16:17], v[78:79], v[14:15], v[62:63]
	v_pk_mul_f32 v[14:15], v[112:113], v[10:11] op_sel_hi:[1,0]
	v_pk_mul_f32 v[14:15], v[96:97], v[14:15]
	v_pk_fma_f32 v[18:19], v[80:81], v[14:15], v[64:65]
	v_cvt_pk_bf16_f32 v134, v16, v17
	v_cvt_pk_bf16_f32 v135, v18, v19
	v_pk_mul_f32 v[14:15], v[114:115], v[10:11] op_sel_hi:[1,0]
	v_pk_mul_f32 v[14:15], v[98:99], v[14:15]
	v_pk_fma_f32 v[16:17], v[82:83], v[14:15], v[66:67]
	v_pk_mul_f32 v[14:15], v[116:117], v[10:11] op_sel_hi:[1,0]
	v_pk_mul_f32 v[14:15], v[100:101], v[14:15]
	v_pk_fma_f32 v[18:19], v[84:85], v[14:15], v[68:69]
	v_cvt_pk_bf16_f32 v138, v16, v17
	v_cvt_pk_bf16_f32 v139, v18, v19
	global_store_dwordx4 v0, v[102:105], s[46:47] offset:0 sc1
	global_store_dwordx4 v0, v[106:109], s[46:47] offset:1024 sc1
	global_store_dwordx4 v0, v[110:113], s[46:47] offset:2048 sc1
	global_store_dwordx4 v0, v[114:117], s[46:47] offset:3072 sc1
	global_store_dwordx2 v1, v[118:119], s[62:63] offset:0 sc1
	global_store_dwordx2 v1, v[122:123], s[62:63] offset:512 sc1
	global_store_dwordx2 v1, v[134:135], s[62:63] offset:1024 sc1
	global_store_dwordx2 v1, v[138:139], s[62:63] offset:1536 sc1
	s_add_u32 s46, s46, 0x1000
	s_addc_u32 s47, s47, 0
	s_add_u32 s62, s62, 0x800
	s_addc_u32 s63, s63, 0

.Lxb_noinv_4:
	v_cmp_eq_u32_e32 vcc, 0, v0
	s_and_saveexec_b64 s[4:5], vcc
	s_cbranch_execz .LBB0_575
	s_load_dwordx2 s[12:13], s[16:17], 0x98
	v_readlane_b32 s14, v255, 0
	v_readlane_b32 s15, v255, 47
	s_nop 0
	s_lshr_b32 s24, s14, 3
	s_and_b32 s24, s24, 7
	s_and_b32 s27, s14, 6
	s_lshl_b32 s27, s27, 2
	s_or_b32 s27, s27, s24
	s_and_b32 s30, s14, 3
	s_lshl_b32 s30, s30, 3
	s_or_b32 s30, s30, s24
	s_lshl_b32 s27, s27, 7
	s_add_u32 s27, s27, 0xb000
	s_add_u32 s15, s15, 8
	v_writelane_b32 v255, s15, 47
	v_mov_b32_e32 v0, s27
	s_waitcnt lgkmcnt(0)
	global_atomic_add v0, v189, s[12:13]
	v_mov_b32_e32 v7, s27
	s_mov_b32 s32, 0

.Lgs_done_b4:
.LBB0_575:
	s_or_b64 exec, exec, s[4:5]
	s_waitcnt lgkmcnt(0)
	s_barrier
	v_readlane_b32 s50, v255, 0
	s_load_dwordx4 s[12:15], s[16:17], 0x90
	v_mov_b32_e32 v10, v147
	s_cmpk_lt_i32 s50, 0x100
	s_cselect_b64 s[10:11], -1, 0
	v_readfirstlane_b32 s2, v10
	s_cmpk_gt_i32 s50, 0xff
	s_mov_b64 s[4:5], 0
	s_cbranch_scc1 .LBB0_581
	s_ashr_i32 s4, s50, 31
	s_lshr_b32 s4, s4, 29
	s_add_i32 s6, s50, s4
	s_and_b32 s4, s6, -8
	s_sub_i32 s7, s50, s4
	s_cmp_gt_i32 s7, -1
	s_mov_b64 s[4:5], -1
	s_cbranch_scc0 .LBB0_578
	s_lshl_b32 s8, s7, 5
	s_mov_b64 s[4:5], 0

.Lxb_noinv_7:
	v_cmp_eq_u32_e32 vcc, 0, v0
	s_and_saveexec_b64 s[4:5], vcc
	s_xor_b64 s[4:5], exec, s[4:5]
	s_cbranch_execz .LBB0_1222
	s_load_dwordx2 s[12:13], s[8:9], 0x98
	v_readlane_b32 s14, v255, 0
	v_readlane_b32 s15, v255, 46
	s_nop 0
	s_lshr_b32 s24, s14, 3
	s_and_b32 s24, s24, 7
	s_and_b32 s27, s14, 6
	s_lshl_b32 s27, s27, 2
	s_or_b32 s27, s27, s24
	s_and_b32 s30, s14, 3
	s_lshl_b32 s30, s30, 3
	s_or_b32 s30, s30, s24
	s_lshl_b32 s27, s27, 7
	s_add_u32 s27, s27, 0xa000
	s_lshl_b32 s30, s30, 7
	s_add_u32 s30, s30, 0xa000
	s_add_u32 s15, s15, 8
	v_writelane_b32 v255, s15, 46
	v_mov_b32_e32 v0, s30
	s_waitcnt lgkmcnt(0)
	global_atomic_add v0, v189, s[12:13]
	v_mov_b32_e32 v7, s27
	s_mov_b32 s32, 0

.Lgs_done_b7:
.LBB0_1222:
	s_or_b64 exec, exec, s[4:5]
	s_waitcnt lgkmcnt(0)
	v_mov_b32_e32 v0, v147
	v_readlane_b32 s2, v255, 0
	s_barrier
	s_nop 0
	v_ashrrev_i32_e32 v1, 6, v0
	v_lshl_add_u32 v16, s2, 3, v1
	s_movk_i32 s2, 0x2000
	v_cmp_gt_i32_e32 vcc, s2, v16
	s_and_saveexec_b64 s[10:11], vcc
	s_cbranch_execz .LBB0_1225
	s_load_dwordx4 s[4:7], s[8:9], 0x90
	s_load_dwordx4 s[16:19], s[8:9], 0x40
	s_mul_i32 s2, s70, 0x2d000
	v_lshlrev_b32_e32 v1, 2, v0
	v_readlane_b32 s20, v255, 12
	s_waitcnt lgkmcnt(0)
	s_add_u32 s14, s6, s2
	s_mul_hi_u32 s2, s70, 0x2d000
	s_addc_u32 s15, s7, s2
	v_cmp_lt_i32_e32 vcc, v188, v183
	v_and_b32_e32 v2, 0xfc, v1
	s_add_u32 s12, s14, 0x106000
	v_readlane_b32 s21, v255, 13
	v_cndmask_b32_e32 v1, v182, v188, vcc
	v_cmp_lt_i32_e32 vcc, v254, v183
	s_addc_u32 s13, s15, 0
	s_lshl_b64 s[20:21], s[20:21], 2
	v_lshlrev_b32_e32 v28, 2, v1
	v_cndmask_b32_e32 v1, v182, v254, vcc
	s_add_u32 s16, s16, s20
	v_lshlrev_b32_e32 v29, 2, v1
	v_xor_b32_e32 v1, 4, v182
	s_addc_u32 s17, s17, s21
	v_cmp_lt_i32_e32 vcc, v1, v183
	s_add_u32 s18, s18, s20
	v_lshlrev_b32_e32 v144, 2, v2
	v_cndmask_b32_e32 v1, v182, v1, vcc
	s_addc_u32 s19, s19, s21
	v_lshl_add_u64 v[4:5], s[14:15], 0, v[144:145]
	s_mov_b64 s[14:15], 0x105000
	v_lshlrev_b32_e32 v30, 2, v1
	v_xor_b32_e32 v1, 8, v182
	v_lshl_add_u64 v[18:19], v[4:5], 0, s[14:15]
	v_lshl_add_u64 v[4:5], s[18:19], 0, v[144:145]
	v_cmp_lt_i32_e32 vcc, v1, v183
	v_lshl_add_u64 v[20:21], v[4:5], 0, s[94:95]
	v_lshl_add_u64 v[4:5], s[16:17], 0, v[144:145]
	s_mov_b64 s[14:15], 0x2000
	v_cndmask_b32_e32 v1, v182, v1, vcc
	v_cmp_lt_i32_e32 vcc, v187, v183
	v_ashrrev_i32_e32 v17, 31, v16
	v_lshl_add_u64 v[22:23], v[4:5], 0, s[14:15]
	v_lshlrev_b32_e32 v31, 2, v1
	v_cndmask_b32_e32 v1, v182, v187, vcc
	v_cmp_lt_i32_e32 vcc, v184, v183
	v_lshlrev_b64 v[4:5], 11, v[16:17]
	v_and_b32_e32 v3, 63, v0
	v_lshlrev_b32_e32 v32, 2, v1
	v_cndmask_b32_e32 v1, v182, v184, vcc
	v_lshl_or_b32 v4, v3, 3, v4
	v_lshlrev_b32_e32 v33, 2, v1
	v_lshl_add_u64 v[0:1], s[6:7], 0, v[4:5]
	s_mov_b64 s[6:7], 0x9800600
	v_lshl_add_u64 v[24:25], v[0:1], 0, s[6:7]
	v_lshlrev_b64 v[0:1], 12, v[16:17]
	v_lshl_or_b32 v0, v3, 4, v0
	v_lshl_add_u64 v[26:27], s[4:5], 0, v[0:1]
	s_mov_b64 s[4:5], 0
	v_lshlrev_b32_e32 v144, 2, v2
	v_readlane_b32 s2, v255, 0
	v_readfirstlane_b32 s7, v147
	s_load_dwordx2 s[4:5], s[8:9], 0x90
	s_load_dwordx2 s[12:13], s[8:9], 0x98
	s_load_dwordx2 s[14:15], s[8:9], 0x40
	s_load_dwordx2 s[40:41], s[8:9], 0x48
	v_and_b32_e32 v0, 63, v147
	v_lshlrev_b32_e32 v1, 3, v0
	v_lshlrev_b32_e32 v0, 4, v0
	s_lshr_b32 s7, s7, 6
	s_and_b32 s27, s2, 6
	s_lshl_b32 s27, s27, 5
	s_and_b32 s37, s2, 0x39
	s_or_b32 s27, s27, s37
	s_lshr_b32 s37, s2, 6
	s_lshl_b32 s37, s37, 1
	s_or_b32 s2, s27, s37
	s_lshl_b32 s2, s2, 3
	s_add_u32 s2, s2, s7
	s_lshl_b32 s24, s2, 2
	s_sub_u32 s27, s24, 0x1000
	s_lshr_b32 s27, s27, 10
	s_add_u32 s27, s27, 1
	s_cmp_lt_u32 s24, 0x1000
	s_cselect_b32 s30, 0, s27
	v_add_u32_e32 v2, 0x5000, v0
	v_add_u32_e32 v3, 0x6000, v0
	v_add_u32_e32 v4, 0x7000, v0
	s_waitcnt lgkmcnt(0)
	s_lshl_b32 s27, s24, 11
	s_add_u32 s62, s12, s27
	s_addc_u32 s63, s13, 0
	s_add_u32 s58, s62, 0x8800000
	s_addc_u32 s59, s63, 0
	s_add_u32 s60, s58, 0x1000000
	s_addc_u32 s61, s59, 0
	s_add_u32 s62, s62, 0x1000000
	s_addc_u32 s63, s63, 0
	s_lshl_b32 s27, s24, 12
	s_add_u32 s46, s4, s27
	s_addc_u32 s47, s5, 0
	s_mov_b64 s[4:5], s[46:47]
	s_mul_i32 s27, s70, 5
	s_add_u32 s27, s27, s30
	s_mul_i32 s27, s27, 0x9000
	s_add_u32 s27, s27, 0x100000
	s_add_u32 s88, s12, s27
	s_addc_u32 s89, s13, 0
	s_mov_b64 s[100:101], s[88:89]
	s_mul_i32 s27, s70, 0x3000
	s_add_u32 s27, s27, 0x1000
	s_add_u32 s40, s40, s27
	s_addc_u32 s41, s41, 0
	s_mul_i32 s27, s70, 0x3000
	s_add_u32 s27, s27, 0x2000
	s_add_u32 s14, s14, s27
	s_addc_u32 s15, s15, 0
	global_load_dwordx4 v[22:25], v2, s[100:101] offset:0
	global_load_dwordx4 v[38:41], v0, s[40:41] offset:0
	global_load_dwordx4 v[54:57], v3, s[88:89] offset:0
	global_load_dwordx4 v[70:73], v4, s[88:89] offset:0
	global_load_dwordx4 v[86:89], v0, s[14:15] offset:0
	global_load_dwordx4 v[26:29], v2, s[100:101] offset:1024
	global_load_dwordx4 v[42:45], v0, s[40:41] offset:1024
	global_load_dwordx4 v[58:61], v3, s[88:89] offset:1024
	global_load_dwordx4 v[74:77], v4, s[88:89] offset:1024
	global_load_dwordx4 v[90:93], v0, s[14:15] offset:1024
	global_load_dwordx4 v[30:33], v2, s[100:101] offset:2048
	global_load_dwordx4 v[46:49], v0, s[40:41] offset:2048
	global_load_dwordx4 v[62:65], v3, s[88:89] offset:2048
	global_load_dwordx4 v[78:81], v4, s[88:89] offset:2048
	global_load_dwordx4 v[94:97], v0, s[14:15] offset:2048
	global_load_dwordx4 v[34:37], v2, s[100:101] offset:3072
	global_load_dwordx4 v[50:53], v0, s[40:41] offset:3072
	global_load_dwordx4 v[66:69], v3, s[88:89] offset:3072
	global_load_dwordx4 v[82:85], v4, s[88:89] offset:3072
	global_load_dwordx4 v[98:101], v0, s[14:15] offset:3072
	global_load_dwordx4 v[102:105], v0, s[4:5] offset:0
	global_load_dwordx4 v[106:109], v0, s[4:5] offset:1024
	global_load_dwordx4 v[110:113], v0, s[4:5] offset:2048
	global_load_dwordx4 v[114:117], v0, s[4:5] offset:3072
	global_load_dwordx2 v[118:119], v1, s[58:59] offset:0
	global_load_dwordx2 v[122:123], v1, s[58:59] offset:512
	global_load_dwordx2 v[134:135], v1, s[58:59] offset:1024
	global_load_dwordx2 v[138:139], v1, s[58:59] offset:1536
	global_load_dwordx2 v[120:121], v1, s[60:61] offset:0
	global_load_dwordx2 v[124:125], v1, s[60:61] offset:512
	global_load_dwordx2 v[136:137], v1, s[60:61] offset:1024
	global_load_dwordx2 v[140:141], v1, s[60:61] offset:1536
	s_add_u32 s4, s4, 0x1000
	s_addc_u32 s5, s5, 0
	s_add_u32 s58, s58, 0x800
	s_addc_u32 s59, s59, 0
	s_add_u32 s60, s60, 0x800
	s_addc_u32 s61, s61, 0
	global_load_dwordx4 v[154:157], v0, s[4:5] offset:0
	global_load_dwordx4 v[158:161], v0, s[4:5] offset:1024
	global_load_dwordx4 v[162:165], v0, s[4:5] offset:2048
	global_load_dwordx4 v[168:171], v0, s[4:5] offset:3072
	global_load_dwordx2 v[172:173], v1, s[58:59] offset:0
	global_load_dwordx2 v[176:177], v1, s[58:59] offset:512
	global_load_dwordx2 v[204:205], v1, s[58:59] offset:1024
	global_load_dwordx2 v[214:215], v1, s[58:59] offset:1536
	global_load_dwordx2 v[174:175], v1, s[60:61] offset:0
	global_load_dwordx2 v[178:179], v1, s[60:61] offset:512
	global_load_dwordx2 v[206:207], v1, s[60:61] offset:1024
	global_load_dwordx2 v[216:217], v1, s[60:61] offset:1536
	s_add_u32 s4, s4, 0x1000
	s_addc_u32 s5, s5, 0
	s_add_u32 s58, s58, 0x800
	s_addc_u32 s59, s59, 0
	s_add_u32 s60, s60, 0x800
	s_addc_u32 s61, s61, 0
	global_load_dwordx4 v[218:221], v0, s[4:5] offset:0
	global_load_dwordx4 v[222:225], v0, s[4:5] offset:1024
	global_load_dwordx4 v[226:229], v0, s[4:5] offset:2048
	global_load_dwordx4 v[230:233], v0, s[4:5] offset:3072
	global_load_dwordx2 v[234:235], v1, s[58:59] offset:0
	global_load_dwordx2 v[238:239], v1, s[58:59] offset:512
	global_load_dwordx2 v[242:243], v1, s[58:59] offset:1024
	global_load_dwordx2 v[246:247], v1, s[58:59] offset:1536
	global_load_dwordx2 v[236:237], v1, s[60:61] offset:0
	global_load_dwordx2 v[240:241], v1, s[60:61] offset:512
	global_load_dwordx2 v[244:245], v1, s[60:61] offset:1024
	global_load_dwordx2 v[248:249], v1, s[60:61] offset:1536
	s_add_u32 s4, s4, 0x1000
	s_addc_u32 s5, s5, 0
	s_add_u32 s58, s58, 0x800
	s_addc_u32 s59, s59, 0
	s_add_u32 s60, s60, 0x800
	s_addc_u32 s61, s61, 0
	s_waitcnt vmcnt(24)
	v_pk_add_f32 v[70:71], v[70:71], 1.0 op_sel_hi:[1,0]
	v_pk_add_f32 v[72:73], v[72:73], 1.0 op_sel_hi:[1,0]
	v_pk_add_f32 v[74:75], v[74:75], 1.0 op_sel_hi:[1,0]
	v_pk_add_f32 v[76:77], v[76:77], 1.0 op_sel_hi:[1,0]
	v_pk_add_f32 v[78:79], v[78:79], 1.0 op_sel_hi:[1,0]
	v_pk_add_f32 v[80:81], v[80:81], 1.0 op_sel_hi:[1,0]
	v_pk_add_f32 v[82:83], v[82:83], 1.0 op_sel_hi:[1,0]
	v_pk_add_f32 v[84:85], v[84:85], 1.0 op_sel_hi:[1,0]
	v_lshlrev_b32_e32 v14, 16, v118
	v_and_b32_e32 v15, 0xffff0000, v118
	v_lshlrev_b32_e32 v16, 16, v120
	v_and_b32_e32 v17, 0xffff0000, v120
	v_lshlrev_b32_e32 v18, 16, v119
	v_and_b32_e32 v19, 0xffff0000, v119
	v_lshlrev_b32_e32 v20, 16, v121
	v_and_b32_e32 v21, 0xffff0000, v121
	v_pk_add_f32 v[118:119], v[14:15], v[16:17]
	v_pk_add_f32 v[120:121], v[18:19], v[20:21]
	v_lshlrev_b32_e32 v14, 16, v122
	v_and_b32_e32 v15, 0xffff0000, v122
	v_lshlrev_b32_e32 v16, 16, v124
	v_and_b32_e32 v17, 0xffff0000, v124
	v_lshlrev_b32_e32 v18, 16, v123
	v_and_b32_e32 v19, 0xffff0000, v123
	v_lshlrev_b32_e32 v20, 16, v125
	v_and_b32_e32 v21, 0xffff0000, v125
	v_pk_add_f32 v[122:123], v[14:15], v[16:17]
	v_pk_add_f32 v[124:125], v[18:19], v[20:21]
	v_lshlrev_b32_e32 v14, 16, v134
	v_and_b32_e32 v15, 0xffff0000, v134
	v_lshlrev_b32_e32 v16, 16, v136
	v_and_b32_e32 v17, 0xffff0000, v136
	v_lshlrev_b32_e32 v18, 16, v135
	v_and_b32_e32 v19, 0xffff0000, v135
	v_lshlrev_b32_e32 v20, 16, v137
	v_and_b32_e32 v21, 0xffff0000, v137
	v_pk_add_f32 v[134:135], v[14:15], v[16:17]
	v_pk_add_f32 v[136:137], v[18:19], v[20:21]
	v_lshlrev_b32_e32 v14, 16, v138
	v_and_b32_e32 v15, 0xffff0000, v138
	v_lshlrev_b32_e32 v16, 16, v140
	v_and_b32_e32 v17, 0xffff0000, v140
	v_lshlrev_b32_e32 v18, 16, v139
	v_and_b32_e32 v19, 0xffff0000, v139
	v_lshlrev_b32_e32 v20, 16, v141
	v_and_b32_e32 v21, 0xffff0000, v141
	v_pk_add_f32 v[138:139], v[14:15], v[16:17]
	v_pk_add_f32 v[140:141], v[18:19], v[20:21]
	v_pk_mul_f32 v[12:13], v[118:119], v[118:119]
	v_pk_fma_f32 v[12:13], v[120:121], v[120:121], v[12:13]
	v_pk_fma_f32 v[12:13], v[122:123], v[122:123], v[12:13]
	v_pk_fma_f32 v[12:13], v[124:125], v[124:125], v[12:13]
	v_pk_fma_f32 v[12:13], v[134:135], v[134:135], v[12:13]
	v_pk_fma_f32 v[12:13], v[136:137], v[136:137], v[12:13]
	v_pk_fma_f32 v[12:13], v[138:139], v[138:139], v[12:13]
	v_pk_fma_f32 v[12:13], v[140:141], v[140:141], v[12:13]
	v_add_f32_e32 v5, v12, v13
	s_nop 1
	v_add_f32_dpp v5, v5, v5 quad_perm:[1,0,3,2] row_mask:0xf bank_mask:0xf
	s_nop 1
	v_add_f32_dpp v5, v5, v5 quad_perm:[2,3,0,1] row_mask:0xf bank_mask:0xf
	s_nop 1
	v_add_f32_dpp v5, v5, v5 row_half_mirror row_mask:0xf bank_mask:0xf
	s_nop 1
	v_add_f32_dpp v5, v5, v5 row_mirror row_mask:0xf bank_mask:0xf
	s_nop 1
	v_add_f32_dpp v5, v5, v5 row_bcast:15 row_mask:0xa bank_mask:0xf
	s_nop 1
	v_add_f32_dpp v5, v5, v5 row_bcast:31 row_mask:0xc bank_mask:0xf
	s_nop 1
	v_readlane_b32 s32, v5, 63
	s_nop 1
	v_mov_b32_e32 v6, s32
	v_fmamk_f32 v6, v6, 0x3a800000, v146
	v_rsq_f32_e32 v6, v6
	s_nop 0
	v_mov_b32_e32 v8, v6
	v_pk_mul_f32 v[14:15], v[118:119], v[8:9] op_sel_hi:[1,0]
	v_pk_mul_f32 v[14:15], v[38:39], v[14:15]
	v_pk_fma_f32 v[102:103], v[22:23], v[14:15], v[102:103]
	v_pk_mul_f32 v[14:15], v[120:121], v[8:9] op_sel_hi:[1,0]
	v_pk_mul_f32 v[14:15], v[40:41], v[14:15]
	v_pk_fma_f32 v[104:105], v[24:25], v[14:15], v[104:105]
	v_pk_mul_f32 v[14:15], v[122:123], v[8:9] op_sel_hi:[1,0]
	v_pk_mul_f32 v[14:15], v[42:43], v[14:15]
	v_pk_fma_f32 v[106:107], v[26:27], v[14:15], v[106:107]
	v_pk_mul_f32 v[14:15], v[124:125], v[8:9] op_sel_hi:[1,0]
	v_pk_mul_f32 v[14:15], v[44:45], v[14:15]
	v_pk_fma_f32 v[108:109], v[28:29], v[14:15], v[108:109]
	v_pk_mul_f32 v[14:15], v[134:135], v[8:9] op_sel_hi:[1,0]
	v_pk_mul_f32 v[14:15], v[46:47], v[14:15]
	v_pk_fma_f32 v[110:111], v[30:31], v[14:15], v[110:111]
	v_pk_mul_f32 v[14:15], v[136:137], v[8:9] op_sel_hi:[1,0]
	v_pk_mul_f32 v[14:15], v[48:49], v[14:15]
	v_pk_fma_f32 v[112:113], v[32:33], v[14:15], v[112:113]
	v_pk_mul_f32 v[14:15], v[138:139], v[8:9] op_sel_hi:[1,0]
	v_pk_mul_f32 v[14:15], v[50:51], v[14:15]
	v_pk_fma_f32 v[114:115], v[34:35], v[14:15], v[114:115]
	v_pk_mul_f32 v[14:15], v[140:141], v[8:9] op_sel_hi:[1,0]
	v_pk_mul_f32 v[14:15], v[52:53], v[14:15]
	v_pk_fma_f32 v[116:117], v[36:37], v[14:15], v[116:117]
	v_pk_mul_f32 v[12:13], v[102:103], v[102:103]
	v_pk_fma_f32 v[12:13], v[104:105], v[104:105], v[12:13]
	v_pk_fma_f32 v[12:13], v[106:107], v[106:107], v[12:13]
	v_pk_fma_f32 v[12:13], v[108:109], v[108:109], v[12:13]
	v_pk_fma_f32 v[12:13], v[110:111], v[110:111], v[12:13]
	v_pk_fma_f32 v[12:13], v[112:113], v[112:113], v[12:13]
	v_pk_fma_f32 v[12:13], v[114:115], v[114:115], v[12:13]
	v_pk_fma_f32 v[12:13], v[116:117], v[116:117], v[12:13]
	v_add_f32_e32 v5, v12, v13
	s_nop 1
	v_add_f32_dpp v5, v5, v5 quad_perm:[1,0,3,2] row_mask:0xf bank_mask:0xf
	s_nop 1
	v_add_f32_dpp v5, v5, v5 quad_perm:[2,3,0,1] row_mask:0xf bank_mask:0xf
	s_nop 1
	v_add_f32_dpp v5, v5, v5 row_half_mirror row_mask:0xf bank_mask:0xf
	s_nop 1
	v_add_f32_dpp v5, v5, v5 row_mirror row_mask:0xf bank_mask:0xf
	s_nop 1
	v_add_f32_dpp v5, v5, v5 row_bcast:15 row_mask:0xa bank_mask:0xf
	s_nop 1
	v_add_f32_dpp v5, v5, v5 row_bcast:31 row_mask:0xc bank_mask:0xf
	s_nop 1
	v_readlane_b32 s32, v5, 63
	s_nop 1
	v_mov_b32_e32 v6, s32
	v_fmamk_f32 v6, v6, 0x3a800000, v146
	v_rsq_f32_e32 v6, v6
	s_nop 0
	v_mov_b32_e32 v10, v6
	v_pk_mul_f32 v[14:15], v[102:103], v[10:11] op_sel_hi:[1,0]
	v_pk_mul_f32 v[14:15], v[86:87], v[14:15]
	v_pk_fma_f32 v[16:17], v[70:71], v[14:15], v[54:55]
	v_pk_mul_f32 v[14:15], v[104:105], v[10:11] op_sel_hi:[1,0]
	v_pk_mul_f32 v[14:15], v[88:89], v[14:15]
	v_pk_fma_f32 v[18:19], v[72:73], v[14:15], v[56:57]
	v_cvt_pk_bf16_f32 v118, v16, v17
	v_cvt_pk_bf16_f32 v119, v18, v19
	v_pk_mul_f32 v[14:15], v[106:107], v[10:11] op_sel_hi:[1,0]
	v_pk_mul_f32 v[14:15], v[90:91], v[14:15]
	v_pk_fma_f32 v[16:17], v[74:75], v[14:15], v[58:59]
	v_pk_mul_f32 v[14:15], v[108:109], v[10:11] op_sel_hi:[1,0]
	v_pk_mul_f32 v[14:15], v[92:93], v[14:15]
	v_pk_fma_f32 v[18:19], v[76:77], v[14:15], v[60:61]
	v_cvt_pk_bf16_f32 v122, v16, v17
	v_cvt_pk_bf16_f32 v123, v18, v19
	v_pk_mul_f32 v[14:15], v[110:111], v[10:11] op_sel_hi:[1,0]
	v_pk_mul_f32 v[14:15], v[94:95], v[14:15]
	v_pk_fma_f32 v[16:17], v[78:79], v[14:15], v[62:63]
	v_pk_mul_f32 v[14:15], v[112:113], v[10:11] op_sel_hi:[1,0]
	v_pk_mul_f32 v[14:15], v[96:97], v[14:15]
	v_pk_fma_f32 v[18:19], v[80:81], v[14:15], v[64:65]
	v_cvt_pk_bf16_f32 v134, v16, v17
	v_cvt_pk_bf16_f32 v135, v18, v19
	v_pk_mul_f32 v[14:15], v[114:115], v[10:11] op_sel_hi:[1,0]
	v_pk_mul_f32 v[14:15], v[98:99], v[14:15]
	v_pk_fma_f32 v[16:17], v[82:83], v[14:15], v[66:67]
	v_pk_mul_f32 v[14:15], v[116:117], v[10:11] op_sel_hi:[1,0]
	v_pk_mul_f32 v[14:15], v[100:101], v[14:15]
	v_pk_fma_f32 v[18:19], v[84:85], v[14:15], v[68:69]
	v_cvt_pk_bf16_f32 v138, v16, v17
	v_cvt_pk_bf16_f32 v139, v18, v19
	global_store_dwordx4 v0, v[102:105], s[46:47] offset:0 sc1
	global_store_dwordx4 v0, v[106:109], s[46:47] offset:1024 sc1
	global_store_dwordx4 v0, v[110:113], s[46:47] offset:2048 sc1
	global_store_dwordx4 v0, v[114:117], s[46:47] offset:3072 sc1
	global_store_dwordx2 v1, v[118:119], s[62:63] offset:0 sc1
	global_store_dwordx2 v1, v[122:123], s[62:63] offset:512 sc1
	global_store_dwordx2 v1, v[134:135], s[62:63] offset:1024 sc1
	global_store_dwordx2 v1, v[138:139], s[62:63] offset:1536 sc1
	s_add_u32 s46, s46, 0x1000
	s_addc_u32 s47, s47, 0
	s_add_u32 s62, s62, 0x800
	s_addc_u32 s63, s63, 0
	s_nop 1
	global_load_dwordx4 v[102:105], v0, s[4:5] offset:0
	global_load_dwordx4 v[106:109], v0, s[4:5] offset:1024
	global_load_dwordx4 v[110:113], v0, s[4:5] offset:2048
	global_load_dwordx4 v[114:117], v0, s[4:5] offset:3072
	global_load_dwordx2 v[118:119], v1, s[58:59] offset:0
	global_load_dwordx2 v[122:123], v1, s[58:59] offset:512
	global_load_dwordx2 v[134:135], v1, s[58:59] offset:1024
	global_load_dwordx2 v[138:139], v1, s[58:59] offset:1536
	global_load_dwordx2 v[120:121], v1, s[60:61] offset:0
	global_load_dwordx2 v[124:125], v1, s[60:61] offset:512
	global_load_dwordx2 v[136:137], v1, s[60:61] offset:1024
	global_load_dwordx2 v[140:141], v1, s[60:61] offset:1536
	s_add_u32 s4, s4, 0x1000
	s_addc_u32 s5, s5, 0
	s_add_u32 s58, s58, 0x800
	s_addc_u32 s59, s59, 0
	s_add_u32 s60, s60, 0x800
	s_addc_u32 s61, s61, 0
	s_waitcnt vmcnt(32)
	v_lshlrev_b32_e32 v14, 16, v172
	v_and_b32_e32 v15, 0xffff0000, v172
	v_lshlrev_b32_e32 v16, 16, v174
	v_and_b32_e32 v17, 0xffff0000, v174
	v_lshlrev_b32_e32 v18, 16, v173
	v_and_b32_e32 v19, 0xffff0000, v173
	v_lshlrev_b32_e32 v20, 16, v175
	v_and_b32_e32 v21, 0xffff0000, v175
	v_pk_add_f32 v[172:173], v[14:15], v[16:17]
	v_pk_add_f32 v[174:175], v[18:19], v[20:21]
	v_lshlrev_b32_e32 v14, 16, v176
	v_and_b32_e32 v15, 0xffff0000, v176
	v_lshlrev_b32_e32 v16, 16, v178
	v_and_b32_e32 v17, 0xffff0000, v178
	v_lshlrev_b32_e32 v18, 16, v177
	v_and_b32_e32 v19, 0xffff0000, v177
	v_lshlrev_b32_e32 v20, 16, v179
	v_and_b32_e32 v21, 0xffff0000, v179
	v_pk_add_f32 v[176:177], v[14:15], v[16:17]
	v_pk_add_f32 v[178:179], v[18:19], v[20:21]
	v_lshlrev_b32_e32 v14, 16, v204
	v_and_b32_e32 v15, 0xffff0000, v204
	v_lshlrev_b32_e32 v16, 16, v206
	v_and_b32_e32 v17, 0xffff0000, v206
	v_lshlrev_b32_e32 v18, 16, v205
	v_and_b32_e32 v19, 0xffff0000, v205
	v_lshlrev_b32_e32 v20, 16, v207
	v_and_b32_e32 v21, 0xffff0000, v207
	v_pk_add_f32 v[204:205], v[14:15], v[16:17]
	v_pk_add_f32 v[206:207], v[18:19], v[20:21]
	v_lshlrev_b32_e32 v14, 16, v214
	v_and_b32_e32 v15, 0xffff0000, v214
	v_lshlrev_b32_e32 v16, 16, v216
	v_and_b32_e32 v17, 0xffff0000, v216
	v_lshlrev_b32_e32 v18, 16, v215
	v_and_b32_e32 v19, 0xffff0000, v215
	v_lshlrev_b32_e32 v20, 16, v217
	v_and_b32_e32 v21, 0xffff0000, v217
	v_pk_add_f32 v[214:215], v[14:15], v[16:17]
	v_pk_add_f32 v[216:217], v[18:19], v[20:21]
	v_pk_mul_f32 v[12:13], v[172:173], v[172:173]
	v_pk_fma_f32 v[12:13], v[174:175], v[174:175], v[12:13]
	v_pk_fma_f32 v[12:13], v[176:177], v[176:177], v[12:13]
	v_pk_fma_f32 v[12:13], v[178:179], v[178:179], v[12:13]
	v_pk_fma_f32 v[12:13], v[204:205], v[204:205], v[12:13]
	v_pk_fma_f32 v[12:13], v[206:207], v[206:207], v[12:13]
	v_pk_fma_f32 v[12:13], v[214:215], v[214:215], v[12:13]
	v_pk_fma_f32 v[12:13], v[216:217], v[216:217], v[12:13]
	v_add_f32_e32 v5, v12, v13
	s_nop 1
	v_add_f32_dpp v5, v5, v5 quad_perm:[1,0,3,2] row_mask:0xf bank_mask:0xf
	s_nop 1
	v_add_f32_dpp v5, v5, v5 quad_perm:[2,3,0,1] row_mask:0xf bank_mask:0xf
	s_nop 1
	v_add_f32_dpp v5, v5, v5 row_half_mirror row_mask:0xf bank_mask:0xf
	s_nop 1
	v_add_f32_dpp v5, v5, v5 row_mirror row_mask:0xf bank_mask:0xf
	s_nop 1
	v_add_f32_dpp v5, v5, v5 row_bcast:15 row_mask:0xa bank_mask:0xf
	s_nop 1
	v_add_f32_dpp v5, v5, v5 row_bcast:31 row_mask:0xc bank_mask:0xf
	s_nop 1
	v_readlane_b32 s32, v5, 63
	s_nop 1
	v_mov_b32_e32 v6, s32
	v_fmamk_f32 v6, v6, 0x3a800000, v146
	v_rsq_f32_e32 v6, v6
	s_nop 0
	v_mov_b32_e32 v8, v6
	v_pk_mul_f32 v[14:15], v[172:173], v[8:9] op_sel_hi:[1,0]
	v_pk_mul_f32 v[14:15], v[38:39], v[14:15]
	v_pk_fma_f32 v[154:155], v[22:23], v[14:15], v[154:155]
	v_pk_mul_f32 v[14:15], v[174:175], v[8:9] op_sel_hi:[1,0]
	v_pk_mul_f32 v[14:15], v[40:41], v[14:15]
	v_pk_fma_f32 v[156:157], v[24:25], v[14:15], v[156:157]
	v_pk_mul_f32 v[14:15], v[176:177], v[8:9] op_sel_hi:[1,0]
	v_pk_mul_f32 v[14:15], v[42:43], v[14:15]
	v_pk_fma_f32 v[158:159], v[26:27], v[14:15], v[158:159]
	v_pk_mul_f32 v[14:15], v[178:179], v[8:9] op_sel_hi:[1,0]
	v_pk_mul_f32 v[14:15], v[44:45], v[14:15]
	v_pk_fma_f32 v[160:161], v[28:29], v[14:15], v[160:161]
	v_pk_mul_f32 v[14:15], v[204:205], v[8:9] op_sel_hi:[1,0]
	v_pk_mul_f32 v[14:15], v[46:47], v[14:15]
	v_pk_fma_f32 v[162:163], v[30:31], v[14:15], v[162:163]
	v_pk_mul_f32 v[14:15], v[206:207], v[8:9] op_sel_hi:[1,0]
	v_pk_mul_f32 v[14:15], v[48:49], v[14:15]
	v_pk_fma_f32 v[164:165], v[32:33], v[14:15], v[164:165]
	v_pk_mul_f32 v[14:15], v[214:215], v[8:9] op_sel_hi:[1,0]
	v_pk_mul_f32 v[14:15], v[50:51], v[14:15]
	v_pk_fma_f32 v[168:169], v[34:35], v[14:15], v[168:169]
	v_pk_mul_f32 v[14:15], v[216:217], v[8:9] op_sel_hi:[1,0]
	v_pk_mul_f32 v[14:15], v[52:53], v[14:15]
	v_pk_fma_f32 v[170:171], v[36:37], v[14:15], v[170:171]
	v_pk_mul_f32 v[12:13], v[154:155], v[154:155]
	v_pk_fma_f32 v[12:13], v[156:157], v[156:157], v[12:13]
	v_pk_fma_f32 v[12:13], v[158:159], v[158:159], v[12:13]
	v_pk_fma_f32 v[12:13], v[160:161], v[160:161], v[12:13]
	v_pk_fma_f32 v[12:13], v[162:163], v[162:163], v[12:13]
	v_pk_fma_f32 v[12:13], v[164:165], v[164:165], v[12:13]
	v_pk_fma_f32 v[12:13], v[168:169], v[168:169], v[12:13]
	v_pk_fma_f32 v[12:13], v[170:171], v[170:171], v[12:13]
	v_add_f32_e32 v5, v12, v13
	s_nop 1
	v_add_f32_dpp v5, v5, v5 quad_perm:[1,0,3,2] row_mask:0xf bank_mask:0xf
	s_nop 1
	v_add_f32_dpp v5, v5, v5 quad_perm:[2,3,0,1] row_mask:0xf bank_mask:0xf
	s_nop 1
	v_add_f32_dpp v5, v5, v5 row_half_mirror row_mask:0xf bank_mask:0xf
	s_nop 1
	v_add_f32_dpp v5, v5, v5 row_mirror row_mask:0xf bank_mask:0xf
	s_nop 1
	v_add_f32_dpp v5, v5, v5 row_bcast:15 row_mask:0xa bank_mask:0xf
	s_nop 1
	v_add_f32_dpp v5, v5, v5 row_bcast:31 row_mask:0xc bank_mask:0xf
	s_nop 1
	v_readlane_b32 s32, v5, 63
	s_nop 1
	v_mov_b32_e32 v6, s32
	v_fmamk_f32 v6, v6, 0x3a800000, v146
	v_rsq_f32_e32 v6, v6
	s_nop 0
	v_mov_b32_e32 v10, v6
	v_pk_mul_f32 v[14:15], v[154:155], v[10:11] op_sel_hi:[1,0]
	v_pk_mul_f32 v[14:15], v[86:87], v[14:15]
	v_pk_fma_f32 v[16:17], v[70:71], v[14:15], v[54:55]
	v_pk_mul_f32 v[14:15], v[156:157], v[10:11] op_sel_hi:[1,0]
	v_pk_mul_f32 v[14:15], v[88:89], v[14:15]
	v_pk_fma_f32 v[18:19], v[72:73], v[14:15], v[56:57]
	v_cvt_pk_bf16_f32 v172, v16, v17
	v_cvt_pk_bf16_f32 v173, v18, v19
	v_pk_mul_f32 v[14:15], v[158:159], v[10:11] op_sel_hi:[1,0]
	v_pk_mul_f32 v[14:15], v[90:91], v[14:15]
	v_pk_fma_f32 v[16:17], v[74:75], v[14:15], v[58:59]
	v_pk_mul_f32 v[14:15], v[160:161], v[10:11] op_sel_hi:[1,0]
	v_pk_mul_f32 v[14:15], v[92:93], v[14:15]
	v_pk_fma_f32 v[18:19], v[76:77], v[14:15], v[60:61]
	v_cvt_pk_bf16_f32 v176, v16, v17
	v_cvt_pk_bf16_f32 v177, v18, v19
	v_pk_mul_f32 v[14:15], v[162:163], v[10:11] op_sel_hi:[1,0]
	v_pk_mul_f32 v[14:15], v[94:95], v[14:15]
	v_pk_fma_f32 v[16:17], v[78:79], v[14:15], v[62:63]
	v_pk_mul_f32 v[14:15], v[164:165], v[10:11] op_sel_hi:[1,0]
	v_pk_mul_f32 v[14:15], v[96:97], v[14:15]
	v_pk_fma_f32 v[18:19], v[80:81], v[14:15], v[64:65]
	v_cvt_pk_bf16_f32 v204, v16, v17
	v_cvt_pk_bf16_f32 v205, v18, v19
	v_pk_mul_f32 v[14:15], v[168:169], v[10:11] op_sel_hi:[1,0]
	v_pk_mul_f32 v[14:15], v[98:99], v[14:15]
	v_pk_fma_f32 v[16:17], v[82:83], v[14:15], v[66:67]
	v_pk_mul_f32 v[14:15], v[170:171], v[10:11] op_sel_hi:[1,0]
	v_pk_mul_f32 v[14:15], v[100:101], v[14:15]
	v_pk_fma_f32 v[18:19], v[84:85], v[14:15], v[68:69]
	v_cvt_pk_bf16_f32 v214, v16, v17
	v_cvt_pk_bf16_f32 v215, v18, v19
	global_store_dwordx4 v0, v[154:157], s[46:47] offset:0 sc1
	global_store_dwordx4 v0, v[158:161], s[46:47] offset:1024 sc1
	global_store_dwordx4 v0, v[162:165], s[46:47] offset:2048 sc1
	global_store_dwordx4 v0, v[168:171], s[46:47] offset:3072 sc1
	global_store_dwordx2 v1, v[172:173], s[62:63] offset:0 sc1
	global_store_dwordx2 v1, v[176:177], s[62:63] offset:512 sc1
	global_store_dwordx2 v1, v[204:205], s[62:63] offset:1024 sc1
	global_store_dwordx2 v1, v[214:215], s[62:63] offset:1536 sc1
	s_add_u32 s46, s46, 0x1000
	s_addc_u32 s47, s47, 0
	s_add_u32 s62, s62, 0x800
	s_addc_u32 s63, s63, 0
	s_waitcnt vmcnt(28)
	v_lshlrev_b32_e32 v14, 16, v234
	v_and_b32_e32 v15, 0xffff0000, v234
	v_lshlrev_b32_e32 v16, 16, v236
	v_and_b32_e32 v17, 0xffff0000, v236
	v_lshlrev_b32_e32 v18, 16, v235
	v_and_b32_e32 v19, 0xffff0000, v235
	v_lshlrev_b32_e32 v20, 16, v237
	v_and_b32_e32 v21, 0xffff0000, v237
	v_pk_add_f32 v[234:235], v[14:15], v[16:17]
	v_pk_add_f32 v[236:237], v[18:19], v[20:21]
	v_lshlrev_b32_e32 v14, 16, v238
	v_and_b32_e32 v15, 0xffff0000, v238
	v_lshlrev_b32_e32 v16, 16, v240
	v_and_b32_e32 v17, 0xffff0000, v240
	v_lshlrev_b32_e32 v18, 16, v239
	v_and_b32_e32 v19, 0xffff0000, v239
	v_lshlrev_b32_e32 v20, 16, v241
	v_and_b32_e32 v21, 0xffff0000, v241
	v_pk_add_f32 v[238:239], v[14:15], v[16:17]
	v_pk_add_f32 v[240:241], v[18:19], v[20:21]
	v_lshlrev_b32_e32 v14, 16, v242
	v_and_b32_e32 v15, 0xffff0000, v242
	v_lshlrev_b32_e32 v16, 16, v244
	v_and_b32_e32 v17, 0xffff0000, v244
	v_lshlrev_b32_e32 v18, 16, v243
	v_and_b32_e32 v19, 0xffff0000, v243
	v_lshlrev_b32_e32 v20, 16, v245
	v_and_b32_e32 v21, 0xffff0000, v245
	v_pk_add_f32 v[242:243], v[14:15], v[16:17]
	v_pk_add_f32 v[244:245], v[18:19], v[20:21]
	v_lshlrev_b32_e32 v14, 16, v246
	v_and_b32_e32 v15, 0xffff0000, v246
	v_lshlrev_b32_e32 v16, 16, v248
	v_and_b32_e32 v17, 0xffff0000, v248
	v_lshlrev_b32_e32 v18, 16, v247
	v_and_b32_e32 v19, 0xffff0000, v247
	v_lshlrev_b32_e32 v20, 16, v249
	v_and_b32_e32 v21, 0xffff0000, v249
	v_pk_add_f32 v[246:247], v[14:15], v[16:17]
	v_pk_add_f32 v[248:249], v[18:19], v[20:21]
	v_pk_mul_f32 v[12:13], v[234:235], v[234:235]
	v_pk_fma_f32 v[12:13], v[236:237], v[236:237], v[12:13]
	v_pk_fma_f32 v[12:13], v[238:239], v[238:239], v[12:13]
	v_pk_fma_f32 v[12:13], v[240:241], v[240:241], v[12:13]
	v_pk_fma_f32 v[12:13], v[242:243], v[242:243], v[12:13]
	v_pk_fma_f32 v[12:13], v[244:245], v[244:245], v[12:13]
	v_pk_fma_f32 v[12:13], v[246:247], v[246:247], v[12:13]
	v_pk_fma_f32 v[12:13], v[248:249], v[248:249], v[12:13]
	v_add_f32_e32 v5, v12, v13
	s_nop 1
	v_add_f32_dpp v5, v5, v5 quad_perm:[1,0,3,2] row_mask:0xf bank_mask:0xf
	s_nop 1
	v_add_f32_dpp v5, v5, v5 quad_perm:[2,3,0,1] row_mask:0xf bank_mask:0xf
	s_nop 1
	v_add_f32_dpp v5, v5, v5 row_half_mirror row_mask:0xf bank_mask:0xf
	s_nop 1
	v_add_f32_dpp v5, v5, v5 row_mirror row_mask:0xf bank_mask:0xf
	s_nop 1
	v_add_f32_dpp v5, v5, v5 row_bcast:15 row_mask:0xa bank_mask:0xf
	s_nop 1
	v_add_f32_dpp v5, v5, v5 row_bcast:31 row_mask:0xc bank_mask:0xf
	s_nop 1
	v_readlane_b32 s32, v5, 63
	s_nop 1
	v_mov_b32_e32 v6, s32
	v_fmamk_f32 v6, v6, 0x3a800000, v146
	v_rsq_f32_e32 v6, v6
	s_nop 0
	v_mov_b32_e32 v8, v6
	v_pk_mul_f32 v[14:15], v[234:235], v[8:9] op_sel_hi:[1,0]
	v_pk_mul_f32 v[14:15], v[38:39], v[14:15]
	v_pk_fma_f32 v[218:219], v[22:23], v[14:15], v[218:219]
	v_pk_mul_f32 v[14:15], v[236:237], v[8:9] op_sel_hi:[1,0]
	v_pk_mul_f32 v[14:15], v[40:41], v[14:15]
	v_pk_fma_f32 v[220:221], v[24:25], v[14:15], v[220:221]
	v_pk_mul_f32 v[14:15], v[238:239], v[8:9] op_sel_hi:[1,0]
	v_pk_mul_f32 v[14:15], v[42:43], v[14:15]
	v_pk_fma_f32 v[222:223], v[26:27], v[14:15], v[222:223]
	v_pk_mul_f32 v[14:15], v[240:241], v[8:9] op_sel_hi:[1,0]
	v_pk_mul_f32 v[14:15], v[44:45], v[14:15]
	v_pk_fma_f32 v[224:225], v[28:29], v[14:15], v[224:225]
	v_pk_mul_f32 v[14:15], v[242:243], v[8:9] op_sel_hi:[1,0]
	v_pk_mul_f32 v[14:15], v[46:47], v[14:15]
	v_pk_fma_f32 v[226:227], v[30:31], v[14:15], v[226:227]
	v_pk_mul_f32 v[14:15], v[244:245], v[8:9] op_sel_hi:[1,0]
	v_pk_mul_f32 v[14:15], v[48:49], v[14:15]
	v_pk_fma_f32 v[228:229], v[32:33], v[14:15], v[228:229]
	v_pk_mul_f32 v[14:15], v[246:247], v[8:9] op_sel_hi:[1,0]
	v_pk_mul_f32 v[14:15], v[50:51], v[14:15]
	v_pk_fma_f32 v[230:231], v[34:35], v[14:15], v[230:231]
	v_pk_mul_f32 v[14:15], v[248:249], v[8:9] op_sel_hi:[1,0]
	v_pk_mul_f32 v[14:15], v[52:53], v[14:15]
	v_pk_fma_f32 v[232:233], v[36:37], v[14:15], v[232:233]
	v_pk_mul_f32 v[12:13], v[218:219], v[218:219]
	v_pk_fma_f32 v[12:13], v[220:221], v[220:221], v[12:13]
	v_pk_fma_f32 v[12:13], v[222:223], v[222:223], v[12:13]
	v_pk_fma_f32 v[12:13], v[224:225], v[224:225], v[12:13]
	v_pk_fma_f32 v[12:13], v[226:227], v[226:227], v[12:13]
	v_pk_fma_f32 v[12:13], v[228:229], v[228:229], v[12:13]
	v_pk_fma_f32 v[12:13], v[230:231], v[230:231], v[12:13]
	v_pk_fma_f32 v[12:13], v[232:233], v[232:233], v[12:13]
	v_add_f32_e32 v5, v12, v13
	s_nop 1
	v_add_f32_dpp v5, v5, v5 quad_perm:[1,0,3,2] row_mask:0xf bank_mask:0xf
	s_nop 1
	v_add_f32_dpp v5, v5, v5 quad_perm:[2,3,0,1] row_mask:0xf bank_mask:0xf
	s_nop 1
	v_add_f32_dpp v5, v5, v5 row_half_mirror row_mask:0xf bank_mask:0xf
	s_nop 1
	v_add_f32_dpp v5, v5, v5 row_mirror row_mask:0xf bank_mask:0xf
	s_nop 1
	v_add_f32_dpp v5, v5, v5 row_bcast:15 row_mask:0xa bank_mask:0xf
	s_nop 1
	v_add_f32_dpp v5, v5, v5 row_bcast:31 row_mask:0xc bank_mask:0xf
	s_nop 1
	v_readlane_b32 s32, v5, 63
	s_nop 1
	v_mov_b32_e32 v6, s32
	v_fmamk_f32 v6, v6, 0x3a800000, v146
	v_rsq_f32_e32 v6, v6
	s_nop 0
	v_mov_b32_e32 v10, v6
	v_pk_mul_f32 v[14:15], v[218:219], v[10:11] op_sel_hi:[1,0]
	v_pk_mul_f32 v[14:15], v[86:87], v[14:15]
	v_pk_fma_f32 v[16:17], v[70:71], v[14:15], v[54:55]
	v_pk_mul_f32 v[14:15], v[220:221], v[10:11] op_sel_hi:[1,0]
	v_pk_mul_f32 v[14:15], v[88:89], v[14:15]
	v_pk_fma_f32 v[18:19], v[72:73], v[14:15], v[56:57]
	v_cvt_pk_bf16_f32 v234, v16, v17
	v_cvt_pk_bf16_f32 v235, v18, v19
	v_pk_mul_f32 v[14:15], v[222:223], v[10:11] op_sel_hi:[1,0]
	v_pk_mul_f32 v[14:15], v[90:91], v[14:15]
	v_pk_fma_f32 v[16:17], v[74:75], v[14:15], v[58:59]
	v_pk_mul_f32 v[14:15], v[224:225], v[10:11] op_sel_hi:[1,0]
	v_pk_mul_f32 v[14:15], v[92:93], v[14:15]
	v_pk_fma_f32 v[18:19], v[76:77], v[14:15], v[60:61]
	v_cvt_pk_bf16_f32 v238, v16, v17
	v_cvt_pk_bf16_f32 v239, v18, v19
	v_pk_mul_f32 v[14:15], v[226:227], v[10:11] op_sel_hi:[1,0]
	v_pk_mul_f32 v[14:15], v[94:95], v[14:15]
	v_pk_fma_f32 v[16:17], v[78:79], v[14:15], v[62:63]
	v_pk_mul_f32 v[14:15], v[228:229], v[10:11] op_sel_hi:[1,0]
	v_pk_mul_f32 v[14:15], v[96:97], v[14:15]
	v_pk_fma_f32 v[18:19], v[80:81], v[14:15], v[64:65]
	v_cvt_pk_bf16_f32 v242, v16, v17
	v_cvt_pk_bf16_f32 v243, v18, v19
	v_pk_mul_f32 v[14:15], v[230:231], v[10:11] op_sel_hi:[1,0]
	v_pk_mul_f32 v[14:15], v[98:99], v[14:15]
	v_pk_fma_f32 v[16:17], v[82:83], v[14:15], v[66:67]
	v_pk_mul_f32 v[14:15], v[232:233], v[10:11] op_sel_hi:[1,0]
	v_pk_mul_f32 v[14:15], v[100:101], v[14:15]
	v_pk_fma_f32 v[18:19], v[84:85], v[14:15], v[68:69]
	v_cvt_pk_bf16_f32 v246, v16, v17
	v_cvt_pk_bf16_f32 v247, v18, v19
	global_store_dwordx4 v0, v[218:221], s[46:47] offset:0 sc1
	global_store_dwordx4 v0, v[222:225], s[46:47] offset:1024 sc1
	global_store_dwordx4 v0, v[226:229], s[46:47] offset:2048 sc1
	global_store_dwordx4 v0, v[230:233], s[46:47] offset:3072 sc1
	global_store_dwordx2 v1, v[234:235], s[62:63] offset:0 sc1
	global_store_dwordx2 v1, v[238:239], s[62:63] offset:512 sc1
	global_store_dwordx2 v1, v[242:243], s[62:63] offset:1024 sc1
	global_store_dwordx2 v1, v[246:247], s[62:63] offset:1536 sc1
	s_add_u32 s46, s46, 0x1000
	s_addc_u32 s47, s47, 0
	s_add_u32 s62, s62, 0x800
	s_addc_u32 s63, s63, 0
	s_waitcnt vmcnt(16)
	v_lshlrev_b32_e32 v14, 16, v118
	v_and_b32_e32 v15, 0xffff0000, v118
	v_lshlrev_b32_e32 v16, 16, v120
	v_and_b32_e32 v17, 0xffff0000, v120
	v_lshlrev_b32_e32 v18, 16, v119
	v_and_b32_e32 v19, 0xffff0000, v119
	v_lshlrev_b32_e32 v20, 16, v121
	v_and_b32_e32 v21, 0xffff0000, v121
	v_pk_add_f32 v[118:119], v[14:15], v[16:17]
	v_pk_add_f32 v[120:121], v[18:19], v[20:21]
	v_lshlrev_b32_e32 v14, 16, v122
	v_and_b32_e32 v15, 0xffff0000, v122
	v_lshlrev_b32_e32 v16, 16, v124
	v_and_b32_e32 v17, 0xffff0000, v124
	v_lshlrev_b32_e32 v18, 16, v123
	v_and_b32_e32 v19, 0xffff0000, v123
	v_lshlrev_b32_e32 v20, 16, v125
	v_and_b32_e32 v21, 0xffff0000, v125
	v_pk_add_f32 v[122:123], v[14:15], v[16:17]
	v_pk_add_f32 v[124:125], v[18:19], v[20:21]
	v_lshlrev_b32_e32 v14, 16, v134
	v_and_b32_e32 v15, 0xffff0000, v134
	v_lshlrev_b32_e32 v16, 16, v136
	v_and_b32_e32 v17, 0xffff0000, v136
	v_lshlrev_b32_e32 v18, 16, v135
	v_and_b32_e32 v19, 0xffff0000, v135
	v_lshlrev_b32_e32 v20, 16, v137
	v_and_b32_e32 v21, 0xffff0000, v137
	v_pk_add_f32 v[134:135], v[14:15], v[16:17]
	v_pk_add_f32 v[136:137], v[18:19], v[20:21]
	v_lshlrev_b32_e32 v14, 16, v138
	v_and_b32_e32 v15, 0xffff0000, v138
	v_lshlrev_b32_e32 v16, 16, v140
	v_and_b32_e32 v17, 0xffff0000, v140
	v_lshlrev_b32_e32 v18, 16, v139
	v_and_b32_e32 v19, 0xffff0000, v139
	v_lshlrev_b32_e32 v20, 16, v141
	v_and_b32_e32 v21, 0xffff0000, v141
	v_pk_add_f32 v[138:139], v[14:15], v[16:17]
	v_pk_add_f32 v[140:141], v[18:19], v[20:21]
	v_pk_mul_f32 v[12:13], v[118:119], v[118:119]
	v_pk_fma_f32 v[12:13], v[120:121], v[120:121], v[12:13]
	v_pk_fma_f32 v[12:13], v[122:123], v[122:123], v[12:13]
	v_pk_fma_f32 v[12:13], v[124:125], v[124:125], v[12:13]
	v_pk_fma_f32 v[12:13], v[134:135], v[134:135], v[12:13]
	v_pk_fma_f32 v[12:13], v[136:137], v[136:137], v[12:13]
	v_pk_fma_f32 v[12:13], v[138:139], v[138:139], v[12:13]
	v_pk_fma_f32 v[12:13], v[140:141], v[140:141], v[12:13]
	v_add_f32_e32 v5, v12, v13
	s_nop 1
	v_add_f32_dpp v5, v5, v5 quad_perm:[1,0,3,2] row_mask:0xf bank_mask:0xf
	s_nop 1
	v_add_f32_dpp v5, v5, v5 quad_perm:[2,3,0,1] row_mask:0xf bank_mask:0xf
	s_nop 1
	v_add_f32_dpp v5, v5, v5 row_half_mirror row_mask:0xf bank_mask:0xf
	s_nop 1
	v_add_f32_dpp v5, v5, v5 row_mirror row_mask:0xf bank_mask:0xf
	s_nop 1
	v_add_f32_dpp v5, v5, v5 row_bcast:15 row_mask:0xa bank_mask:0xf
	s_nop 1
	v_add_f32_dpp v5, v5, v5 row_bcast:31 row_mask:0xc bank_mask:0xf
	s_nop 1
	v_readlane_b32 s32, v5, 63
	s_nop 1
	v_mov_b32_e32 v6, s32
	v_fmamk_f32 v6, v6, 0x3a800000, v146
	v_rsq_f32_e32 v6, v6
	s_nop 0
	v_mov_b32_e32 v8, v6
	v_pk_mul_f32 v[14:15], v[118:119], v[8:9] op_sel_hi:[1,0]
	v_pk_mul_f32 v[14:15], v[38:39], v[14:15]
	v_pk_fma_f32 v[102:103], v[22:23], v[14:15], v[102:103]
	v_pk_mul_f32 v[14:15], v[120:121], v[8:9] op_sel_hi:[1,0]
	v_pk_mul_f32 v[14:15], v[40:41], v[14:15]
	v_pk_fma_f32 v[104:105], v[24:25], v[14:15], v[104:105]
	v_pk_mul_f32 v[14:15], v[122:123], v[8:9] op_sel_hi:[1,0]
	v_pk_mul_f32 v[14:15], v[42:43], v[14:15]
	v_pk_fma_f32 v[106:107], v[26:27], v[14:15], v[106:107]
	v_pk_mul_f32 v[14:15], v[124:125], v[8:9] op_sel_hi:[1,0]
	v_pk_mul_f32 v[14:15], v[44:45], v[14:15]
	v_pk_fma_f32 v[108:109], v[28:29], v[14:15], v[108:109]
	v_pk_mul_f32 v[14:15], v[134:135], v[8:9] op_sel_hi:[1,0]
	v_pk_mul_f32 v[14:15], v[46:47], v[14:15]
	v_pk_fma_f32 v[110:111], v[30:31], v[14:15], v[110:111]
	v_pk_mul_f32 v[14:15], v[136:137], v[8:9] op_sel_hi:[1,0]
	v_pk_mul_f32 v[14:15], v[48:49], v[14:15]
	v_pk_fma_f32 v[112:113], v[32:33], v[14:15], v[112:113]
	v_pk_mul_f32 v[14:15], v[138:139], v[8:9] op_sel_hi:[1,0]
	v_pk_mul_f32 v[14:15], v[50:51], v[14:15]
	v_pk_fma_f32 v[114:115], v[34:35], v[14:15], v[114:115]
	v_pk_mul_f32 v[14:15], v[140:141], v[8:9] op_sel_hi:[1,0]
	v_pk_mul_f32 v[14:15], v[52:53], v[14:15]
	v_pk_fma_f32 v[116:117], v[36:37], v[14:15], v[116:117]
	v_pk_mul_f32 v[12:13], v[102:103], v[102:103]
	v_pk_fma_f32 v[12:13], v[104:105], v[104:105], v[12:13]
	v_pk_fma_f32 v[12:13], v[106:107], v[106:107], v[12:13]
	v_pk_fma_f32 v[12:13], v[108:109], v[108:109], v[12:13]
	v_pk_fma_f32 v[12:13], v[110:111], v[110:111], v[12:13]
	v_pk_fma_f32 v[12:13], v[112:113], v[112:113], v[12:13]
	v_pk_fma_f32 v[12:13], v[114:115], v[114:115], v[12:13]
	v_pk_fma_f32 v[12:13], v[116:117], v[116:117], v[12:13]
	v_add_f32_e32 v5, v12, v13
	s_nop 1
	v_add_f32_dpp v5, v5, v5 quad_perm:[1,0,3,2] row_mask:0xf bank_mask:0xf
	s_nop 1
	v_add_f32_dpp v5, v5, v5 quad_perm:[2,3,0,1] row_mask:0xf bank_mask:0xf
	s_nop 1
	v_add_f32_dpp v5, v5, v5 row_half_mirror row_mask:0xf bank_mask:0xf
	s_nop 1
	v_add_f32_dpp v5, v5, v5 row_mirror row_mask:0xf bank_mask:0xf
	s_nop 1
	v_add_f32_dpp v5, v5, v5 row_bcast:15 row_mask:0xa bank_mask:0xf
	s_nop 1
	v_add_f32_dpp v5, v5, v5 row_bcast:31 row_mask:0xc bank_mask:0xf
	s_nop 1
	v_readlane_b32 s32, v5, 63
	s_nop 1
	v_mov_b32_e32 v6, s32
	v_fmamk_f32 v6, v6, 0x3a800000, v146
	v_rsq_f32_e32 v6, v6
	s_nop 0
	v_mov_b32_e32 v10, v6
	v_pk_mul_f32 v[14:15], v[102:103], v[10:11] op_sel_hi:[1,0]
	v_pk_mul_f32 v[14:15], v[86:87], v[14:15]
	v_pk_fma_f32 v[16:17], v[70:71], v[14:15], v[54:55]
	v_pk_mul_f32 v[14:15], v[104:105], v[10:11] op_sel_hi:[1,0]
	v_pk_mul_f32 v[14:15], v[88:89], v[14:15]
	v_pk_fma_f32 v[18:19], v[72:73], v[14:15], v[56:57]
	v_cvt_pk_bf16_f32 v118, v16, v17
	v_cvt_pk_bf16_f32 v119, v18, v19
	v_pk_mul_f32 v[14:15], v[106:107], v[10:11] op_sel_hi:[1,0]
	v_pk_mul_f32 v[14:15], v[90:91], v[14:15]
	v_pk_fma_f32 v[16:17], v[74:75], v[14:15], v[58:59]
	v_pk_mul_f32 v[14:15], v[108:109], v[10:11] op_sel_hi:[1,0]
	v_pk_mul_f32 v[14:15], v[92:93], v[14:15]
	v_pk_fma_f32 v[18:19], v[76:77], v[14:15], v[60:61]
	v_cvt_pk_bf16_f32 v122, v16, v17
	v_cvt_pk_bf16_f32 v123, v18, v19
	v_pk_mul_f32 v[14:15], v[110:111], v[10:11] op_sel_hi:[1,0]
	v_pk_mul_f32 v[14:15], v[94:95], v[14:15]
	v_pk_fma_f32 v[16:17], v[78:79], v[14:15], v[62:63]
	v_pk_mul_f32 v[14:15], v[112:113], v[10:11] op_sel_hi:[1,0]
	v_pk_mul_f32 v[14:15], v[96:97], v[14:15]
	v_pk_fma_f32 v[18:19], v[80:81], v[14:15], v[64:65]
	v_cvt_pk_bf16_f32 v134, v16, v17
	v_cvt_pk_bf16_f32 v135, v18, v19
	v_pk_mul_f32 v[14:15], v[114:115], v[10:11] op_sel_hi:[1,0]
	v_pk_mul_f32 v[14:15], v[98:99], v[14:15]
	v_pk_fma_f32 v[16:17], v[82:83], v[14:15], v[66:67]
	v_pk_mul_f32 v[14:15], v[116:117], v[10:11] op_sel_hi:[1,0]
	v_pk_mul_f32 v[14:15], v[100:101], v[14:15]
	v_pk_fma_f32 v[18:19], v[84:85], v[14:15], v[68:69]
	v_cvt_pk_bf16_f32 v138, v16, v17
	v_cvt_pk_bf16_f32 v139, v18, v19
	global_store_dwordx4 v0, v[102:105], s[46:47] offset:0 sc1
	global_store_dwordx4 v0, v[106:109], s[46:47] offset:1024 sc1
	global_store_dwordx4 v0, v[110:113], s[46:47] offset:2048 sc1
	global_store_dwordx4 v0, v[114:117], s[46:47] offset:3072 sc1
	global_store_dwordx2 v1, v[118:119], s[62:63] offset:0 sc1
	global_store_dwordx2 v1, v[122:123], s[62:63] offset:512 sc1
	global_store_dwordx2 v1, v[134:135], s[62:63] offset:1024 sc1
	global_store_dwordx2 v1, v[138:139], s[62:63] offset:1536 sc1
	s_add_u32 s46, s46, 0x1000
	s_addc_u32 s47, s47, 0
	s_add_u32 s62, s62, 0x800
	s_addc_u32 s63, s63, 0

.Lxb_noinv_8:
	v_cmp_eq_u32_e32 vcc, 0, v0
	s_and_saveexec_b64 s[4:5], vcc
	s_cbranch_execz .LBB0_334
	s_load_dwordx2 s[12:13], s[8:9], 0x98
	v_readlane_b32 s14, v255, 0
	v_readlane_b32 s15, v255, 47
	s_nop 0
	s_lshr_b32 s24, s14, 3
	s_and_b32 s24, s24, 7
	s_and_b32 s27, s14, 6
	s_lshl_b32 s27, s27, 2
	s_or_b32 s27, s27, s24
	s_and_b32 s30, s14, 3
	s_lshl_b32 s30, s30, 3
	s_or_b32 s30, s30, s24
	s_lshl_b32 s27, s27, 7
	s_add_u32 s27, s27, 0xb000
	s_add_u32 s15, s15, 8
	v_writelane_b32 v255, s15, 47
	v_mov_b32_e32 v0, s27
	s_waitcnt lgkmcnt(0)
	global_atomic_add v0, v189, s[12:13]
	v_mov_b32_e32 v7, s27
	s_mov_b32 s32, 0

.LBB0_1276:
	v_readlane_b32 s2, v255, 0
	s_nop 0
	v_ashrrev_i32_e32 v0, 6, v147
	v_lshl_add_u32 v32, s2, 3, v0
	s_movk_i32 s2, 0x2000
	v_cmp_gt_i32_e32 vcc, s2, v32
	s_and_saveexec_b64 s[2:3], vcc
	s_cbranch_execz .LBB0_1279
	v_readlane_b32 s2, v255, 0
	v_readfirstlane_b32 s7, v147
	s_load_dwordx2 s[4:5], s[0:1], 0x90
	s_load_dwordx2 s[12:13], s[0:1], 0x98
	s_load_dwordx2 s[40:41], s[0:1], 0x48
	v_and_b32_e32 v0, 63, v147
	v_lshlrev_b32_e32 v1, 3, v0
	v_lshlrev_b32_e32 v0, 4, v0
	s_lshr_b32 s7, s7, 6
	s_and_b32 s27, s2, 6
	s_lshl_b32 s27, s27, 5
	s_and_b32 s37, s2, 0x39
	s_or_b32 s27, s27, s37
	s_lshr_b32 s37, s2, 6
	s_lshl_b32 s37, s37, 1
	s_or_b32 s2, s27, s37
	s_lshl_b32 s2, s2, 3
	s_add_u32 s2, s2, s7
	s_lshl_b32 s24, s2, 2
	s_sub_u32 s27, s24, 0x1000
	s_lshr_b32 s27, s27, 10
	s_add_u32 s27, s27, 1
	s_cmp_lt_u32 s24, 0x1000
	s_cselect_b32 s30, 0, s27
	v_add_u32_e32 v2, 0x8000, v0
	v_mov_b32_e32 v3, v0
	v_add_u32_e32 v4, 0x1000, v0
	s_waitcnt lgkmcnt(0)
	s_lshl_b32 s27, s24, 11
	s_add_u32 s62, s12, s27
	s_addc_u32 s63, s13, 0
	s_add_u32 s58, s62, 0x8800000
	s_addc_u32 s59, s63, 0
	s_add_u32 s60, s58, 0x1000000
	s_addc_u32 s61, s59, 0
	s_add_u32 s62, s62, 0x1000000
	s_addc_u32 s63, s63, 0
	s_lshl_b32 s27, s24, 12
	s_add_u32 s46, s4, s27
	s_addc_u32 s47, s5, 0
	s_mov_b64 s[4:5], s[46:47]
	s_add_u32 s27, s30, 15
	s_mul_i32 s27, s27, 0x9000
	s_add_u32 s27, s27, 0x100000
	s_add_u32 s88, s12, s27
	s_addc_u32 s89, s13, 0
	s_mov_b64 s[100:101], s[88:89]
	s_mov_b32 s27, 0xb000
	s_add_u32 s40, s40, s27
	s_addc_u32 s41, s41, 0
	global_load_dwordx4 v[22:25], v2, s[100:101] offset:0
	global_load_dwordx4 v[38:41], v0, s[40:41] offset:0
	global_load_dwordx4 v[26:29], v2, s[100:101] offset:1024
	global_load_dwordx4 v[42:45], v0, s[40:41] offset:1024
	global_load_dwordx4 v[30:33], v2, s[100:101] offset:2048
	global_load_dwordx4 v[46:49], v0, s[40:41] offset:2048
	global_load_dwordx4 v[34:37], v2, s[100:101] offset:3072
	global_load_dwordx4 v[50:53], v0, s[40:41] offset:3072
	global_load_dwordx4 v[54:57], v0, s[4:5] offset:0
	global_load_dwordx4 v[58:61], v0, s[4:5] offset:1024
	global_load_dwordx4 v[62:65], v0, s[4:5] offset:2048
	global_load_dwordx4 v[66:69], v0, s[4:5] offset:3072
	global_load_dwordx2 v[70:71], v1, s[58:59] offset:0
	global_load_dwordx2 v[74:75], v1, s[58:59] offset:512
	global_load_dwordx2 v[78:79], v1, s[58:59] offset:1024
	global_load_dwordx2 v[82:83], v1, s[58:59] offset:1536
	global_load_dwordx2 v[72:73], v1, s[60:61] offset:0
	global_load_dwordx2 v[76:77], v1, s[60:61] offset:512
	global_load_dwordx2 v[80:81], v1, s[60:61] offset:1024
	global_load_dwordx2 v[84:85], v1, s[60:61] offset:1536
	s_add_u32 s4, s4, 0x1000
	s_addc_u32 s5, s5, 0
	s_add_u32 s58, s58, 0x800
	s_addc_u32 s59, s59, 0
	s_add_u32 s60, s60, 0x800
	s_addc_u32 s61, s61, 0
	global_load_dwordx4 v[86:89], v0, s[4:5] offset:0
	global_load_dwordx4 v[90:93], v0, s[4:5] offset:1024
	global_load_dwordx4 v[94:97], v0, s[4:5] offset:2048
	global_load_dwordx4 v[98:101], v0, s[4:5] offset:3072
	global_load_dwordx2 v[102:103], v1, s[58:59] offset:0
	global_load_dwordx2 v[106:107], v1, s[58:59] offset:512
	global_load_dwordx2 v[110:111], v1, s[58:59] offset:1024
	global_load_dwordx2 v[114:115], v1, s[58:59] offset:1536
	global_load_dwordx2 v[104:105], v1, s[60:61] offset:0
	global_load_dwordx2 v[108:109], v1, s[60:61] offset:512
	global_load_dwordx2 v[112:113], v1, s[60:61] offset:1024
	global_load_dwordx2 v[116:117], v1, s[60:61] offset:1536
	s_add_u32 s4, s4, 0x1000
	s_addc_u32 s5, s5, 0
	s_add_u32 s58, s58, 0x800
	s_addc_u32 s59, s59, 0
	s_add_u32 s60, s60, 0x800
	s_addc_u32 s61, s61, 0
	global_load_dwordx4 v[118:121], v0, s[4:5] offset:0
	global_load_dwordx4 v[122:125], v0, s[4:5] offset:1024
	global_load_dwordx4 v[134:137], v0, s[4:5] offset:2048
	global_load_dwordx4 v[138:141], v0, s[4:5] offset:3072
	global_load_dwordx2 v[154:155], v1, s[58:59] offset:0
	global_load_dwordx2 v[158:159], v1, s[58:59] offset:512
	global_load_dwordx2 v[162:163], v1, s[58:59] offset:1024
	global_load_dwordx2 v[168:169], v1, s[58:59] offset:1536
	global_load_dwordx2 v[156:157], v1, s[60:61] offset:0
	global_load_dwordx2 v[160:161], v1, s[60:61] offset:512
	global_load_dwordx2 v[164:165], v1, s[60:61] offset:1024
	global_load_dwordx2 v[170:171], v1, s[60:61] offset:1536
	s_add_u32 s4, s4, 0x1000
	s_addc_u32 s5, s5, 0
	s_add_u32 s58, s58, 0x800
	s_addc_u32 s59, s59, 0
	s_add_u32 s60, s60, 0x800
	s_addc_u32 s61, s61, 0
	s_waitcnt vmcnt(24)
	v_lshlrev_b32_e32 v14, 16, v70
	v_and_b32_e32 v15, 0xffff0000, v70
	v_lshlrev_b32_e32 v16, 16, v72
	v_and_b32_e32 v17, 0xffff0000, v72
	v_lshlrev_b32_e32 v18, 16, v71
	v_and_b32_e32 v19, 0xffff0000, v71
	v_lshlrev_b32_e32 v20, 16, v73
	v_and_b32_e32 v21, 0xffff0000, v73
	v_pk_add_f32 v[70:71], v[14:15], v[16:17]
	v_pk_add_f32 v[72:73], v[18:19], v[20:21]
	v_lshlrev_b32_e32 v14, 16, v74
	v_and_b32_e32 v15, 0xffff0000, v74
	v_lshlrev_b32_e32 v16, 16, v76
	v_and_b32_e32 v17, 0xffff0000, v76
	v_lshlrev_b32_e32 v18, 16, v75
	v_and_b32_e32 v19, 0xffff0000, v75
	v_lshlrev_b32_e32 v20, 16, v77
	v_and_b32_e32 v21, 0xffff0000, v77
	v_pk_add_f32 v[74:75], v[14:15], v[16:17]
	v_pk_add_f32 v[76:77], v[18:19], v[20:21]
	v_lshlrev_b32_e32 v14, 16, v78
	v_and_b32_e32 v15, 0xffff0000, v78
	v_lshlrev_b32_e32 v16, 16, v80
	v_and_b32_e32 v17, 0xffff0000, v80
	v_lshlrev_b32_e32 v18, 16, v79
	v_and_b32_e32 v19, 0xffff0000, v79
	v_lshlrev_b32_e32 v20, 16, v81
	v_and_b32_e32 v21, 0xffff0000, v81
	v_pk_add_f32 v[78:79], v[14:15], v[16:17]
	v_pk_add_f32 v[80:81], v[18:19], v[20:21]
	v_lshlrev_b32_e32 v14, 16, v82
	v_and_b32_e32 v15, 0xffff0000, v82
	v_lshlrev_b32_e32 v16, 16, v84
	v_and_b32_e32 v17, 0xffff0000, v84
	v_lshlrev_b32_e32 v18, 16, v83
	v_and_b32_e32 v19, 0xffff0000, v83
	v_lshlrev_b32_e32 v20, 16, v85
	v_and_b32_e32 v21, 0xffff0000, v85
	v_pk_add_f32 v[82:83], v[14:15], v[16:17]
	v_pk_add_f32 v[84:85], v[18:19], v[20:21]
	v_pk_mul_f32 v[12:13], v[70:71], v[70:71]
	v_pk_fma_f32 v[12:13], v[72:73], v[72:73], v[12:13]
	v_pk_fma_f32 v[12:13], v[74:75], v[74:75], v[12:13]
	v_pk_fma_f32 v[12:13], v[76:77], v[76:77], v[12:13]
	v_pk_fma_f32 v[12:13], v[78:79], v[78:79], v[12:13]
	v_pk_fma_f32 v[12:13], v[80:81], v[80:81], v[12:13]
	v_pk_fma_f32 v[12:13], v[82:83], v[82:83], v[12:13]
	v_pk_fma_f32 v[12:13], v[84:85], v[84:85], v[12:13]
	v_add_f32_e32 v5, v12, v13
	s_nop 1
	v_add_f32_dpp v5, v5, v5 quad_perm:[1,0,3,2] row_mask:0xf bank_mask:0xf
	s_nop 1
	v_add_f32_dpp v5, v5, v5 quad_perm:[2,3,0,1] row_mask:0xf bank_mask:0xf
	s_nop 1
	v_add_f32_dpp v5, v5, v5 row_half_mirror row_mask:0xf bank_mask:0xf
	s_nop 1
	v_add_f32_dpp v5, v5, v5 row_mirror row_mask:0xf bank_mask:0xf
	s_nop 1
	v_add_f32_dpp v5, v5, v5 row_bcast:15 row_mask:0xa bank_mask:0xf
	s_nop 1
	v_add_f32_dpp v5, v5, v5 row_bcast:31 row_mask:0xc bank_mask:0xf
	s_nop 1
	v_readlane_b32 s32, v5, 63
	s_nop 1
	v_mov_b32_e32 v6, s32
	v_fmamk_f32 v6, v6, 0x3a800000, v146
	v_rsq_f32_e32 v6, v6
	s_nop 0
	v_mul_f32_e32 v8, 0.5, v6
	v_pk_mul_f32 v[14:15], v[70:71], v[8:9] op_sel_hi:[1,0]
	v_pk_mul_f32 v[14:15], v[38:39], v[14:15]
	v_pk_fma_f32 v[54:55], v[22:23], v[14:15], v[54:55]
	v_pk_mul_f32 v[14:15], v[72:73], v[8:9] op_sel_hi:[1,0]
	v_pk_mul_f32 v[14:15], v[40:41], v[14:15]
	v_pk_fma_f32 v[56:57], v[24:25], v[14:15], v[56:57]
	v_pk_mul_f32 v[14:15], v[74:75], v[8:9] op_sel_hi:[1,0]
	v_pk_mul_f32 v[14:15], v[42:43], v[14:15]
	v_pk_fma_f32 v[58:59], v[26:27], v[14:15], v[58:59]
	v_pk_mul_f32 v[14:15], v[76:77], v[8:9] op_sel_hi:[1,0]
	v_pk_mul_f32 v[14:15], v[44:45], v[14:15]
	v_pk_fma_f32 v[60:61], v[28:29], v[14:15], v[60:61]
	v_pk_mul_f32 v[14:15], v[78:79], v[8:9] op_sel_hi:[1,0]
	v_pk_mul_f32 v[14:15], v[46:47], v[14:15]
	v_pk_fma_f32 v[62:63], v[30:31], v[14:15], v[62:63]
	v_pk_mul_f32 v[14:15], v[80:81], v[8:9] op_sel_hi:[1,0]
	v_pk_mul_f32 v[14:15], v[48:49], v[14:15]
	v_pk_fma_f32 v[64:65], v[32:33], v[14:15], v[64:65]
	v_pk_mul_f32 v[14:15], v[82:83], v[8:9] op_sel_hi:[1,0]
	v_pk_mul_f32 v[14:15], v[50:51], v[14:15]
	v_pk_fma_f32 v[66:67], v[34:35], v[14:15], v[66:67]
	v_pk_mul_f32 v[14:15], v[84:85], v[8:9] op_sel_hi:[1,0]
	v_pk_mul_f32 v[14:15], v[52:53], v[14:15]
	v_pk_fma_f32 v[68:69], v[36:37], v[14:15], v[68:69]
	global_store_dwordx4 v0, v[54:57], s[46:47] offset:0
	global_store_dwordx4 v0, v[58:61], s[46:47] offset:1024
	global_store_dwordx4 v0, v[62:65], s[46:47] offset:2048
	global_store_dwordx4 v0, v[66:69], s[46:47] offset:3072
	s_add_u32 s46, s46, 0x1000
	s_addc_u32 s47, s47, 0
	s_add_u32 s62, s62, 0x800
	s_addc_u32 s63, s63, 0
	s_nop 1
	global_load_dwordx4 v[54:57], v0, s[4:5] offset:0
	global_load_dwordx4 v[58:61], v0, s[4:5] offset:1024
	global_load_dwordx4 v[62:65], v0, s[4:5] offset:2048
	global_load_dwordx4 v[66:69], v0, s[4:5] offset:3072
	global_load_dwordx2 v[70:71], v1, s[58:59] offset:0
	global_load_dwordx2 v[74:75], v1, s[58:59] offset:512
	global_load_dwordx2 v[78:79], v1, s[58:59] offset:1024
	global_load_dwordx2 v[82:83], v1, s[58:59] offset:1536
	global_load_dwordx2 v[72:73], v1, s[60:61] offset:0
	global_load_dwordx2 v[76:77], v1, s[60:61] offset:512
	global_load_dwordx2 v[80:81], v1, s[60:61] offset:1024
	global_load_dwordx2 v[84:85], v1, s[60:61] offset:1536
	s_add_u32 s4, s4, 0x1000
	s_addc_u32 s5, s5, 0
	s_add_u32 s58, s58, 0x800
	s_addc_u32 s59, s59, 0
	s_add_u32 s60, s60, 0x800
	s_addc_u32 s61, s61, 0
	s_waitcnt vmcnt(28)
	v_lshlrev_b32_e32 v14, 16, v102
	v_and_b32_e32 v15, 0xffff0000, v102
	v_lshlrev_b32_e32 v16, 16, v104
	v_and_b32_e32 v17, 0xffff0000, v104
	v_lshlrev_b32_e32 v18, 16, v103
	v_and_b32_e32 v19, 0xffff0000, v103
	v_lshlrev_b32_e32 v20, 16, v105
	v_and_b32_e32 v21, 0xffff0000, v105
	v_pk_add_f32 v[102:103], v[14:15], v[16:17]
	v_pk_add_f32 v[104:105], v[18:19], v[20:21]
	v_lshlrev_b32_e32 v14, 16, v106
	v_and_b32_e32 v15, 0xffff0000, v106
	v_lshlrev_b32_e32 v16, 16, v108
	v_and_b32_e32 v17, 0xffff0000, v108
	v_lshlrev_b32_e32 v18, 16, v107
	v_and_b32_e32 v19, 0xffff0000, v107
	v_lshlrev_b32_e32 v20, 16, v109
	v_and_b32_e32 v21, 0xffff0000, v109
	v_pk_add_f32 v[106:107], v[14:15], v[16:17]
	v_pk_add_f32 v[108:109], v[18:19], v[20:21]
	v_lshlrev_b32_e32 v14, 16, v110
	v_and_b32_e32 v15, 0xffff0000, v110
	v_lshlrev_b32_e32 v16, 16, v112
	v_and_b32_e32 v17, 0xffff0000, v112
	v_lshlrev_b32_e32 v18, 16, v111
	v_and_b32_e32 v19, 0xffff0000, v111
	v_lshlrev_b32_e32 v20, 16, v113
	v_and_b32_e32 v21, 0xffff0000, v113
	v_pk_add_f32 v[110:111], v[14:15], v[16:17]
	v_pk_add_f32 v[112:113], v[18:19], v[20:21]
	v_lshlrev_b32_e32 v14, 16, v114
	v_and_b32_e32 v15, 0xffff0000, v114
	v_lshlrev_b32_e32 v16, 16, v116
	v_and_b32_e32 v17, 0xffff0000, v116
	v_lshlrev_b32_e32 v18, 16, v115
	v_and_b32_e32 v19, 0xffff0000, v115
	v_lshlrev_b32_e32 v20, 16, v117
	v_and_b32_e32 v21, 0xffff0000, v117
	v_pk_add_f32 v[114:115], v[14:15], v[16:17]
	v_pk_add_f32 v[116:117], v[18:19], v[20:21]
	v_pk_mul_f32 v[12:13], v[102:103], v[102:103]
	v_pk_fma_f32 v[12:13], v[104:105], v[104:105], v[12:13]
	v_pk_fma_f32 v[12:13], v[106:107], v[106:107], v[12:13]
	v_pk_fma_f32 v[12:13], v[108:109], v[108:109], v[12:13]
	v_pk_fma_f32 v[12:13], v[110:111], v[110:111], v[12:13]
	v_pk_fma_f32 v[12:13], v[112:113], v[112:113], v[12:13]
	v_pk_fma_f32 v[12:13], v[114:115], v[114:115], v[12:13]
	v_pk_fma_f32 v[12:13], v[116:117], v[116:117], v[12:13]
	v_add_f32_e32 v5, v12, v13
	s_nop 1
	v_add_f32_dpp v5, v5, v5 quad_perm:[1,0,3,2] row_mask:0xf bank_mask:0xf
	s_nop 1
	v_add_f32_dpp v5, v5, v5 quad_perm:[2,3,0,1] row_mask:0xf bank_mask:0xf
	s_nop 1
	v_add_f32_dpp v5, v5, v5 row_half_mirror row_mask:0xf bank_mask:0xf
	s_nop 1
	v_add_f32_dpp v5, v5, v5 row_mirror row_mask:0xf bank_mask:0xf
	s_nop 1
	v_add_f32_dpp v5, v5, v5 row_bcast:15 row_mask:0xa bank_mask:0xf
	s_nop 1
	v_add_f32_dpp v5, v5, v5 row_bcast:31 row_mask:0xc bank_mask:0xf
	s_nop 1
	v_readlane_b32 s32, v5, 63
	s_nop 1
	v_mov_b32_e32 v6, s32
	v_fmamk_f32 v6, v6, 0x3a800000, v146
	v_rsq_f32_e32 v6, v6
	s_nop 0
	v_mul_f32_e32 v8, 0.5, v6
	v_pk_mul_f32 v[14:15], v[102:103], v[8:9] op_sel_hi:[1,0]
	v_pk_mul_f32 v[14:15], v[38:39], v[14:15]
	v_pk_fma_f32 v[86:87], v[22:23], v[14:15], v[86:87]
	v_pk_mul_f32 v[14:15], v[104:105], v[8:9] op_sel_hi:[1,0]
	v_pk_mul_f32 v[14:15], v[40:41], v[14:15]
	v_pk_fma_f32 v[88:89], v[24:25], v[14:15], v[88:89]
	v_pk_mul_f32 v[14:15], v[106:107], v[8:9] op_sel_hi:[1,0]
	v_pk_mul_f32 v[14:15], v[42:43], v[14:15]
	v_pk_fma_f32 v[90:91], v[26:27], v[14:15], v[90:91]
	v_pk_mul_f32 v[14:15], v[108:109], v[8:9] op_sel_hi:[1,0]
	v_pk_mul_f32 v[14:15], v[44:45], v[14:15]
	v_pk_fma_f32 v[92:93], v[28:29], v[14:15], v[92:93]
	v_pk_mul_f32 v[14:15], v[110:111], v[8:9] op_sel_hi:[1,0]
	v_pk_mul_f32 v[14:15], v[46:47], v[14:15]
	v_pk_fma_f32 v[94:95], v[30:31], v[14:15], v[94:95]
	v_pk_mul_f32 v[14:15], v[112:113], v[8:9] op_sel_hi:[1,0]
	v_pk_mul_f32 v[14:15], v[48:49], v[14:15]
	v_pk_fma_f32 v[96:97], v[32:33], v[14:15], v[96:97]
	v_pk_mul_f32 v[14:15], v[114:115], v[8:9] op_sel_hi:[1,0]
	v_pk_mul_f32 v[14:15], v[50:51], v[14:15]
	v_pk_fma_f32 v[98:99], v[34:35], v[14:15], v[98:99]
	v_pk_mul_f32 v[14:15], v[116:117], v[8:9] op_sel_hi:[1,0]
	v_pk_mul_f32 v[14:15], v[52:53], v[14:15]
	v_pk_fma_f32 v[100:101], v[36:37], v[14:15], v[100:101]
	global_store_dwordx4 v0, v[86:89], s[46:47] offset:0
	global_store_dwordx4 v0, v[90:93], s[46:47] offset:1024
	global_store_dwordx4 v0, v[94:97], s[46:47] offset:2048
	global_store_dwordx4 v0, v[98:101], s[46:47] offset:3072
	s_add_u32 s46, s46, 0x1000
	s_addc_u32 s47, s47, 0
	s_add_u32 s62, s62, 0x800
	s_addc_u32 s63, s63, 0
	s_waitcnt vmcnt(20)
	v_lshlrev_b32_e32 v14, 16, v154
	v_and_b32_e32 v15, 0xffff0000, v154
	v_lshlrev_b32_e32 v16, 16, v156
	v_and_b32_e32 v17, 0xffff0000, v156
	v_lshlrev_b32_e32 v18, 16, v155
	v_and_b32_e32 v19, 0xffff0000, v155
	v_lshlrev_b32_e32 v20, 16, v157
	v_and_b32_e32 v21, 0xffff0000, v157
	v_pk_add_f32 v[154:155], v[14:15], v[16:17]
	v_pk_add_f32 v[156:157], v[18:19], v[20:21]
	v_lshlrev_b32_e32 v14, 16, v158
	v_and_b32_e32 v15, 0xffff0000, v158
	v_lshlrev_b32_e32 v16, 16, v160
	v_and_b32_e32 v17, 0xffff0000, v160
	v_lshlrev_b32_e32 v18, 16, v159
	v_and_b32_e32 v19, 0xffff0000, v159
	v_lshlrev_b32_e32 v20, 16, v161
	v_and_b32_e32 v21, 0xffff0000, v161
	v_pk_add_f32 v[158:159], v[14:15], v[16:17]
	v_pk_add_f32 v[160:161], v[18:19], v[20:21]
	v_lshlrev_b32_e32 v14, 16, v162
	v_and_b32_e32 v15, 0xffff0000, v162
	v_lshlrev_b32_e32 v16, 16, v164
	v_and_b32_e32 v17, 0xffff0000, v164
	v_lshlrev_b32_e32 v18, 16, v163
	v_and_b32_e32 v19, 0xffff0000, v163
	v_lshlrev_b32_e32 v20, 16, v165
	v_and_b32_e32 v21, 0xffff0000, v165
	v_pk_add_f32 v[162:163], v[14:15], v[16:17]
	v_pk_add_f32 v[164:165], v[18:19], v[20:21]
	v_lshlrev_b32_e32 v14, 16, v168
	v_and_b32_e32 v15, 0xffff0000, v168
	v_lshlrev_b32_e32 v16, 16, v170
	v_and_b32_e32 v17, 0xffff0000, v170
	v_lshlrev_b32_e32 v18, 16, v169
	v_and_b32_e32 v19, 0xffff0000, v169
	v_lshlrev_b32_e32 v20, 16, v171
	v_and_b32_e32 v21, 0xffff0000, v171
	v_pk_add_f32 v[168:169], v[14:15], v[16:17]
	v_pk_add_f32 v[170:171], v[18:19], v[20:21]
	v_pk_mul_f32 v[12:13], v[154:155], v[154:155]
	v_pk_fma_f32 v[12:13], v[156:157], v[156:157], v[12:13]
	v_pk_fma_f32 v[12:13], v[158:159], v[158:159], v[12:13]
	v_pk_fma_f32 v[12:13], v[160:161], v[160:161], v[12:13]
	v_pk_fma_f32 v[12:13], v[162:163], v[162:163], v[12:13]
	v_pk_fma_f32 v[12:13], v[164:165], v[164:165], v[12:13]
	v_pk_fma_f32 v[12:13], v[168:169], v[168:169], v[12:13]
	v_pk_fma_f32 v[12:13], v[170:171], v[170:171], v[12:13]
	v_add_f32_e32 v5, v12, v13
	s_nop 1
	v_add_f32_dpp v5, v5, v5 quad_perm:[1,0,3,2] row_mask:0xf bank_mask:0xf
	s_nop 1
	v_add_f32_dpp v5, v5, v5 quad_perm:[2,3,0,1] row_mask:0xf bank_mask:0xf
	s_nop 1
	v_add_f32_dpp v5, v5, v5 row_half_mirror row_mask:0xf bank_mask:0xf
	s_nop 1
	v_add_f32_dpp v5, v5, v5 row_mirror row_mask:0xf bank_mask:0xf
	s_nop 1
	v_add_f32_dpp v5, v5, v5 row_bcast:15 row_mask:0xa bank_mask:0xf
	s_nop 1
	v_add_f32_dpp v5, v5, v5 row_bcast:31 row_mask:0xc bank_mask:0xf
	s_nop 1
	v_readlane_b32 s32, v5, 63
	s_nop 1
	v_mov_b32_e32 v6, s32
	v_fmamk_f32 v6, v6, 0x3a800000, v146
	v_rsq_f32_e32 v6, v6
	s_nop 0
	v_mul_f32_e32 v8, 0.5, v6
	v_pk_mul_f32 v[14:15], v[154:155], v[8:9] op_sel_hi:[1,0]
	v_pk_mul_f32 v[14:15], v[38:39], v[14:15]
	v_pk_fma_f32 v[118:119], v[22:23], v[14:15], v[118:119]
	v_pk_mul_f32 v[14:15], v[156:157], v[8:9] op_sel_hi:[1,0]
	v_pk_mul_f32 v[14:15], v[40:41], v[14:15]
	v_pk_fma_f32 v[120:121], v[24:25], v[14:15], v[120:121]
	v_pk_mul_f32 v[14:15], v[158:159], v[8:9] op_sel_hi:[1,0]
	v_pk_mul_f32 v[14:15], v[42:43], v[14:15]
	v_pk_fma_f32 v[122:123], v[26:27], v[14:15], v[122:123]
	v_pk_mul_f32 v[14:15], v[160:161], v[8:9] op_sel_hi:[1,0]
	v_pk_mul_f32 v[14:15], v[44:45], v[14:15]
	v_pk_fma_f32 v[124:125], v[28:29], v[14:15], v[124:125]
	v_pk_mul_f32 v[14:15], v[162:163], v[8:9] op_sel_hi:[1,0]
	v_pk_mul_f32 v[14:15], v[46:47], v[14:15]
	v_pk_fma_f32 v[134:135], v[30:31], v[14:15], v[134:135]
	v_pk_mul_f32 v[14:15], v[164:165], v[8:9] op_sel_hi:[1,0]
	v_pk_mul_f32 v[14:15], v[48:49], v[14:15]
	v_pk_fma_f32 v[136:137], v[32:33], v[14:15], v[136:137]
	v_pk_mul_f32 v[14:15], v[168:169], v[8:9] op_sel_hi:[1,0]
	v_pk_mul_f32 v[14:15], v[50:51], v[14:15]
	v_pk_fma_f32 v[138:139], v[34:35], v[14:15], v[138:139]
	v_pk_mul_f32 v[14:15], v[170:171], v[8:9] op_sel_hi:[1,0]
	v_pk_mul_f32 v[14:15], v[52:53], v[14:15]
	v_pk_fma_f32 v[140:141], v[36:37], v[14:15], v[140:141]
	global_store_dwordx4 v0, v[118:121], s[46:47] offset:0
	global_store_dwordx4 v0, v[122:125], s[46:47] offset:1024
	global_store_dwordx4 v0, v[134:137], s[46:47] offset:2048
	global_store_dwordx4 v0, v[138:141], s[46:47] offset:3072
	s_add_u32 s46, s46, 0x1000
	s_addc_u32 s47, s47, 0
	s_add_u32 s62, s62, 0x800
	s_addc_u32 s63, s63, 0
	s_waitcnt vmcnt(8)
	v_lshlrev_b32_e32 v14, 16, v70
	v_and_b32_e32 v15, 0xffff0000, v70
	v_lshlrev_b32_e32 v16, 16, v72
	v_and_b32_e32 v17, 0xffff0000, v72
	v_lshlrev_b32_e32 v18, 16, v71
	v_and_b32_e32 v19, 0xffff0000, v71
	v_lshlrev_b32_e32 v20, 16, v73
	v_and_b32_e32 v21, 0xffff0000, v73
	v_pk_add_f32 v[70:71], v[14:15], v[16:17]
	v_pk_add_f32 v[72:73], v[18:19], v[20:21]
	v_lshlrev_b32_e32 v14, 16, v74
	v_and_b32_e32 v15, 0xffff0000, v74
	v_lshlrev_b32_e32 v16, 16, v76
	v_and_b32_e32 v17, 0xffff0000, v76
	v_lshlrev_b32_e32 v18, 16, v75
	v_and_b32_e32 v19, 0xffff0000, v75
	v_lshlrev_b32_e32 v20, 16, v77
	v_and_b32_e32 v21, 0xffff0000, v77
	v_pk_add_f32 v[74:75], v[14:15], v[16:17]
	v_pk_add_f32 v[76:77], v[18:19], v[20:21]
	v_lshlrev_b32_e32 v14, 16, v78
	v_and_b32_e32 v15, 0xffff0000, v78
	v_lshlrev_b32_e32 v16, 16, v80
	v_and_b32_e32 v17, 0xffff0000, v80
	v_lshlrev_b32_e32 v18, 16, v79
	v_and_b32_e32 v19, 0xffff0000, v79
	v_lshlrev_b32_e32 v20, 16, v81
	v_and_b32_e32 v21, 0xffff0000, v81
	v_pk_add_f32 v[78:79], v[14:15], v[16:17]
	v_pk_add_f32 v[80:81], v[18:19], v[20:21]
	v_lshlrev_b32_e32 v14, 16, v82
	v_and_b32_e32 v15, 0xffff0000, v82
	v_lshlrev_b32_e32 v16, 16, v84
	v_and_b32_e32 v17, 0xffff0000, v84
	v_lshlrev_b32_e32 v18, 16, v83
	v_and_b32_e32 v19, 0xffff0000, v83
	v_lshlrev_b32_e32 v20, 16, v85
	v_and_b32_e32 v21, 0xffff0000, v85
	v_pk_add_f32 v[82:83], v[14:15], v[16:17]
	v_pk_add_f32 v[84:85], v[18:19], v[20:21]
	v_pk_mul_f32 v[12:13], v[70:71], v[70:71]
	v_pk_fma_f32 v[12:13], v[72:73], v[72:73], v[12:13]
	v_pk_fma_f32 v[12:13], v[74:75], v[74:75], v[12:13]
	v_pk_fma_f32 v[12:13], v[76:77], v[76:77], v[12:13]
	v_pk_fma_f32 v[12:13], v[78:79], v[78:79], v[12:13]
	v_pk_fma_f32 v[12:13], v[80:81], v[80:81], v[12:13]
	v_pk_fma_f32 v[12:13], v[82:83], v[82:83], v[12:13]
	v_pk_fma_f32 v[12:13], v[84:85], v[84:85], v[12:13]
	v_add_f32_e32 v5, v12, v13
	s_nop 1
	v_add_f32_dpp v5, v5, v5 quad_perm:[1,0,3,2] row_mask:0xf bank_mask:0xf
	s_nop 1
	v_add_f32_dpp v5, v5, v5 quad_perm:[2,3,0,1] row_mask:0xf bank_mask:0xf
	s_nop 1
	v_add_f32_dpp v5, v5, v5 row_half_mirror row_mask:0xf bank_mask:0xf
	s_nop 1
	v_add_f32_dpp v5, v5, v5 row_mirror row_mask:0xf bank_mask:0xf
	s_nop 1
	v_add_f32_dpp v5, v5, v5 row_bcast:15 row_mask:0xa bank_mask:0xf
	s_nop 1
	v_add_f32_dpp v5, v5, v5 row_bcast:31 row_mask:0xc bank_mask:0xf
	s_nop 1
	v_readlane_b32 s32, v5, 63
	s_nop 1
	v_mov_b32_e32 v6, s32
	v_fmamk_f32 v6, v6, 0x3a800000, v146
	v_rsq_f32_e32 v6, v6
	s_nop 0
	v_mul_f32_e32 v8, 0.5, v6
	v_pk_mul_f32 v[14:15], v[70:71], v[8:9] op_sel_hi:[1,0]
	v_pk_mul_f32 v[14:15], v[38:39], v[14:15]
	v_pk_fma_f32 v[54:55], v[22:23], v[14:15], v[54:55]
	v_pk_mul_f32 v[14:15], v[72:73], v[8:9] op_sel_hi:[1,0]
	v_pk_mul_f32 v[14:15], v[40:41], v[14:15]
	v_pk_fma_f32 v[56:57], v[24:25], v[14:15], v[56:57]
	v_pk_mul_f32 v[14:15], v[74:75], v[8:9] op_sel_hi:[1,0]
	v_pk_mul_f32 v[14:15], v[42:43], v[14:15]
	v_pk_fma_f32 v[58:59], v[26:27], v[14:15], v[58:59]
	v_pk_mul_f32 v[14:15], v[76:77], v[8:9] op_sel_hi:[1,0]
	v_pk_mul_f32 v[14:15], v[44:45], v[14:15]
	v_pk_fma_f32 v[60:61], v[28:29], v[14:15], v[60:61]
	v_pk_mul_f32 v[14:15], v[78:79], v[8:9] op_sel_hi:[1,0]
	v_pk_mul_f32 v[14:15], v[46:47], v[14:15]
	v_pk_fma_f32 v[62:63], v[30:31], v[14:15], v[62:63]
	v_pk_mul_f32 v[14:15], v[80:81], v[8:9] op_sel_hi:[1,0]
	v_pk_mul_f32 v[14:15], v[48:49], v[14:15]
	v_pk_fma_f32 v[64:65], v[32:33], v[14:15], v[64:65]
	v_pk_mul_f32 v[14:15], v[82:83], v[8:9] op_sel_hi:[1,0]
	v_pk_mul_f32 v[14:15], v[50:51], v[14:15]
	v_pk_fma_f32 v[66:67], v[34:35], v[14:15], v[66:67]
	v_pk_mul_f32 v[14:15], v[84:85], v[8:9] op_sel_hi:[1,0]
	v_pk_mul_f32 v[14:15], v[52:53], v[14:15]
	v_pk_fma_f32 v[68:69], v[36:37], v[14:15], v[68:69]
	global_store_dwordx4 v0, v[54:57], s[46:47] offset:0
	global_store_dwordx4 v0, v[58:61], s[46:47] offset:1024
	global_store_dwordx4 v0, v[62:65], s[46:47] offset:2048
	global_store_dwordx4 v0, v[66:69], s[46:47] offset:3072
	s_add_u32 s46, s46, 0x1000
	s_addc_u32 s47, s47, 0
	s_add_u32 s62, s62, 0x800
	s_addc_u32 s63, s63, 0
